# convert_layer(0) tr_item loops unrolled to 32 loads in flight; compression-bias partial sums: two 8-k groups per iteration (68 loads in flight), both instances
# speedup vs baseline: 1.0023x; 1.0023x over previous
; #define LAS __attribute__((address_space(3)))
; __device__ __forceinline__ void tr_item(const float* W, int ldw, int src_col, int nvalid, int k0, bf16_t* WT, int ldt, int dst_row, int dst_k, LAS float* scr, int lane) {
; #pragma unroll 8
;     for (int i = 0; i < 32; ++i) { const int kk = 2 * i + (lane >> 5), c = lane & 31; scr[kk * 33 + c] = (c < nvalid) ? W[(size_t)(k0 + kk) * ldw + src_col + c] : 0.f; }
.LBB0_31:
	s_lshl_b32 s15, s3, 1
	s_lshl_b32 s16, s7, 1
	v_or_b32_e32 v8, s15, v1
	v_or_b32_e32 v47, s16, v2
	s_add_i32 s17, s15, 4
	s_add_i32 s18, s16, 4
	s_add_i32 s19, s15, 8
	s_add_i32 s23, s16, 8
	s_add_i32 s24, s15, 12
	s_add_i32 s26, s16, 12
	s_add_i32 s27, s15, 16
	s_add_i32 s28, s16, 16
	s_add_i32 s29, s15, 20
	s_add_i32 s30, s16, 20
	s_add_i32 s31, s15, 24
	s_add_i32 s34, s16, 24
	s_add_i32 s15, s15, 28
	s_add_i32 s16, s16, 28
	v_add_u32_e32 v54, s4, v47
	v_or_b32_e32 v96, s17, v1
	v_or_b32_e32 v97, s18, v2
	v_or_b32_e32 v98, s19, v1
	v_or_b32_e32 v99, s23, v2
	v_or_b32_e32 v100, s24, v1
	v_or_b32_e32 v101, s26, v2
	v_or_b32_e32 v102, s27, v1
	v_or_b32_e32 v103, s28, v2
	v_or_b32_e32 v104, s29, v1
	v_or_b32_e32 v105, s30, v2
	v_or_b32_e32 v106, s31, v1
	v_or_b32_e32 v107, s34, v2
	v_or_b32_e32 v108, s15, v1
	v_or_b32_e32 v109, s16, v2
	v_add_u32_e32 v52, s5, v8
	v_ashrrev_i32_e32 v55, 31, v54
	v_add_u32_e32 v56, s5, v96
	v_add_u32_e32 v58, s4, v97
	v_add_u32_e32 v60, s5, v98
	v_add_u32_e32 v62, s4, v99
	v_add_u32_e32 v64, s5, v100
	v_add_u32_e32 v78, s4, v101
	v_add_u32_e32 v80, s5, v102
	v_add_u32_e32 v82, s4, v103
	v_add_u32_e32 v84, s5, v104
	v_add_u32_e32 v86, s4, v105
	v_add_u32_e32 v88, s5, v106
	v_add_u32_e32 v90, s4, v107
	v_add_u32_e32 v92, s5, v108
	v_add_u32_e32 v94, s4, v109
	v_ashrrev_i32_e32 v53, 31, v52
	v_lshlrev_b64 v[54:55], 12, v[54:55]
	v_ashrrev_i32_e32 v59, 31, v58
	v_ashrrev_i32_e32 v57, 31, v56
	v_ashrrev_i32_e32 v63, 31, v62
	v_ashrrev_i32_e32 v61, 31, v60
	v_ashrrev_i32_e32 v79, 31, v78
	v_ashrrev_i32_e32 v65, 31, v64
	v_ashrrev_i32_e32 v83, 31, v82
	v_ashrrev_i32_e32 v81, 31, v80
	v_ashrrev_i32_e32 v87, 31, v86
	v_ashrrev_i32_e32 v85, 31, v84
	v_ashrrev_i32_e32 v91, 31, v90
	v_ashrrev_i32_e32 v89, 31, v88
	v_ashrrev_i32_e32 v95, 31, v94
	v_ashrrev_i32_e32 v93, 31, v92
	v_lshlrev_b64 v[52:53], 12, v[52:53]
	v_lshl_add_u64 v[54:55], v[50:51], 0, v[54:55]
	v_lshlrev_b64 v[56:57], 12, v[56:57]
	v_lshlrev_b64 v[58:59], 12, v[58:59]
	v_lshlrev_b64 v[60:61], 12, v[60:61]
	v_lshlrev_b64 v[62:63], 12, v[62:63]
	v_lshlrev_b64 v[64:65], 12, v[64:65]
	v_lshlrev_b64 v[78:79], 12, v[78:79]
	v_lshlrev_b64 v[80:81], 12, v[80:81]
	v_lshlrev_b64 v[82:83], 12, v[82:83]
	v_lshlrev_b64 v[84:85], 12, v[84:85]
	v_lshlrev_b64 v[86:87], 12, v[86:87]
	v_lshlrev_b64 v[88:89], 12, v[88:89]
	v_lshlrev_b64 v[90:91], 12, v[90:91]
	v_lshlrev_b64 v[92:93], 12, v[92:93]
	v_lshlrev_b64 v[94:95], 12, v[94:95]
	v_lshl_add_u64 v[52:53], v[50:51], 0, v[52:53]
	v_lshl_add_u64 v[58:59], v[50:51], 0, v[58:59]
	v_lshl_add_u64 v[56:57], v[50:51], 0, v[56:57]
	v_lshl_add_u64 v[62:63], v[50:51], 0, v[62:63]
	v_lshl_add_u64 v[60:61], v[50:51], 0, v[60:61]
	v_lshl_add_u64 v[78:79], v[50:51], 0, v[78:79]
	v_lshl_add_u64 v[64:65], v[50:51], 0, v[64:65]
	v_lshl_add_u64 v[82:83], v[50:51], 0, v[82:83]
	v_lshl_add_u64 v[80:81], v[50:51], 0, v[80:81]
	v_lshl_add_u64 v[86:87], v[50:51], 0, v[86:87]
	v_lshl_add_u64 v[84:85], v[50:51], 0, v[84:85]
	v_lshl_add_u64 v[90:91], v[50:51], 0, v[90:91]
	v_lshl_add_u64 v[88:89], v[50:51], 0, v[88:89]
	v_lshl_add_u64 v[94:95], v[50:51], 0, v[94:95]
	v_lshl_add_u64 v[92:93], v[50:51], 0, v[92:93]
	global_load_dword v132, v[54:55], off
	global_load_dword v133, v[52:53], off
	global_load_dword v134, v[58:59], off
	global_load_dword v135, v[56:57], off
	global_load_dword v136, v[62:63], off
	global_load_dword v137, v[60:61], off
	global_load_dword v138, v[78:79], off
	global_load_dword v139, v[64:65], off
	global_load_dword v140, v[82:83], off
	global_load_dword v141, v[80:81], off
	global_load_dword v142, v[86:87], off
	global_load_dword v143, v[84:85], off
	global_load_dword v144, v[90:91], off
	global_load_dword v145, v[88:89], off
	global_load_dword v146, v[94:95], off
	global_load_dword v147, v[92:93], off
	s_add_i32 s7, s7, 16
	s_add_i32 s3, s3, 16
	s_add_i32 s14, s14, -16
	v_mad_u64_u32 v[52:53], s[16:17], v47, s8, v[6:7]
	s_cmp_lg_u32 s14, 0
	v_mad_u64_u32 v[54:55], s[16:17], v8, s8, v[6:7]
	v_mad_u64_u32 v[56:57], s[16:17], v97, s8, v[6:7]
	v_mad_u64_u32 v[58:59], s[16:17], v96, s8, v[6:7]
	v_mad_u64_u32 v[60:61], s[16:17], v99, s8, v[6:7]
	v_mad_u64_u32 v[62:63], s[16:17], v98, s8, v[6:7]
	v_mad_u64_u32 v[64:65], s[16:17], v101, s8, v[6:7]
	v_mad_u64_u32 v[78:79], s[16:17], v100, s8, v[6:7]
	v_mad_u64_u32 v[80:81], s[16:17], v103, s8, v[6:7]
	v_mad_u64_u32 v[82:83], s[16:17], v102, s8, v[6:7]
	v_mad_u64_u32 v[84:85], s[16:17], v105, s8, v[6:7]
	v_mad_u64_u32 v[86:87], s[16:17], v104, s8, v[6:7]
	v_mad_u64_u32 v[88:89], s[16:17], v107, s8, v[6:7]
	v_mad_u64_u32 v[90:91], s[16:17], v106, s8, v[6:7]
	v_mad_u64_u32 v[92:93], s[16:17], v109, s8, v[6:7]
	v_mad_u64_u32 v[94:95], s[16:17], v108, s8, v[6:7]
	v_mov_b32_e32 v148, v52
	v_mov_b32_e32 v149, v54
	v_mov_b32_e32 v150, v56
	v_mov_b32_e32 v151, v58
	v_mov_b32_e32 v152, v60
	v_mov_b32_e32 v153, v62
	v_mov_b32_e32 v154, v64
	v_mov_b32_e32 v155, v78
	v_mov_b32_e32 v156, v80
	v_mov_b32_e32 v157, v82
	v_mov_b32_e32 v158, v84
	v_mov_b32_e32 v159, v86
	v_mov_b32_e32 v160, v88
	v_mov_b32_e32 v161, v90
	v_mov_b32_e32 v162, v92
	v_mov_b32_e32 v163, v94
	s_lshl_b32 s15, s3, 1
	s_lshl_b32 s16, s7, 1
	v_or_b32_e32 v8, s15, v1
	v_or_b32_e32 v47, s16, v2
	s_add_i32 s17, s15, 4
	s_add_i32 s18, s16, 4
	s_add_i32 s19, s15, 8
	s_add_i32 s23, s16, 8
	s_add_i32 s24, s15, 12
	s_add_i32 s26, s16, 12
	s_add_i32 s27, s15, 16
	s_add_i32 s28, s16, 16
	s_add_i32 s29, s15, 20
	s_add_i32 s30, s16, 20
	s_add_i32 s31, s15, 24
	s_add_i32 s34, s16, 24
	s_add_i32 s15, s15, 28
	s_add_i32 s16, s16, 28
	v_add_u32_e32 v54, s4, v47
	v_or_b32_e32 v96, s17, v1
	v_or_b32_e32 v97, s18, v2
	v_or_b32_e32 v98, s19, v1
; __device__ __forceinline__ void tr_item(const float* W, int ldw, int src_col, int nvalid, int k0, bf16_t* WT, int ldt, int dst_row, int dst_k, LAS float* scr, int lane) {
; #pragma unroll 8
;     for (int i = 0; i < 32; ++i) { const int kk = 2 * i + (lane >> 5), c = lane & 31; scr[kk * 33 + c] = (c < nvalid) ? W[(size_t)(k0 + kk) * ldw + src_col + c] : 0.f; }
	v_or_b32_e32 v99, s23, v2
	v_or_b32_e32 v100, s24, v1
	v_or_b32_e32 v101, s26, v2
	v_or_b32_e32 v102, s27, v1
	v_or_b32_e32 v103, s28, v2
	v_or_b32_e32 v104, s29, v1
	v_or_b32_e32 v105, s30, v2
	v_or_b32_e32 v106, s31, v1
	v_or_b32_e32 v107, s34, v2
	v_or_b32_e32 v108, s15, v1
	v_or_b32_e32 v109, s16, v2
	v_add_u32_e32 v52, s5, v8
	v_ashrrev_i32_e32 v55, 31, v54
	v_add_u32_e32 v56, s5, v96
	v_add_u32_e32 v58, s4, v97
	v_add_u32_e32 v60, s5, v98
	v_add_u32_e32 v62, s4, v99
	v_add_u32_e32 v64, s5, v100
	v_add_u32_e32 v78, s4, v101
	v_add_u32_e32 v80, s5, v102
	v_add_u32_e32 v82, s4, v103
	v_add_u32_e32 v84, s5, v104
	v_add_u32_e32 v86, s4, v105
	v_add_u32_e32 v88, s5, v106
	v_add_u32_e32 v90, s4, v107
	v_add_u32_e32 v92, s5, v108
	v_add_u32_e32 v94, s4, v109
	v_ashrrev_i32_e32 v53, 31, v52
	v_lshlrev_b64 v[54:55], 12, v[54:55]
	v_ashrrev_i32_e32 v59, 31, v58
	v_ashrrev_i32_e32 v57, 31, v56
	v_ashrrev_i32_e32 v63, 31, v62
	v_ashrrev_i32_e32 v61, 31, v60
	v_ashrrev_i32_e32 v79, 31, v78
	v_ashrrev_i32_e32 v65, 31, v64
	v_ashrrev_i32_e32 v83, 31, v82
	v_ashrrev_i32_e32 v81, 31, v80
	v_ashrrev_i32_e32 v87, 31, v86
	v_ashrrev_i32_e32 v85, 31, v84
	v_ashrrev_i32_e32 v91, 31, v90
	v_ashrrev_i32_e32 v89, 31, v88
	v_ashrrev_i32_e32 v95, 31, v94
	v_ashrrev_i32_e32 v93, 31, v92
	v_lshlrev_b64 v[52:53], 12, v[52:53]
	v_lshl_add_u64 v[54:55], v[50:51], 0, v[54:55]
	v_lshlrev_b64 v[56:57], 12, v[56:57]
	v_lshlrev_b64 v[58:59], 12, v[58:59]
	v_lshlrev_b64 v[60:61], 12, v[60:61]
	v_lshlrev_b64 v[62:63], 12, v[62:63]
	v_lshlrev_b64 v[64:65], 12, v[64:65]
	v_lshlrev_b64 v[78:79], 12, v[78:79]
	v_lshlrev_b64 v[80:81], 12, v[80:81]
	v_lshlrev_b64 v[82:83], 12, v[82:83]
	v_lshlrev_b64 v[84:85], 12, v[84:85]
	v_lshlrev_b64 v[86:87], 12, v[86:87]
	v_lshlrev_b64 v[88:89], 12, v[88:89]
	v_lshlrev_b64 v[90:91], 12, v[90:91]
	v_lshlrev_b64 v[92:93], 12, v[92:93]
	v_lshlrev_b64 v[94:95], 12, v[94:95]
	v_lshl_add_u64 v[52:53], v[50:51], 0, v[52:53]
	v_lshl_add_u64 v[58:59], v[50:51], 0, v[58:59]
	v_lshl_add_u64 v[56:57], v[50:51], 0, v[56:57]
	v_lshl_add_u64 v[62:63], v[50:51], 0, v[62:63]
	v_lshl_add_u64 v[60:61], v[50:51], 0, v[60:61]
	v_lshl_add_u64 v[78:79], v[50:51], 0, v[78:79]
	v_lshl_add_u64 v[64:65], v[50:51], 0, v[64:65]
	v_lshl_add_u64 v[82:83], v[50:51], 0, v[82:83]
	v_lshl_add_u64 v[80:81], v[50:51], 0, v[80:81]
	v_lshl_add_u64 v[86:87], v[50:51], 0, v[86:87]
	v_lshl_add_u64 v[84:85], v[50:51], 0, v[84:85]
	v_lshl_add_u64 v[90:91], v[50:51], 0, v[90:91]
	v_lshl_add_u64 v[88:89], v[50:51], 0, v[88:89]
	v_lshl_add_u64 v[94:95], v[50:51], 0, v[94:95]
	v_lshl_add_u64 v[92:93], v[50:51], 0, v[92:93]
	global_load_dword v110, v[54:55], off
	global_load_dword v111, v[52:53], off
	global_load_dword v112, v[58:59], off
	global_load_dword v113, v[56:57], off
	global_load_dword v114, v[62:63], off
	global_load_dword v115, v[60:61], off
	global_load_dword v116, v[78:79], off
	global_load_dword v117, v[64:65], off
	global_load_dword v118, v[82:83], off
	global_load_dword v119, v[80:81], off
	global_load_dword v120, v[86:87], off
	global_load_dword v121, v[84:85], off
	global_load_dword v122, v[90:91], off
	global_load_dword v123, v[88:89], off
	global_load_dword v124, v[94:95], off
	global_load_dword v125, v[92:93], off
	s_add_i32 s7, s7, 16
	s_add_i32 s3, s3, 16
	s_add_i32 s14, s14, -16
	v_mad_u64_u32 v[52:53], s[16:17], v47, s8, v[6:7]
	s_cmp_lg_u32 s14, 0
	v_mad_u64_u32 v[54:55], s[16:17], v8, s8, v[6:7]
	v_mad_u64_u32 v[56:57], s[16:17], v97, s8, v[6:7]
	v_mad_u64_u32 v[58:59], s[16:17], v96, s8, v[6:7]
	v_mad_u64_u32 v[60:61], s[16:17], v99, s8, v[6:7]
	v_mad_u64_u32 v[62:63], s[16:17], v98, s8, v[6:7]
	v_mad_u64_u32 v[64:65], s[16:17], v101, s8, v[6:7]
	v_mad_u64_u32 v[78:79], s[16:17], v100, s8, v[6:7]
	v_mad_u64_u32 v[80:81], s[16:17], v103, s8, v[6:7]
	v_mad_u64_u32 v[82:83], s[16:17], v102, s8, v[6:7]
	v_mad_u64_u32 v[84:85], s[16:17], v105, s8, v[6:7]
	v_mad_u64_u32 v[86:87], s[16:17], v104, s8, v[6:7]
	v_mad_u64_u32 v[88:89], s[16:17], v107, s8, v[6:7]
	v_mad_u64_u32 v[90:91], s[16:17], v106, s8, v[6:7]
	v_mad_u64_u32 v[92:93], s[16:17], v109, s8, v[6:7]
	v_mad_u64_u32 v[94:95], s[16:17], v108, s8, v[6:7]
	s_waitcnt vmcnt(31)
; #define LAS __attribute__((address_space(3)))
; __device__ __forceinline__ unsigned cvt_pk_bf16(float lo, float hi) { f32x2_t v = {lo, hi}; bf16x2_t b = __builtin_convertvector(v, bf16x2_t); return __builtin_bit_cast(unsigned, b); }
; #define LDS_WAIT() asm volatile("s_waitcnt lgkmcnt(0)" ::: "memory")
; __device__ __forceinline__ void tr_item(const float* W, int ldw, int src_col, int nvalid, int k0, bf16_t* WT, int ldt, int dst_row, int dst_k, LAS float* scr, int lane) {
;     ...
;     for (int i = 0; i < 32; ++i) { const int kk = 2 * i + (lane >> 5), c = lane & 31; scr[kk * 33 + c] = (c < nvalid) ? W[(size_t)(k0 + kk) * ldw + src_col + c] : 0.f; }
;     LDS_WAIT();
;     const int c = lane & 7;
; #pragma unroll
;     for (int j = 0; j < 4; ++j) { const int n = (lane >> 3) + 8 * j; const LAS float* s = scr + (8 * c) * 33 + n;
;         u32x4 o; o.x = cvt_pk_bf16(s[0 * 33], s[1 * 33]); o.y = cvt_pk_bf16(s[2 * 33], s[3 * 33]); o.z = cvt_pk_bf16(s[4 * 33], s[5 * 33]); o.w = cvt_pk_bf16(s[6 * 33], s[7 * 33]);
;         *(u32x4*)(WT + (size_t)(dst_row + n) * ldt + dst_k + k0 + 8 * c) = o; }
;     LDS_WAIT();
	ds_write_b32 v148, v132
	s_waitcnt vmcnt(30)
	ds_write_b32 v149, v133
	s_waitcnt vmcnt(29)
	ds_write_b32 v150, v134
	s_waitcnt vmcnt(28)
	ds_write_b32 v151, v135
	s_waitcnt vmcnt(27)
	ds_write_b32 v152, v136
	s_waitcnt vmcnt(26)
	ds_write_b32 v153, v137
	s_waitcnt vmcnt(25)
	ds_write_b32 v154, v138
	s_waitcnt vmcnt(24)
	ds_write_b32 v155, v139
	s_waitcnt vmcnt(23)
	ds_write_b32 v156, v140
	s_waitcnt vmcnt(22)
	ds_write_b32 v157, v141
	s_waitcnt vmcnt(21)
	ds_write_b32 v158, v142
	s_waitcnt vmcnt(20)
	ds_write_b32 v159, v143
	s_waitcnt vmcnt(19)
	ds_write_b32 v160, v144
	s_waitcnt vmcnt(18)
	ds_write_b32 v161, v145
	s_waitcnt vmcnt(17)
	ds_write_b32 v162, v146
	s_waitcnt vmcnt(16)
	ds_write_b32 v163, v147
	s_waitcnt vmcnt(15)
	ds_write_b32 v52, v110
	s_waitcnt vmcnt(14)
	ds_write_b32 v54, v111
	s_waitcnt vmcnt(13)
	ds_write_b32 v56, v112
	s_waitcnt vmcnt(12)
	ds_write_b32 v58, v113
	s_waitcnt vmcnt(11)
	ds_write_b32 v60, v114
	s_waitcnt vmcnt(10)
	ds_write_b32 v62, v115
	s_waitcnt vmcnt(9)
	ds_write_b32 v64, v116
	s_waitcnt vmcnt(8)
	ds_write_b32 v78, v117
	s_waitcnt vmcnt(7)
	ds_write_b32 v80, v118
	s_waitcnt vmcnt(6)
	ds_write_b32 v82, v119
	s_waitcnt vmcnt(5)
	ds_write_b32 v84, v120
	s_waitcnt vmcnt(4)
	ds_write_b32 v86, v121
	s_waitcnt vmcnt(3)
	ds_write_b32 v88, v122
	s_waitcnt vmcnt(2)
	ds_write_b32 v90, v123
	s_waitcnt vmcnt(1)
	ds_write_b32 v92, v124
	s_waitcnt vmcnt(0)
	ds_write_b32 v94, v125
	s_waitcnt lgkmcnt(0)
	ds_read2_b32 v[54:55], v5 offset0:33 offset1:41
	ds_read2_b32 v[56:57], v5 offset1:8
	ds_read2_b32 v[58:59], v5 offset0:66 offset1:74
	ds_read2_b32 v[60:61], v5 offset0:99 offset1:107
	ds_read2_b32 v[62:63], v5 offset0:132 offset1:140
	ds_read2_b32 v[64:65], v5 offset0:165 offset1:173
	ds_read2_b32 v[78:79], v5 offset0:198 offset1:206
	ds_read2_b32 v[80:81], v5 offset0:231 offset1:239
	s_mov_b32 s5, s25
	v_or_b32_e32 v8, s2, v3
	v_lshl_add_u64 v[82:83], s[4:5], 1, v[12:13]
	v_lshlrev_b32_e32 v8, 11, v8
	s_waitcnt lgkmcnt(6)
	v_cvt_pk_bf16_f32 v50, v56, v54
	s_waitcnt lgkmcnt(4)
	v_cvt_pk_bf16_f32 v51, v58, v60
	s_waitcnt lgkmcnt(2)
	v_cvt_pk_bf16_f32 v52, v62, v64
	s_waitcnt lgkmcnt(0)
	v_cvt_pk_bf16_f32 v53, v78, v80
	v_lshl_add_u64 v[84:85], v[82:83], 0, v[8:9]
	global_store_dwordx4 v[84:85], v[50:53], off
	v_or_b32_e32 v8, s2, v7
	v_lshlrev_b32_e32 v8, 11, v8
	v_cvt_pk_bf16_f32 v50, v57, v55
	v_cvt_pk_bf16_f32 v51, v59, v61
	v_cvt_pk_bf16_f32 v52, v63, v65
	v_cvt_pk_bf16_f32 v53, v79, v81
	ds_read2_b32 v[56:57], v5 offset0:49 offset1:57
	ds_read2_b32 v[58:59], v5 offset0:16 offset1:24
	ds_read2_b32 v[60:61], v5 offset0:82 offset1:90
	ds_read2_b32 v[62:63], v5 offset0:115 offset1:123
	ds_read2_b32 v[64:65], v5 offset0:148 offset1:156
	ds_read2_b32 v[78:79], v5 offset0:181 offset1:189
	ds_read2_b32 v[80:81], v5 offset0:214 offset1:222
	ds_read2_b32 v[84:85], v5 offset0:247 offset1:255
	v_lshl_add_u64 v[54:55], v[82:83], 0, v[8:9]
	v_or_b32_e32 v8, s2, v68
	v_lshlrev_b32_e32 v8, 11, v8
	global_store_dwordx4 v[54:55], v[50:53], off
	v_lshl_add_u64 v[54:55], v[82:83], 0, v[8:9]
	v_or_b32_e32 v8, s2, v69
	s_waitcnt lgkmcnt(6)
	v_cvt_pk_bf16_f32 v50, v58, v56
	s_waitcnt lgkmcnt(4)
	v_cvt_pk_bf16_f32 v51, v60, v62
	s_waitcnt lgkmcnt(2)
	v_cvt_pk_bf16_f32 v52, v64, v78
	s_waitcnt lgkmcnt(0)
	v_cvt_pk_bf16_f32 v53, v80, v84
	v_lshlrev_b32_e32 v8, 11, v8
	global_store_dwordx4 v[54:55], v[50:53], off
	v_lshl_add_u64 v[54:55], v[82:83], 0, v[8:9]
	s_mov_b64 s[2:3], 0
	v_cvt_pk_bf16_f32 v50, v59, v57
	v_cvt_pk_bf16_f32 v51, v61, v63
	v_cvt_pk_bf16_f32 v52, v65, v79
	v_cvt_pk_bf16_f32 v53, v81, v85
	global_store_dwordx4 v[54:55], v[50:53], off
	s_waitcnt lgkmcnt(0)

; __device__ __forceinline__ void tr_item(const float* W, int ldw, int src_col, int nvalid, int k0, bf16_t* WT, int ldt, int dst_row, int dst_k, LAS float* scr, int lane) {
; #pragma unroll 8
;     for (int i = 0; i < 32; ++i) { const int kk = 2 * i + (lane >> 5), c = lane & 31; scr[kk * 33 + c] = (c < nvalid) ? W[(size_t)(k0 + kk) * ldw + src_col + c] : 0.f; }
.LBB0_35:
	s_lshl_b32 s14, s5, 1
	s_lshl_b32 s15, s6, 1
	v_or_b32_e32 v8, s14, v1
	v_or_b32_e32 v47, s15, v2
	s_add_i32 s16, s14, 4
	s_add_i32 s17, s15, 4
	s_add_i32 s18, s14, 8
	s_add_i32 s19, s15, 8
	s_add_i32 s23, s14, 12
	s_add_i32 s24, s15, 12
	s_add_i32 s26, s14, 16
	s_add_i32 s27, s15, 16
	s_add_i32 s28, s14, 20
	s_add_i32 s29, s15, 20
	s_add_i32 s30, s14, 24
	s_add_i32 s31, s15, 24
	s_add_i32 s14, s14, 28
	s_add_i32 s15, s15, 28
	v_add_u32_e32 v54, s4, v47
	v_or_b32_e32 v96, s16, v1
	v_or_b32_e32 v97, s17, v2
	v_or_b32_e32 v98, s18, v1
	v_or_b32_e32 v99, s19, v2
	v_or_b32_e32 v100, s23, v1
	v_or_b32_e32 v101, s24, v2
	v_or_b32_e32 v102, s26, v1
	v_or_b32_e32 v103, s27, v2
	v_or_b32_e32 v104, s28, v1
	v_or_b32_e32 v105, s29, v2
	v_or_b32_e32 v106, s30, v1
	v_or_b32_e32 v107, s31, v2
	v_or_b32_e32 v108, s14, v1
	v_or_b32_e32 v109, s15, v2
	v_add_u32_e32 v52, s3, v8
	v_ashrrev_i32_e32 v55, 31, v54
	v_add_u32_e32 v56, s3, v96
	v_add_u32_e32 v58, s4, v97
	v_add_u32_e32 v60, s3, v98
	v_add_u32_e32 v62, s4, v99
	v_add_u32_e32 v64, s3, v100
	v_add_u32_e32 v78, s4, v101
	v_add_u32_e32 v80, s3, v102
	v_add_u32_e32 v82, s4, v103
	v_add_u32_e32 v84, s3, v104
	v_add_u32_e32 v86, s4, v105
	v_add_u32_e32 v88, s3, v106
	v_add_u32_e32 v90, s4, v107
	v_add_u32_e32 v92, s3, v108
	v_add_u32_e32 v94, s4, v109
	v_ashrrev_i32_e32 v53, 31, v52
	v_lshlrev_b64 v[54:55], 10, v[54:55]
	v_ashrrev_i32_e32 v59, 31, v58
	v_ashrrev_i32_e32 v57, 31, v56
	v_ashrrev_i32_e32 v63, 31, v62
	v_ashrrev_i32_e32 v61, 31, v60
	v_ashrrev_i32_e32 v79, 31, v78
	v_ashrrev_i32_e32 v65, 31, v64
	v_ashrrev_i32_e32 v83, 31, v82
	v_ashrrev_i32_e32 v81, 31, v80
	v_ashrrev_i32_e32 v87, 31, v86
	v_ashrrev_i32_e32 v85, 31, v84
	v_ashrrev_i32_e32 v91, 31, v90
	v_ashrrev_i32_e32 v89, 31, v88
	v_ashrrev_i32_e32 v95, 31, v94
	v_ashrrev_i32_e32 v93, 31, v92
	v_lshlrev_b64 v[52:53], 10, v[52:53]
	v_lshl_add_u64 v[54:55], v[50:51], 0, v[54:55]
	v_lshlrev_b64 v[56:57], 10, v[56:57]
	v_lshlrev_b64 v[58:59], 10, v[58:59]
	v_lshlrev_b64 v[60:61], 10, v[60:61]
	v_lshlrev_b64 v[62:63], 10, v[62:63]
	v_lshlrev_b64 v[64:65], 10, v[64:65]
	v_lshlrev_b64 v[78:79], 10, v[78:79]
	v_lshlrev_b64 v[80:81], 10, v[80:81]
	v_lshlrev_b64 v[82:83], 10, v[82:83]
	v_lshlrev_b64 v[84:85], 10, v[84:85]
	v_lshlrev_b64 v[86:87], 10, v[86:87]
	v_lshlrev_b64 v[88:89], 10, v[88:89]
	v_lshlrev_b64 v[90:91], 10, v[90:91]
	v_lshlrev_b64 v[92:93], 10, v[92:93]
	v_lshlrev_b64 v[94:95], 10, v[94:95]
	v_lshl_add_u64 v[52:53], v[50:51], 0, v[52:53]
	v_lshl_add_u64 v[58:59], v[50:51], 0, v[58:59]
	v_lshl_add_u64 v[56:57], v[50:51], 0, v[56:57]
	v_lshl_add_u64 v[62:63], v[50:51], 0, v[62:63]
	v_lshl_add_u64 v[60:61], v[50:51], 0, v[60:61]
	v_lshl_add_u64 v[78:79], v[50:51], 0, v[78:79]
	v_lshl_add_u64 v[64:65], v[50:51], 0, v[64:65]
	v_lshl_add_u64 v[82:83], v[50:51], 0, v[82:83]
	v_lshl_add_u64 v[80:81], v[50:51], 0, v[80:81]
	v_lshl_add_u64 v[86:87], v[50:51], 0, v[86:87]
	v_lshl_add_u64 v[84:85], v[50:51], 0, v[84:85]
	v_lshl_add_u64 v[90:91], v[50:51], 0, v[90:91]
	v_lshl_add_u64 v[88:89], v[50:51], 0, v[88:89]
	v_lshl_add_u64 v[94:95], v[50:51], 0, v[94:95]
	v_lshl_add_u64 v[92:93], v[50:51], 0, v[92:93]
	global_load_dword v132, v[54:55], off
	global_load_dword v133, v[52:53], off
	global_load_dword v134, v[58:59], off
	global_load_dword v135, v[56:57], off
	global_load_dword v136, v[62:63], off
	global_load_dword v137, v[60:61], off
	global_load_dword v138, v[78:79], off
	global_load_dword v139, v[64:65], off
	global_load_dword v140, v[82:83], off
	global_load_dword v141, v[80:81], off
	global_load_dword v142, v[86:87], off
	global_load_dword v143, v[84:85], off
	global_load_dword v144, v[90:91], off
	global_load_dword v145, v[88:89], off
	global_load_dword v146, v[94:95], off
	global_load_dword v147, v[92:93], off
	s_add_i32 s6, s6, 16
	s_add_i32 s5, s5, 16
	s_add_i32 s7, s7, -16
	v_mad_u64_u32 v[52:53], s[14:15], v47, s8, v[6:7]
	s_cmp_lg_u32 s7, 0
	v_mad_u64_u32 v[54:55], s[14:15], v8, s8, v[6:7]
	v_mad_u64_u32 v[56:57], s[14:15], v97, s8, v[6:7]
	v_mad_u64_u32 v[58:59], s[14:15], v96, s8, v[6:7]
	v_mad_u64_u32 v[60:61], s[14:15], v99, s8, v[6:7]
	v_mad_u64_u32 v[62:63], s[14:15], v98, s8, v[6:7]
	v_mad_u64_u32 v[64:65], s[14:15], v101, s8, v[6:7]
	v_mad_u64_u32 v[78:79], s[14:15], v100, s8, v[6:7]
	v_mad_u64_u32 v[80:81], s[14:15], v103, s8, v[6:7]
	v_mad_u64_u32 v[82:83], s[14:15], v102, s8, v[6:7]
	v_mad_u64_u32 v[84:85], s[14:15], v105, s8, v[6:7]
	v_mad_u64_u32 v[86:87], s[14:15], v104, s8, v[6:7]
	v_mad_u64_u32 v[88:89], s[14:15], v107, s8, v[6:7]
	v_mad_u64_u32 v[90:91], s[14:15], v106, s8, v[6:7]
	v_mad_u64_u32 v[92:93], s[14:15], v109, s8, v[6:7]
	v_mad_u64_u32 v[94:95], s[14:15], v108, s8, v[6:7]
	v_mov_b32_e32 v148, v52
	v_mov_b32_e32 v149, v54
	v_mov_b32_e32 v150, v56
	v_mov_b32_e32 v151, v58
	v_mov_b32_e32 v152, v60
	v_mov_b32_e32 v153, v62
	v_mov_b32_e32 v154, v64
	v_mov_b32_e32 v155, v78
	v_mov_b32_e32 v156, v80
	v_mov_b32_e32 v157, v82
	v_mov_b32_e32 v158, v84
	v_mov_b32_e32 v159, v86
	v_mov_b32_e32 v160, v88
	v_mov_b32_e32 v161, v90
	v_mov_b32_e32 v162, v92
	v_mov_b32_e32 v163, v94
	s_lshl_b32 s14, s5, 1
	s_lshl_b32 s15, s6, 1
	v_or_b32_e32 v8, s14, v1
	v_or_b32_e32 v47, s15, v2
	s_add_i32 s16, s14, 4
	s_add_i32 s17, s15, 4
	s_add_i32 s18, s14, 8
	s_add_i32 s19, s15, 8
	s_add_i32 s23, s14, 12
	s_add_i32 s24, s15, 12
	s_add_i32 s26, s14, 16
	s_add_i32 s27, s15, 16
	s_add_i32 s28, s14, 20
	s_add_i32 s29, s15, 20
	s_add_i32 s30, s14, 24
	s_add_i32 s31, s15, 24
	s_add_i32 s14, s14, 28
	s_add_i32 s15, s15, 28
	v_add_u32_e32 v54, s4, v47
	v_or_b32_e32 v96, s16, v1
	v_or_b32_e32 v97, s17, v2
	v_or_b32_e32 v98, s18, v1
; __device__ __forceinline__ void tr_item(const float* W, int ldw, int src_col, int nvalid, int k0, bf16_t* WT, int ldt, int dst_row, int dst_k, LAS float* scr, int lane) {
; #pragma unroll 8
;     for (int i = 0; i < 32; ++i) { const int kk = 2 * i + (lane >> 5), c = lane & 31; scr[kk * 33 + c] = (c < nvalid) ? W[(size_t)(k0 + kk) * ldw + src_col + c] : 0.f; }
	v_or_b32_e32 v99, s19, v2
	v_or_b32_e32 v100, s23, v1
	v_or_b32_e32 v101, s24, v2
	v_or_b32_e32 v102, s26, v1
	v_or_b32_e32 v103, s27, v2
	v_or_b32_e32 v104, s28, v1
	v_or_b32_e32 v105, s29, v2
	v_or_b32_e32 v106, s30, v1
	v_or_b32_e32 v107, s31, v2
	v_or_b32_e32 v108, s14, v1
	v_or_b32_e32 v109, s15, v2
	v_add_u32_e32 v52, s3, v8
	v_ashrrev_i32_e32 v55, 31, v54
	v_add_u32_e32 v56, s3, v96
	v_add_u32_e32 v58, s4, v97
	v_add_u32_e32 v60, s3, v98
	v_add_u32_e32 v62, s4, v99
	v_add_u32_e32 v64, s3, v100
	v_add_u32_e32 v78, s4, v101
	v_add_u32_e32 v80, s3, v102
	v_add_u32_e32 v82, s4, v103
	v_add_u32_e32 v84, s3, v104
	v_add_u32_e32 v86, s4, v105
	v_add_u32_e32 v88, s3, v106
	v_add_u32_e32 v90, s4, v107
	v_add_u32_e32 v92, s3, v108
	v_add_u32_e32 v94, s4, v109
	v_ashrrev_i32_e32 v53, 31, v52
	v_lshlrev_b64 v[54:55], 10, v[54:55]
	v_ashrrev_i32_e32 v59, 31, v58
	v_ashrrev_i32_e32 v57, 31, v56
	v_ashrrev_i32_e32 v63, 31, v62
	v_ashrrev_i32_e32 v61, 31, v60
	v_ashrrev_i32_e32 v79, 31, v78
	v_ashrrev_i32_e32 v65, 31, v64
	v_ashrrev_i32_e32 v83, 31, v82
	v_ashrrev_i32_e32 v81, 31, v80
	v_ashrrev_i32_e32 v87, 31, v86
	v_ashrrev_i32_e32 v85, 31, v84
	v_ashrrev_i32_e32 v91, 31, v90
	v_ashrrev_i32_e32 v89, 31, v88
	v_ashrrev_i32_e32 v95, 31, v94
	v_ashrrev_i32_e32 v93, 31, v92
	v_lshlrev_b64 v[52:53], 10, v[52:53]
	v_lshl_add_u64 v[54:55], v[50:51], 0, v[54:55]
	v_lshlrev_b64 v[56:57], 10, v[56:57]
	v_lshlrev_b64 v[58:59], 10, v[58:59]
	v_lshlrev_b64 v[60:61], 10, v[60:61]
	v_lshlrev_b64 v[62:63], 10, v[62:63]
	v_lshlrev_b64 v[64:65], 10, v[64:65]
	v_lshlrev_b64 v[78:79], 10, v[78:79]
	v_lshlrev_b64 v[80:81], 10, v[80:81]
	v_lshlrev_b64 v[82:83], 10, v[82:83]
	v_lshlrev_b64 v[84:85], 10, v[84:85]
	v_lshlrev_b64 v[86:87], 10, v[86:87]
	v_lshlrev_b64 v[88:89], 10, v[88:89]
	v_lshlrev_b64 v[90:91], 10, v[90:91]
	v_lshlrev_b64 v[92:93], 10, v[92:93]
	v_lshlrev_b64 v[94:95], 10, v[94:95]
	v_lshl_add_u64 v[52:53], v[50:51], 0, v[52:53]
	v_lshl_add_u64 v[58:59], v[50:51], 0, v[58:59]
	v_lshl_add_u64 v[56:57], v[50:51], 0, v[56:57]
	v_lshl_add_u64 v[62:63], v[50:51], 0, v[62:63]
	v_lshl_add_u64 v[60:61], v[50:51], 0, v[60:61]
	v_lshl_add_u64 v[78:79], v[50:51], 0, v[78:79]
	v_lshl_add_u64 v[64:65], v[50:51], 0, v[64:65]
	v_lshl_add_u64 v[82:83], v[50:51], 0, v[82:83]
	v_lshl_add_u64 v[80:81], v[50:51], 0, v[80:81]
	v_lshl_add_u64 v[86:87], v[50:51], 0, v[86:87]
	v_lshl_add_u64 v[84:85], v[50:51], 0, v[84:85]
	v_lshl_add_u64 v[90:91], v[50:51], 0, v[90:91]
	v_lshl_add_u64 v[88:89], v[50:51], 0, v[88:89]
	v_lshl_add_u64 v[94:95], v[50:51], 0, v[94:95]
	v_lshl_add_u64 v[92:93], v[50:51], 0, v[92:93]
	global_load_dword v110, v[54:55], off
	global_load_dword v111, v[52:53], off
	global_load_dword v112, v[58:59], off
	global_load_dword v113, v[56:57], off
	global_load_dword v114, v[62:63], off
	global_load_dword v115, v[60:61], off
	global_load_dword v116, v[78:79], off
	global_load_dword v117, v[64:65], off
	global_load_dword v118, v[82:83], off
	global_load_dword v119, v[80:81], off
	global_load_dword v120, v[86:87], off
	global_load_dword v121, v[84:85], off
	global_load_dword v122, v[90:91], off
	global_load_dword v123, v[88:89], off
	global_load_dword v124, v[94:95], off
	global_load_dword v125, v[92:93], off
	s_add_i32 s6, s6, 16
	s_add_i32 s5, s5, 16
	s_add_i32 s7, s7, -16
	v_mad_u64_u32 v[52:53], s[14:15], v47, s8, v[6:7]
	s_cmp_lg_u32 s7, 0
	v_mad_u64_u32 v[54:55], s[14:15], v8, s8, v[6:7]
	v_mad_u64_u32 v[56:57], s[14:15], v97, s8, v[6:7]
	v_mad_u64_u32 v[58:59], s[14:15], v96, s8, v[6:7]
	v_mad_u64_u32 v[60:61], s[14:15], v99, s8, v[6:7]
	v_mad_u64_u32 v[62:63], s[14:15], v98, s8, v[6:7]
	v_mad_u64_u32 v[64:65], s[14:15], v101, s8, v[6:7]
	v_mad_u64_u32 v[78:79], s[14:15], v100, s8, v[6:7]
	v_mad_u64_u32 v[80:81], s[14:15], v103, s8, v[6:7]
	v_mad_u64_u32 v[82:83], s[14:15], v102, s8, v[6:7]
	v_mad_u64_u32 v[84:85], s[14:15], v105, s8, v[6:7]
	v_mad_u64_u32 v[86:87], s[14:15], v104, s8, v[6:7]
	v_mad_u64_u32 v[88:89], s[14:15], v107, s8, v[6:7]
	v_mad_u64_u32 v[90:91], s[14:15], v106, s8, v[6:7]
	v_mad_u64_u32 v[92:93], s[14:15], v109, s8, v[6:7]
	v_mad_u64_u32 v[94:95], s[14:15], v108, s8, v[6:7]
	s_waitcnt vmcnt(31)
; #define LAS __attribute__((address_space(3)))
; __device__ __forceinline__ unsigned cvt_pk_bf16(float lo, float hi) { f32x2_t v = {lo, hi}; bf16x2_t b = __builtin_convertvector(v, bf16x2_t); return __builtin_bit_cast(unsigned, b); }
; #define LDS_WAIT() asm volatile("s_waitcnt lgkmcnt(0)" ::: "memory")
; __device__ __forceinline__ void tr_item(const float* W, int ldw, int src_col, int nvalid, int k0, bf16_t* WT, int ldt, int dst_row, int dst_k, LAS float* scr, int lane) {
;     ...
;     for (int i = 0; i < 32; ++i) { const int kk = 2 * i + (lane >> 5), c = lane & 31; scr[kk * 33 + c] = (c < nvalid) ? W[(size_t)(k0 + kk) * ldw + src_col + c] : 0.f; }
;     LDS_WAIT();
;     const int c = lane & 7;
; #pragma unroll
;     for (int j = 0; j < 4; ++j) { const int n = (lane >> 3) + 8 * j; const LAS float* s = scr + (8 * c) * 33 + n;
;         u32x4 o; o.x = cvt_pk_bf16(s[0 * 33], s[1 * 33]); o.y = cvt_pk_bf16(s[2 * 33], s[3 * 33]); o.z = cvt_pk_bf16(s[4 * 33], s[5 * 33]); o.w = cvt_pk_bf16(s[6 * 33], s[7 * 33]);
;         *(u32x4*)(WT + (size_t)(dst_row + n) * ldt + dst_k + k0 + 8 * c) = o; }
;     LDS_WAIT();
	ds_write_b32 v148, v132
	s_waitcnt vmcnt(30)
	ds_write_b32 v149, v133
	s_waitcnt vmcnt(29)
	ds_write_b32 v150, v134
	s_waitcnt vmcnt(28)
	ds_write_b32 v151, v135
	s_waitcnt vmcnt(27)
	ds_write_b32 v152, v136
	s_waitcnt vmcnt(26)
	ds_write_b32 v153, v137
	s_waitcnt vmcnt(25)
	ds_write_b32 v154, v138
	s_waitcnt vmcnt(24)
	ds_write_b32 v155, v139
	s_waitcnt vmcnt(23)
	ds_write_b32 v156, v140
	s_waitcnt vmcnt(22)
	ds_write_b32 v157, v141
	s_waitcnt vmcnt(21)
	ds_write_b32 v158, v142
	s_waitcnt vmcnt(20)
	ds_write_b32 v159, v143
	s_waitcnt vmcnt(19)
	ds_write_b32 v160, v144
	s_waitcnt vmcnt(18)
	ds_write_b32 v161, v145
	s_waitcnt vmcnt(17)
	ds_write_b32 v162, v146
	s_waitcnt vmcnt(16)
	ds_write_b32 v163, v147
	s_waitcnt vmcnt(15)
	ds_write_b32 v52, v110
	s_waitcnt vmcnt(14)
	ds_write_b32 v54, v111
	s_waitcnt vmcnt(13)
	ds_write_b32 v56, v112
	s_waitcnt vmcnt(12)
	ds_write_b32 v58, v113
	s_waitcnt vmcnt(11)
	ds_write_b32 v60, v114
	s_waitcnt vmcnt(10)
	ds_write_b32 v62, v115
	s_waitcnt vmcnt(9)
	ds_write_b32 v64, v116
	s_waitcnt vmcnt(8)
	ds_write_b32 v78, v117
	s_waitcnt vmcnt(7)
	ds_write_b32 v80, v118
	s_waitcnt vmcnt(6)
	ds_write_b32 v82, v119
	s_waitcnt vmcnt(5)
	ds_write_b32 v84, v120
	s_waitcnt vmcnt(4)
	ds_write_b32 v86, v121
	s_waitcnt vmcnt(3)
	ds_write_b32 v88, v122
	s_waitcnt vmcnt(2)
	ds_write_b32 v90, v123
	s_waitcnt vmcnt(1)
	ds_write_b32 v92, v124
	s_waitcnt vmcnt(0)
	ds_write_b32 v94, v125
	s_waitcnt lgkmcnt(0)
	ds_read2_b32 v[54:55], v5 offset0:33 offset1:41
	ds_read2_b32 v[56:57], v5 offset1:8
	ds_read2_b32 v[58:59], v5 offset0:66 offset1:74
	ds_read2_b32 v[60:61], v5 offset0:99 offset1:107
	ds_read2_b32 v[62:63], v5 offset0:132 offset1:140
	ds_read2_b32 v[64:65], v5 offset0:165 offset1:173
	ds_read2_b32 v[78:79], v5 offset0:198 offset1:206
	ds_read2_b32 v[80:81], v5 offset0:231 offset1:239
	s_mov_b32 s5, s25
	v_or_b32_e32 v8, s2, v3
	v_lshl_add_u64 v[82:83], s[4:5], 1, v[14:15]
	v_lshlrev_b32_e32 v8, 12, v8
	s_waitcnt lgkmcnt(6)
	v_cvt_pk_bf16_f32 v50, v56, v54
	s_waitcnt lgkmcnt(4)
	v_cvt_pk_bf16_f32 v51, v58, v60
	s_waitcnt lgkmcnt(2)
	v_cvt_pk_bf16_f32 v52, v62, v64
	s_waitcnt lgkmcnt(0)
	v_cvt_pk_bf16_f32 v53, v78, v80
	v_lshl_add_u64 v[84:85], v[82:83], 0, v[8:9]
	global_store_dwordx4 v[84:85], v[50:53], off
	v_or_b32_e32 v8, s2, v7
	v_lshlrev_b32_e32 v8, 12, v8
	v_cvt_pk_bf16_f32 v50, v57, v55
	v_cvt_pk_bf16_f32 v51, v59, v61
	v_cvt_pk_bf16_f32 v52, v63, v65
	v_cvt_pk_bf16_f32 v53, v79, v81
	ds_read2_b32 v[56:57], v5 offset0:49 offset1:57
	ds_read2_b32 v[58:59], v5 offset0:16 offset1:24
	ds_read2_b32 v[60:61], v5 offset0:82 offset1:90
	ds_read2_b32 v[62:63], v5 offset0:115 offset1:123
	ds_read2_b32 v[64:65], v5 offset0:148 offset1:156
	ds_read2_b32 v[78:79], v5 offset0:181 offset1:189
	ds_read2_b32 v[80:81], v5 offset0:214 offset1:222
	ds_read2_b32 v[84:85], v5 offset0:247 offset1:255
	v_lshl_add_u64 v[54:55], v[82:83], 0, v[8:9]
	v_or_b32_e32 v8, s2, v68
	v_lshlrev_b32_e32 v8, 12, v8
	global_store_dwordx4 v[54:55], v[50:53], off
	v_lshl_add_u64 v[54:55], v[82:83], 0, v[8:9]
	v_or_b32_e32 v8, s2, v69
	s_waitcnt lgkmcnt(6)
	v_cvt_pk_bf16_f32 v50, v58, v56
	s_waitcnt lgkmcnt(4)
	v_cvt_pk_bf16_f32 v51, v60, v62
	s_waitcnt lgkmcnt(2)
	v_cvt_pk_bf16_f32 v52, v64, v78
	s_waitcnt lgkmcnt(0)
	v_cvt_pk_bf16_f32 v53, v80, v84
	v_lshlrev_b32_e32 v8, 12, v8
	global_store_dwordx4 v[54:55], v[50:53], off
	v_lshl_add_u64 v[54:55], v[82:83], 0, v[8:9]
	s_nop 0
	v_cvt_pk_bf16_f32 v50, v59, v57
	v_cvt_pk_bf16_f32 v51, v61, v63
	v_cvt_pk_bf16_f32 v52, v65, v79
	v_cvt_pk_bf16_f32 v53, v81, v85
	global_store_dwordx4 v[54:55], v[50:53], off
	s_waitcnt lgkmcnt(0)

; __device__ __forceinline__ void tr_item(const float* W, int ldw, int src_col, int nvalid, int k0, bf16_t* WT, int ldt, int dst_row, int dst_k, LAS float* scr, int lane) {
; #pragma unroll 8
;     for (int i = 0; i < 32; ++i) { const int kk = 2 * i + (lane >> 5), c = lane & 31; scr[kk * 33 + c] = (c < nvalid) ? W[(size_t)(k0 + kk) * ldw + src_col + c] : 0.f; }
.LBB0_40:
	s_lshl_b32 s14, s5, 1
	s_lshl_b32 s15, s6, 1
	v_or_b32_e32 v8, s14, v1
	v_or_b32_e32 v47, s15, v2
	s_add_i32 s16, s14, 4
	s_add_i32 s17, s15, 4
	s_add_i32 s18, s14, 8
	s_add_i32 s19, s15, 8
	s_add_i32 s23, s14, 12
	s_add_i32 s24, s15, 12
	s_add_i32 s26, s14, 16
	s_add_i32 s27, s15, 16
	s_add_i32 s28, s14, 20
	s_add_i32 s29, s15, 20
	s_add_i32 s30, s14, 24
	s_add_i32 s31, s15, 24
	s_add_i32 s14, s14, 28
	s_add_i32 s15, s15, 28
	v_add_u32_e32 v54, s4, v47
	v_or_b32_e32 v96, s16, v1
	v_or_b32_e32 v97, s17, v2
	v_or_b32_e32 v98, s18, v1
	v_or_b32_e32 v99, s19, v2
	v_or_b32_e32 v100, s23, v1
	v_or_b32_e32 v101, s24, v2
	v_or_b32_e32 v102, s26, v1
	v_or_b32_e32 v103, s27, v2
	v_or_b32_e32 v104, s28, v1
	v_or_b32_e32 v105, s29, v2
	v_or_b32_e32 v106, s30, v1
	v_or_b32_e32 v107, s31, v2
	v_or_b32_e32 v108, s14, v1
	v_or_b32_e32 v109, s15, v2
	v_add_u32_e32 v52, s3, v8
	v_ashrrev_i32_e32 v55, 31, v54
	v_add_u32_e32 v56, s3, v96
	v_add_u32_e32 v58, s4, v97
	v_add_u32_e32 v60, s3, v98
	v_add_u32_e32 v62, s4, v99
	v_add_u32_e32 v64, s3, v100
	v_add_u32_e32 v78, s4, v101
	v_add_u32_e32 v80, s3, v102
	v_add_u32_e32 v82, s4, v103
	v_add_u32_e32 v84, s3, v104
	v_add_u32_e32 v86, s4, v105
	v_add_u32_e32 v88, s3, v106
	v_add_u32_e32 v90, s4, v107
	v_add_u32_e32 v92, s3, v108
	v_add_u32_e32 v94, s4, v109
	v_ashrrev_i32_e32 v53, 31, v52
	v_lshlrev_b64 v[54:55], 10, v[54:55]
	v_ashrrev_i32_e32 v59, 31, v58
	v_ashrrev_i32_e32 v57, 31, v56
	v_ashrrev_i32_e32 v63, 31, v62
	v_ashrrev_i32_e32 v61, 31, v60
	v_ashrrev_i32_e32 v79, 31, v78
	v_ashrrev_i32_e32 v65, 31, v64
	v_ashrrev_i32_e32 v83, 31, v82
	v_ashrrev_i32_e32 v81, 31, v80
	v_ashrrev_i32_e32 v87, 31, v86
	v_ashrrev_i32_e32 v85, 31, v84
	v_ashrrev_i32_e32 v91, 31, v90
	v_ashrrev_i32_e32 v89, 31, v88
	v_ashrrev_i32_e32 v95, 31, v94
	v_ashrrev_i32_e32 v93, 31, v92
	v_lshlrev_b64 v[52:53], 10, v[52:53]
	v_lshl_add_u64 v[54:55], v[50:51], 0, v[54:55]
	v_lshlrev_b64 v[56:57], 10, v[56:57]
	v_lshlrev_b64 v[58:59], 10, v[58:59]
	v_lshlrev_b64 v[60:61], 10, v[60:61]
	v_lshlrev_b64 v[62:63], 10, v[62:63]
	v_lshlrev_b64 v[64:65], 10, v[64:65]
	v_lshlrev_b64 v[78:79], 10, v[78:79]
	v_lshlrev_b64 v[80:81], 10, v[80:81]
	v_lshlrev_b64 v[82:83], 10, v[82:83]
	v_lshlrev_b64 v[84:85], 10, v[84:85]
	v_lshlrev_b64 v[86:87], 10, v[86:87]
	v_lshlrev_b64 v[88:89], 10, v[88:89]
	v_lshlrev_b64 v[90:91], 10, v[90:91]
	v_lshlrev_b64 v[92:93], 10, v[92:93]
	v_lshlrev_b64 v[94:95], 10, v[94:95]
	v_lshl_add_u64 v[52:53], v[50:51], 0, v[52:53]
	v_lshl_add_u64 v[58:59], v[50:51], 0, v[58:59]
	v_lshl_add_u64 v[56:57], v[50:51], 0, v[56:57]
	v_lshl_add_u64 v[62:63], v[50:51], 0, v[62:63]
	v_lshl_add_u64 v[60:61], v[50:51], 0, v[60:61]
	v_lshl_add_u64 v[78:79], v[50:51], 0, v[78:79]
	v_lshl_add_u64 v[64:65], v[50:51], 0, v[64:65]
	v_lshl_add_u64 v[82:83], v[50:51], 0, v[82:83]
	v_lshl_add_u64 v[80:81], v[50:51], 0, v[80:81]
	v_lshl_add_u64 v[86:87], v[50:51], 0, v[86:87]
	v_lshl_add_u64 v[84:85], v[50:51], 0, v[84:85]
	v_lshl_add_u64 v[90:91], v[50:51], 0, v[90:91]
	v_lshl_add_u64 v[88:89], v[50:51], 0, v[88:89]
	v_lshl_add_u64 v[94:95], v[50:51], 0, v[94:95]
	v_lshl_add_u64 v[92:93], v[50:51], 0, v[92:93]
	global_load_dword v132, v[54:55], off
	global_load_dword v133, v[52:53], off
	global_load_dword v134, v[58:59], off
	global_load_dword v135, v[56:57], off
	global_load_dword v136, v[62:63], off
	global_load_dword v137, v[60:61], off
	global_load_dword v138, v[78:79], off
	global_load_dword v139, v[64:65], off
	global_load_dword v140, v[82:83], off
	global_load_dword v141, v[80:81], off
	global_load_dword v142, v[86:87], off
	global_load_dword v143, v[84:85], off
	global_load_dword v144, v[90:91], off
	global_load_dword v145, v[88:89], off
	global_load_dword v146, v[94:95], off
	global_load_dword v147, v[92:93], off
	s_add_i32 s6, s6, 16
	s_add_i32 s5, s5, 16
	s_add_i32 s7, s7, -16
	v_mad_u64_u32 v[52:53], s[14:15], v47, s8, v[6:7]
	s_cmp_lg_u32 s7, 0
	v_mad_u64_u32 v[54:55], s[14:15], v8, s8, v[6:7]
	v_mad_u64_u32 v[56:57], s[14:15], v97, s8, v[6:7]
	v_mad_u64_u32 v[58:59], s[14:15], v96, s8, v[6:7]
	v_mad_u64_u32 v[60:61], s[14:15], v99, s8, v[6:7]
	v_mad_u64_u32 v[62:63], s[14:15], v98, s8, v[6:7]
	v_mad_u64_u32 v[64:65], s[14:15], v101, s8, v[6:7]
	v_mad_u64_u32 v[78:79], s[14:15], v100, s8, v[6:7]
	v_mad_u64_u32 v[80:81], s[14:15], v103, s8, v[6:7]
	v_mad_u64_u32 v[82:83], s[14:15], v102, s8, v[6:7]
	v_mad_u64_u32 v[84:85], s[14:15], v105, s8, v[6:7]
	v_mad_u64_u32 v[86:87], s[14:15], v104, s8, v[6:7]
	v_mad_u64_u32 v[88:89], s[14:15], v107, s8, v[6:7]
	v_mad_u64_u32 v[90:91], s[14:15], v106, s8, v[6:7]
	v_mad_u64_u32 v[92:93], s[14:15], v109, s8, v[6:7]
	v_mad_u64_u32 v[94:95], s[14:15], v108, s8, v[6:7]
	v_mov_b32_e32 v148, v52
	v_mov_b32_e32 v149, v54
	v_mov_b32_e32 v150, v56
	v_mov_b32_e32 v151, v58
	v_mov_b32_e32 v152, v60
	v_mov_b32_e32 v153, v62
	v_mov_b32_e32 v154, v64
	v_mov_b32_e32 v155, v78
	v_mov_b32_e32 v156, v80
	v_mov_b32_e32 v157, v82
	v_mov_b32_e32 v158, v84
	v_mov_b32_e32 v159, v86
	v_mov_b32_e32 v160, v88
	v_mov_b32_e32 v161, v90
	v_mov_b32_e32 v162, v92
	v_mov_b32_e32 v163, v94
	s_lshl_b32 s14, s5, 1
	s_lshl_b32 s15, s6, 1
	v_or_b32_e32 v8, s14, v1
	v_or_b32_e32 v47, s15, v2
	s_add_i32 s16, s14, 4
	s_add_i32 s17, s15, 4
	s_add_i32 s18, s14, 8
	s_add_i32 s19, s15, 8
	s_add_i32 s23, s14, 12
	s_add_i32 s24, s15, 12
	s_add_i32 s26, s14, 16
	s_add_i32 s27, s15, 16
	s_add_i32 s28, s14, 20
	s_add_i32 s29, s15, 20
	s_add_i32 s30, s14, 24
	s_add_i32 s31, s15, 24
	s_add_i32 s14, s14, 28
	s_add_i32 s15, s15, 28
	v_add_u32_e32 v54, s4, v47
	v_or_b32_e32 v96, s16, v1
	v_or_b32_e32 v97, s17, v2
	v_or_b32_e32 v98, s18, v1
; __device__ __forceinline__ void tr_item(const float* W, int ldw, int src_col, int nvalid, int k0, bf16_t* WT, int ldt, int dst_row, int dst_k, LAS float* scr, int lane) {
; #pragma unroll 8
;     for (int i = 0; i < 32; ++i) { const int kk = 2 * i + (lane >> 5), c = lane & 31; scr[kk * 33 + c] = (c < nvalid) ? W[(size_t)(k0 + kk) * ldw + src_col + c] : 0.f; }
	v_or_b32_e32 v99, s19, v2
	v_or_b32_e32 v100, s23, v1
	v_or_b32_e32 v101, s24, v2
	v_or_b32_e32 v102, s26, v1
	v_or_b32_e32 v103, s27, v2
	v_or_b32_e32 v104, s28, v1
	v_or_b32_e32 v105, s29, v2
	v_or_b32_e32 v106, s30, v1
	v_or_b32_e32 v107, s31, v2
	v_or_b32_e32 v108, s14, v1
	v_or_b32_e32 v109, s15, v2
	v_add_u32_e32 v52, s3, v8
	v_ashrrev_i32_e32 v55, 31, v54
	v_add_u32_e32 v56, s3, v96
	v_add_u32_e32 v58, s4, v97
	v_add_u32_e32 v60, s3, v98
	v_add_u32_e32 v62, s4, v99
	v_add_u32_e32 v64, s3, v100
	v_add_u32_e32 v78, s4, v101
	v_add_u32_e32 v80, s3, v102
	v_add_u32_e32 v82, s4, v103
	v_add_u32_e32 v84, s3, v104
	v_add_u32_e32 v86, s4, v105
	v_add_u32_e32 v88, s3, v106
	v_add_u32_e32 v90, s4, v107
	v_add_u32_e32 v92, s3, v108
	v_add_u32_e32 v94, s4, v109
	v_ashrrev_i32_e32 v53, 31, v52
	v_lshlrev_b64 v[54:55], 10, v[54:55]
	v_ashrrev_i32_e32 v59, 31, v58
	v_ashrrev_i32_e32 v57, 31, v56
	v_ashrrev_i32_e32 v63, 31, v62
	v_ashrrev_i32_e32 v61, 31, v60
	v_ashrrev_i32_e32 v79, 31, v78
	v_ashrrev_i32_e32 v65, 31, v64
	v_ashrrev_i32_e32 v83, 31, v82
	v_ashrrev_i32_e32 v81, 31, v80
	v_ashrrev_i32_e32 v87, 31, v86
	v_ashrrev_i32_e32 v85, 31, v84
	v_ashrrev_i32_e32 v91, 31, v90
	v_ashrrev_i32_e32 v89, 31, v88
	v_ashrrev_i32_e32 v95, 31, v94
	v_ashrrev_i32_e32 v93, 31, v92
	v_lshlrev_b64 v[52:53], 10, v[52:53]
	v_lshl_add_u64 v[54:55], v[50:51], 0, v[54:55]
	v_lshlrev_b64 v[56:57], 10, v[56:57]
	v_lshlrev_b64 v[58:59], 10, v[58:59]
	v_lshlrev_b64 v[60:61], 10, v[60:61]
	v_lshlrev_b64 v[62:63], 10, v[62:63]
	v_lshlrev_b64 v[64:65], 10, v[64:65]
	v_lshlrev_b64 v[78:79], 10, v[78:79]
	v_lshlrev_b64 v[80:81], 10, v[80:81]
	v_lshlrev_b64 v[82:83], 10, v[82:83]
	v_lshlrev_b64 v[84:85], 10, v[84:85]
	v_lshlrev_b64 v[86:87], 10, v[86:87]
	v_lshlrev_b64 v[88:89], 10, v[88:89]
	v_lshlrev_b64 v[90:91], 10, v[90:91]
	v_lshlrev_b64 v[92:93], 10, v[92:93]
	v_lshlrev_b64 v[94:95], 10, v[94:95]
	v_lshl_add_u64 v[52:53], v[50:51], 0, v[52:53]
	v_lshl_add_u64 v[58:59], v[50:51], 0, v[58:59]
	v_lshl_add_u64 v[56:57], v[50:51], 0, v[56:57]
	v_lshl_add_u64 v[62:63], v[50:51], 0, v[62:63]
	v_lshl_add_u64 v[60:61], v[50:51], 0, v[60:61]
	v_lshl_add_u64 v[78:79], v[50:51], 0, v[78:79]
	v_lshl_add_u64 v[64:65], v[50:51], 0, v[64:65]
	v_lshl_add_u64 v[82:83], v[50:51], 0, v[82:83]
	v_lshl_add_u64 v[80:81], v[50:51], 0, v[80:81]
	v_lshl_add_u64 v[86:87], v[50:51], 0, v[86:87]
	v_lshl_add_u64 v[84:85], v[50:51], 0, v[84:85]
	v_lshl_add_u64 v[90:91], v[50:51], 0, v[90:91]
	v_lshl_add_u64 v[88:89], v[50:51], 0, v[88:89]
	v_lshl_add_u64 v[94:95], v[50:51], 0, v[94:95]
	v_lshl_add_u64 v[92:93], v[50:51], 0, v[92:93]
	global_load_dword v110, v[54:55], off
	global_load_dword v111, v[52:53], off
	global_load_dword v112, v[58:59], off
	global_load_dword v113, v[56:57], off
	global_load_dword v114, v[62:63], off
	global_load_dword v115, v[60:61], off
	global_load_dword v116, v[78:79], off
	global_load_dword v117, v[64:65], off
	global_load_dword v118, v[82:83], off
	global_load_dword v119, v[80:81], off
	global_load_dword v120, v[86:87], off
	global_load_dword v121, v[84:85], off
	global_load_dword v122, v[90:91], off
	global_load_dword v123, v[88:89], off
	global_load_dword v124, v[94:95], off
	global_load_dword v125, v[92:93], off
	s_add_i32 s6, s6, 16
	s_add_i32 s5, s5, 16
	s_add_i32 s7, s7, -16
	v_mad_u64_u32 v[52:53], s[14:15], v47, s8, v[6:7]
	s_cmp_lg_u32 s7, 0
	v_mad_u64_u32 v[54:55], s[14:15], v8, s8, v[6:7]
	v_mad_u64_u32 v[56:57], s[14:15], v97, s8, v[6:7]
	v_mad_u64_u32 v[58:59], s[14:15], v96, s8, v[6:7]
	v_mad_u64_u32 v[60:61], s[14:15], v99, s8, v[6:7]
	v_mad_u64_u32 v[62:63], s[14:15], v98, s8, v[6:7]
	v_mad_u64_u32 v[64:65], s[14:15], v101, s8, v[6:7]
	v_mad_u64_u32 v[78:79], s[14:15], v100, s8, v[6:7]
	v_mad_u64_u32 v[80:81], s[14:15], v103, s8, v[6:7]
	v_mad_u64_u32 v[82:83], s[14:15], v102, s8, v[6:7]
	v_mad_u64_u32 v[84:85], s[14:15], v105, s8, v[6:7]
	v_mad_u64_u32 v[86:87], s[14:15], v104, s8, v[6:7]
	v_mad_u64_u32 v[88:89], s[14:15], v107, s8, v[6:7]
	v_mad_u64_u32 v[90:91], s[14:15], v106, s8, v[6:7]
	v_mad_u64_u32 v[92:93], s[14:15], v109, s8, v[6:7]
	v_mad_u64_u32 v[94:95], s[14:15], v108, s8, v[6:7]
	s_waitcnt vmcnt(31)
; #define LAS __attribute__((address_space(3)))
; __device__ __forceinline__ unsigned cvt_pk_bf16(float lo, float hi) { f32x2_t v = {lo, hi}; bf16x2_t b = __builtin_convertvector(v, bf16x2_t); return __builtin_bit_cast(unsigned, b); }
; #define LDS_WAIT() asm volatile("s_waitcnt lgkmcnt(0)" ::: "memory")
; __device__ __forceinline__ void tr_item(const float* W, int ldw, int src_col, int nvalid, int k0, bf16_t* WT, int ldt, int dst_row, int dst_k, LAS float* scr, int lane) {
;     ...
;     for (int i = 0; i < 32; ++i) { const int kk = 2 * i + (lane >> 5), c = lane & 31; scr[kk * 33 + c] = (c < nvalid) ? W[(size_t)(k0 + kk) * ldw + src_col + c] : 0.f; }
;     LDS_WAIT();
;     const int c = lane & 7;
; #pragma unroll
;     for (int j = 0; j < 4; ++j) { const int n = (lane >> 3) + 8 * j; const LAS float* s = scr + (8 * c) * 33 + n;
;         u32x4 o; o.x = cvt_pk_bf16(s[0 * 33], s[1 * 33]); o.y = cvt_pk_bf16(s[2 * 33], s[3 * 33]); o.z = cvt_pk_bf16(s[4 * 33], s[5 * 33]); o.w = cvt_pk_bf16(s[6 * 33], s[7 * 33]);
;         *(u32x4*)(WT + (size_t)(dst_row + n) * ldt + dst_k + k0 + 8 * c) = o; }
;     LDS_WAIT();
	ds_write_b32 v148, v132
	s_waitcnt vmcnt(30)
	ds_write_b32 v149, v133
	s_waitcnt vmcnt(29)
	ds_write_b32 v150, v134
	s_waitcnt vmcnt(28)
	ds_write_b32 v151, v135
	s_waitcnt vmcnt(27)
	ds_write_b32 v152, v136
	s_waitcnt vmcnt(26)
	ds_write_b32 v153, v137
	s_waitcnt vmcnt(25)
	ds_write_b32 v154, v138
	s_waitcnt vmcnt(24)
	ds_write_b32 v155, v139
	s_waitcnt vmcnt(23)
	ds_write_b32 v156, v140
	s_waitcnt vmcnt(22)
	ds_write_b32 v157, v141
	s_waitcnt vmcnt(21)
	ds_write_b32 v158, v142
	s_waitcnt vmcnt(20)
	ds_write_b32 v159, v143
	s_waitcnt vmcnt(19)
	ds_write_b32 v160, v144
	s_waitcnt vmcnt(18)
	ds_write_b32 v161, v145
	s_waitcnt vmcnt(17)
	ds_write_b32 v162, v146
	s_waitcnt vmcnt(16)
	ds_write_b32 v163, v147
	s_waitcnt vmcnt(15)
	ds_write_b32 v52, v110
	s_waitcnt vmcnt(14)
	ds_write_b32 v54, v111
	s_waitcnt vmcnt(13)
	ds_write_b32 v56, v112
	s_waitcnt vmcnt(12)
	ds_write_b32 v58, v113
	s_waitcnt vmcnt(11)
	ds_write_b32 v60, v114
	s_waitcnt vmcnt(10)
	ds_write_b32 v62, v115
	s_waitcnt vmcnt(9)
	ds_write_b32 v64, v116
	s_waitcnt vmcnt(8)
	ds_write_b32 v78, v117
	s_waitcnt vmcnt(7)
	ds_write_b32 v80, v118
	s_waitcnt vmcnt(6)
	ds_write_b32 v82, v119
	s_waitcnt vmcnt(5)
	ds_write_b32 v84, v120
	s_waitcnt vmcnt(4)
	ds_write_b32 v86, v121
	s_waitcnt vmcnt(3)
	ds_write_b32 v88, v122
	s_waitcnt vmcnt(2)
	ds_write_b32 v90, v123
	s_waitcnt vmcnt(1)
	ds_write_b32 v92, v124
	s_waitcnt vmcnt(0)
	ds_write_b32 v94, v125
	s_waitcnt lgkmcnt(0)
	ds_read2_b32 v[54:55], v5 offset0:33 offset1:41
	ds_read2_b32 v[56:57], v5 offset1:8
	ds_read2_b32 v[58:59], v5 offset0:66 offset1:74
	ds_read2_b32 v[60:61], v5 offset0:99 offset1:107
	ds_read2_b32 v[62:63], v5 offset0:132 offset1:140
	ds_read2_b32 v[64:65], v5 offset0:165 offset1:173
	ds_read2_b32 v[78:79], v5 offset0:198 offset1:206
	ds_read2_b32 v[80:81], v5 offset0:231 offset1:239
	s_mov_b32 s5, s25
	v_or_b32_e32 v8, s2, v3
	v_lshl_add_u64 v[82:83], s[4:5], 1, v[16:17]
	v_lshlrev_b32_e32 v8, 12, v8
	s_waitcnt lgkmcnt(6)
	v_cvt_pk_bf16_f32 v50, v56, v54
	s_waitcnt lgkmcnt(4)
	v_cvt_pk_bf16_f32 v51, v58, v60
	s_waitcnt lgkmcnt(2)
	v_cvt_pk_bf16_f32 v52, v62, v64
	s_waitcnt lgkmcnt(0)
	v_cvt_pk_bf16_f32 v53, v78, v80
	v_lshl_add_u64 v[84:85], v[82:83], 0, v[8:9]
	global_store_dwordx4 v[84:85], v[50:53], off
	v_or_b32_e32 v8, s2, v7
	v_lshlrev_b32_e32 v8, 12, v8
	v_cvt_pk_bf16_f32 v50, v57, v55
	v_cvt_pk_bf16_f32 v51, v59, v61
	v_cvt_pk_bf16_f32 v52, v63, v65
	v_cvt_pk_bf16_f32 v53, v79, v81
	ds_read2_b32 v[56:57], v5 offset0:49 offset1:57
	ds_read2_b32 v[58:59], v5 offset0:16 offset1:24
	ds_read2_b32 v[60:61], v5 offset0:82 offset1:90
	ds_read2_b32 v[62:63], v5 offset0:115 offset1:123
	ds_read2_b32 v[64:65], v5 offset0:148 offset1:156
	ds_read2_b32 v[78:79], v5 offset0:181 offset1:189
	ds_read2_b32 v[80:81], v5 offset0:214 offset1:222
	ds_read2_b32 v[84:85], v5 offset0:247 offset1:255
	v_lshl_add_u64 v[54:55], v[82:83], 0, v[8:9]
	v_or_b32_e32 v8, s2, v68
	v_lshlrev_b32_e32 v8, 12, v8
	global_store_dwordx4 v[54:55], v[50:53], off
	v_lshl_add_u64 v[54:55], v[82:83], 0, v[8:9]
	v_or_b32_e32 v8, s2, v69
	s_waitcnt lgkmcnt(6)
	v_cvt_pk_bf16_f32 v50, v58, v56
	s_waitcnt lgkmcnt(4)
	v_cvt_pk_bf16_f32 v51, v60, v62
	s_waitcnt lgkmcnt(2)
	v_cvt_pk_bf16_f32 v52, v64, v78
	s_waitcnt lgkmcnt(0)
	v_cvt_pk_bf16_f32 v53, v80, v84
	v_lshlrev_b32_e32 v8, 12, v8
	global_store_dwordx4 v[54:55], v[50:53], off
	v_lshl_add_u64 v[54:55], v[82:83], 0, v[8:9]
	s_nop 0
	v_cvt_pk_bf16_f32 v50, v59, v57
	v_cvt_pk_bf16_f32 v51, v61, v63
	v_cvt_pk_bf16_f32 v52, v65, v79
	v_cvt_pk_bf16_f32 v53, v81, v85
	global_store_dwordx4 v[54:55], v[50:53], off
	s_waitcnt lgkmcnt(0)

; __device__ __forceinline__ void tr_item(const float* W, int ldw, int src_col, int nvalid, int k0, bf16_t* WT, int ldt, int dst_row, int dst_k, LAS float* scr, int lane) {
; #pragma unroll 8
;     for (int i = 0; i < 32; ++i) { const int kk = 2 * i + (lane >> 5), c = lane & 31; scr[kk * 33 + c] = (c < nvalid) ? W[(size_t)(k0 + kk) * ldw + src_col + c] : 0.f; }
.LBB0_45:
	s_lshl_b32 s14, s3, 1
	s_lshl_b32 s15, s6, 1
	v_or_b32_e32 v8, s14, v1
	v_or_b32_e32 v47, s15, v2
	s_add_i32 s16, s14, 4
	s_add_i32 s17, s15, 4
	s_add_i32 s18, s14, 8
	s_add_i32 s19, s15, 8
	s_add_i32 s23, s14, 12
	s_add_i32 s24, s15, 12
	s_add_i32 s26, s14, 16
	s_add_i32 s27, s15, 16
	s_add_i32 s28, s14, 20
	s_add_i32 s29, s15, 20
	s_add_i32 s30, s14, 24
	s_add_i32 s31, s15, 24
	s_add_i32 s14, s14, 28
	s_add_i32 s15, s15, 28
	v_add_u32_e32 v54, s4, v47
	v_or_b32_e32 v96, s16, v1
	v_or_b32_e32 v97, s17, v2
	v_or_b32_e32 v98, s18, v1
	v_or_b32_e32 v99, s19, v2
	v_or_b32_e32 v100, s23, v1
	v_or_b32_e32 v101, s24, v2
	v_or_b32_e32 v102, s26, v1
	v_or_b32_e32 v103, s27, v2
	v_or_b32_e32 v104, s28, v1
	v_or_b32_e32 v105, s29, v2
	v_or_b32_e32 v106, s30, v1
	v_or_b32_e32 v107, s31, v2
	v_or_b32_e32 v108, s14, v1
	v_or_b32_e32 v109, s15, v2
	v_add_u32_e32 v52, s5, v8
	v_ashrrev_i32_e32 v55, 31, v54
	v_add_u32_e32 v56, s5, v96
	v_add_u32_e32 v58, s4, v97
	v_add_u32_e32 v60, s5, v98
	v_add_u32_e32 v62, s4, v99
	v_add_u32_e32 v64, s5, v100
	v_add_u32_e32 v78, s4, v101
	v_add_u32_e32 v80, s5, v102
	v_add_u32_e32 v82, s4, v103
	v_add_u32_e32 v84, s5, v104
	v_add_u32_e32 v86, s4, v105
	v_add_u32_e32 v88, s5, v106
	v_add_u32_e32 v90, s4, v107
	v_add_u32_e32 v92, s5, v108
	v_add_u32_e32 v94, s4, v109
	v_ashrrev_i32_e32 v53, 31, v52
	v_lshlrev_b64 v[54:55], 12, v[54:55]
	v_ashrrev_i32_e32 v59, 31, v58
	v_ashrrev_i32_e32 v57, 31, v56
	v_ashrrev_i32_e32 v63, 31, v62
	v_ashrrev_i32_e32 v61, 31, v60
	v_ashrrev_i32_e32 v79, 31, v78
	v_ashrrev_i32_e32 v65, 31, v64
	v_ashrrev_i32_e32 v83, 31, v82
	v_ashrrev_i32_e32 v81, 31, v80
	v_ashrrev_i32_e32 v87, 31, v86
	v_ashrrev_i32_e32 v85, 31, v84
	v_ashrrev_i32_e32 v91, 31, v90
	v_ashrrev_i32_e32 v89, 31, v88
	v_ashrrev_i32_e32 v95, 31, v94
	v_ashrrev_i32_e32 v93, 31, v92
	v_lshlrev_b64 v[52:53], 12, v[52:53]
	v_lshl_add_u64 v[54:55], v[50:51], 0, v[54:55]
	v_lshlrev_b64 v[56:57], 12, v[56:57]
	v_lshlrev_b64 v[58:59], 12, v[58:59]
	v_lshlrev_b64 v[60:61], 12, v[60:61]
	v_lshlrev_b64 v[62:63], 12, v[62:63]
	v_lshlrev_b64 v[64:65], 12, v[64:65]
	v_lshlrev_b64 v[78:79], 12, v[78:79]
	v_lshlrev_b64 v[80:81], 12, v[80:81]
	v_lshlrev_b64 v[82:83], 12, v[82:83]
	v_lshlrev_b64 v[84:85], 12, v[84:85]
	v_lshlrev_b64 v[86:87], 12, v[86:87]
	v_lshlrev_b64 v[88:89], 12, v[88:89]
	v_lshlrev_b64 v[90:91], 12, v[90:91]
	v_lshlrev_b64 v[92:93], 12, v[92:93]
	v_lshlrev_b64 v[94:95], 12, v[94:95]
	v_lshl_add_u64 v[52:53], v[50:51], 0, v[52:53]
	v_lshl_add_u64 v[58:59], v[50:51], 0, v[58:59]
	v_lshl_add_u64 v[56:57], v[50:51], 0, v[56:57]
	v_lshl_add_u64 v[62:63], v[50:51], 0, v[62:63]
	v_lshl_add_u64 v[60:61], v[50:51], 0, v[60:61]
	v_lshl_add_u64 v[78:79], v[50:51], 0, v[78:79]
	v_lshl_add_u64 v[64:65], v[50:51], 0, v[64:65]
	v_lshl_add_u64 v[82:83], v[50:51], 0, v[82:83]
	v_lshl_add_u64 v[80:81], v[50:51], 0, v[80:81]
	v_lshl_add_u64 v[86:87], v[50:51], 0, v[86:87]
	v_lshl_add_u64 v[84:85], v[50:51], 0, v[84:85]
	v_lshl_add_u64 v[90:91], v[50:51], 0, v[90:91]
	v_lshl_add_u64 v[88:89], v[50:51], 0, v[88:89]
	v_lshl_add_u64 v[94:95], v[50:51], 0, v[94:95]
	v_lshl_add_u64 v[92:93], v[50:51], 0, v[92:93]
	global_load_dword v132, v[54:55], off
	global_load_dword v133, v[52:53], off
	global_load_dword v134, v[58:59], off
	global_load_dword v135, v[56:57], off
	global_load_dword v136, v[62:63], off
	global_load_dword v137, v[60:61], off
	global_load_dword v138, v[78:79], off
	global_load_dword v139, v[64:65], off
	global_load_dword v140, v[82:83], off
	global_load_dword v141, v[80:81], off
	global_load_dword v142, v[86:87], off
	global_load_dword v143, v[84:85], off
	global_load_dword v144, v[90:91], off
	global_load_dword v145, v[88:89], off
	global_load_dword v146, v[94:95], off
	global_load_dword v147, v[92:93], off
	s_add_i32 s6, s6, 16
	s_add_i32 s3, s3, 16
	s_add_i32 s7, s7, -16
	v_mad_u64_u32 v[52:53], s[14:15], v47, s8, v[6:7]
	s_cmp_lg_u32 s7, 0
	v_mad_u64_u32 v[54:55], s[14:15], v8, s8, v[6:7]
	v_mad_u64_u32 v[56:57], s[14:15], v97, s8, v[6:7]
	v_mad_u64_u32 v[58:59], s[14:15], v96, s8, v[6:7]
	v_mad_u64_u32 v[60:61], s[14:15], v99, s8, v[6:7]
	v_mad_u64_u32 v[62:63], s[14:15], v98, s8, v[6:7]
	v_mad_u64_u32 v[64:65], s[14:15], v101, s8, v[6:7]
	v_mad_u64_u32 v[78:79], s[14:15], v100, s8, v[6:7]
	v_mad_u64_u32 v[80:81], s[14:15], v103, s8, v[6:7]
	v_mad_u64_u32 v[82:83], s[14:15], v102, s8, v[6:7]
	v_mad_u64_u32 v[84:85], s[14:15], v105, s8, v[6:7]
	v_mad_u64_u32 v[86:87], s[14:15], v104, s8, v[6:7]
	v_mad_u64_u32 v[88:89], s[14:15], v107, s8, v[6:7]
	v_mad_u64_u32 v[90:91], s[14:15], v106, s8, v[6:7]
	v_mad_u64_u32 v[92:93], s[14:15], v109, s8, v[6:7]
	v_mad_u64_u32 v[94:95], s[14:15], v108, s8, v[6:7]
	v_mov_b32_e32 v148, v52
	v_mov_b32_e32 v149, v54
	v_mov_b32_e32 v150, v56
	v_mov_b32_e32 v151, v58
	v_mov_b32_e32 v152, v60
	v_mov_b32_e32 v153, v62
	v_mov_b32_e32 v154, v64
	v_mov_b32_e32 v155, v78
	v_mov_b32_e32 v156, v80
	v_mov_b32_e32 v157, v82
	v_mov_b32_e32 v158, v84
	v_mov_b32_e32 v159, v86
	v_mov_b32_e32 v160, v88
	v_mov_b32_e32 v161, v90
	v_mov_b32_e32 v162, v92
	v_mov_b32_e32 v163, v94
	s_lshl_b32 s14, s3, 1
	s_lshl_b32 s15, s6, 1
	v_or_b32_e32 v8, s14, v1
	v_or_b32_e32 v47, s15, v2
	s_add_i32 s16, s14, 4
	s_add_i32 s17, s15, 4
	s_add_i32 s18, s14, 8
	s_add_i32 s19, s15, 8
	s_add_i32 s23, s14, 12
	s_add_i32 s24, s15, 12
	s_add_i32 s26, s14, 16
	s_add_i32 s27, s15, 16
	s_add_i32 s28, s14, 20
	s_add_i32 s29, s15, 20
	s_add_i32 s30, s14, 24
	s_add_i32 s31, s15, 24
	s_add_i32 s14, s14, 28
	s_add_i32 s15, s15, 28
	v_add_u32_e32 v54, s4, v47
	v_or_b32_e32 v96, s16, v1
	v_or_b32_e32 v97, s17, v2
	v_or_b32_e32 v98, s18, v1
; __device__ __forceinline__ void tr_item(const float* W, int ldw, int src_col, int nvalid, int k0, bf16_t* WT, int ldt, int dst_row, int dst_k, LAS float* scr, int lane) {
; #pragma unroll 8
;     for (int i = 0; i < 32; ++i) { const int kk = 2 * i + (lane >> 5), c = lane & 31; scr[kk * 33 + c] = (c < nvalid) ? W[(size_t)(k0 + kk) * ldw + src_col + c] : 0.f; }
	v_or_b32_e32 v99, s19, v2
	v_or_b32_e32 v100, s23, v1
	v_or_b32_e32 v101, s24, v2
	v_or_b32_e32 v102, s26, v1
	v_or_b32_e32 v103, s27, v2
	v_or_b32_e32 v104, s28, v1
	v_or_b32_e32 v105, s29, v2
	v_or_b32_e32 v106, s30, v1
	v_or_b32_e32 v107, s31, v2
	v_or_b32_e32 v108, s14, v1
	v_or_b32_e32 v109, s15, v2
	v_add_u32_e32 v52, s5, v8
	v_ashrrev_i32_e32 v55, 31, v54
	v_add_u32_e32 v56, s5, v96
	v_add_u32_e32 v58, s4, v97
	v_add_u32_e32 v60, s5, v98
	v_add_u32_e32 v62, s4, v99
	v_add_u32_e32 v64, s5, v100
	v_add_u32_e32 v78, s4, v101
	v_add_u32_e32 v80, s5, v102
	v_add_u32_e32 v82, s4, v103
	v_add_u32_e32 v84, s5, v104
	v_add_u32_e32 v86, s4, v105
	v_add_u32_e32 v88, s5, v106
	v_add_u32_e32 v90, s4, v107
	v_add_u32_e32 v92, s5, v108
	v_add_u32_e32 v94, s4, v109
	v_ashrrev_i32_e32 v53, 31, v52
	v_lshlrev_b64 v[54:55], 12, v[54:55]
	v_ashrrev_i32_e32 v59, 31, v58
	v_ashrrev_i32_e32 v57, 31, v56
	v_ashrrev_i32_e32 v63, 31, v62
	v_ashrrev_i32_e32 v61, 31, v60
	v_ashrrev_i32_e32 v79, 31, v78
	v_ashrrev_i32_e32 v65, 31, v64
	v_ashrrev_i32_e32 v83, 31, v82
	v_ashrrev_i32_e32 v81, 31, v80
	v_ashrrev_i32_e32 v87, 31, v86
	v_ashrrev_i32_e32 v85, 31, v84
	v_ashrrev_i32_e32 v91, 31, v90
	v_ashrrev_i32_e32 v89, 31, v88
	v_ashrrev_i32_e32 v95, 31, v94
	v_ashrrev_i32_e32 v93, 31, v92
	v_lshlrev_b64 v[52:53], 12, v[52:53]
	v_lshl_add_u64 v[54:55], v[50:51], 0, v[54:55]
	v_lshlrev_b64 v[56:57], 12, v[56:57]
	v_lshlrev_b64 v[58:59], 12, v[58:59]
	v_lshlrev_b64 v[60:61], 12, v[60:61]
	v_lshlrev_b64 v[62:63], 12, v[62:63]
	v_lshlrev_b64 v[64:65], 12, v[64:65]
	v_lshlrev_b64 v[78:79], 12, v[78:79]
	v_lshlrev_b64 v[80:81], 12, v[80:81]
	v_lshlrev_b64 v[82:83], 12, v[82:83]
	v_lshlrev_b64 v[84:85], 12, v[84:85]
	v_lshlrev_b64 v[86:87], 12, v[86:87]
	v_lshlrev_b64 v[88:89], 12, v[88:89]
	v_lshlrev_b64 v[90:91], 12, v[90:91]
	v_lshlrev_b64 v[92:93], 12, v[92:93]
	v_lshlrev_b64 v[94:95], 12, v[94:95]
	v_lshl_add_u64 v[52:53], v[50:51], 0, v[52:53]
	v_lshl_add_u64 v[58:59], v[50:51], 0, v[58:59]
	v_lshl_add_u64 v[56:57], v[50:51], 0, v[56:57]
	v_lshl_add_u64 v[62:63], v[50:51], 0, v[62:63]
	v_lshl_add_u64 v[60:61], v[50:51], 0, v[60:61]
	v_lshl_add_u64 v[78:79], v[50:51], 0, v[78:79]
	v_lshl_add_u64 v[64:65], v[50:51], 0, v[64:65]
	v_lshl_add_u64 v[82:83], v[50:51], 0, v[82:83]
	v_lshl_add_u64 v[80:81], v[50:51], 0, v[80:81]
	v_lshl_add_u64 v[86:87], v[50:51], 0, v[86:87]
	v_lshl_add_u64 v[84:85], v[50:51], 0, v[84:85]
	v_lshl_add_u64 v[90:91], v[50:51], 0, v[90:91]
	v_lshl_add_u64 v[88:89], v[50:51], 0, v[88:89]
	v_lshl_add_u64 v[94:95], v[50:51], 0, v[94:95]
	v_lshl_add_u64 v[92:93], v[50:51], 0, v[92:93]
	global_load_dword v110, v[54:55], off
	global_load_dword v111, v[52:53], off
	global_load_dword v112, v[58:59], off
	global_load_dword v113, v[56:57], off
	global_load_dword v114, v[62:63], off
	global_load_dword v115, v[60:61], off
	global_load_dword v116, v[78:79], off
	global_load_dword v117, v[64:65], off
	global_load_dword v118, v[82:83], off
	global_load_dword v119, v[80:81], off
	global_load_dword v120, v[86:87], off
	global_load_dword v121, v[84:85], off
	global_load_dword v122, v[90:91], off
	global_load_dword v123, v[88:89], off
	global_load_dword v124, v[94:95], off
	global_load_dword v125, v[92:93], off
	s_add_i32 s6, s6, 16
	s_add_i32 s3, s3, 16
	s_add_i32 s7, s7, -16
	v_mad_u64_u32 v[52:53], s[14:15], v47, s8, v[6:7]
	s_cmp_lg_u32 s7, 0
	v_mad_u64_u32 v[54:55], s[14:15], v8, s8, v[6:7]
	v_mad_u64_u32 v[56:57], s[14:15], v97, s8, v[6:7]
	v_mad_u64_u32 v[58:59], s[14:15], v96, s8, v[6:7]
	v_mad_u64_u32 v[60:61], s[14:15], v99, s8, v[6:7]
	v_mad_u64_u32 v[62:63], s[14:15], v98, s8, v[6:7]
	v_mad_u64_u32 v[64:65], s[14:15], v101, s8, v[6:7]
	v_mad_u64_u32 v[78:79], s[14:15], v100, s8, v[6:7]
	v_mad_u64_u32 v[80:81], s[14:15], v103, s8, v[6:7]
	v_mad_u64_u32 v[82:83], s[14:15], v102, s8, v[6:7]
	v_mad_u64_u32 v[84:85], s[14:15], v105, s8, v[6:7]
	v_mad_u64_u32 v[86:87], s[14:15], v104, s8, v[6:7]
	v_mad_u64_u32 v[88:89], s[14:15], v107, s8, v[6:7]
	v_mad_u64_u32 v[90:91], s[14:15], v106, s8, v[6:7]
	v_mad_u64_u32 v[92:93], s[14:15], v109, s8, v[6:7]
	v_mad_u64_u32 v[94:95], s[14:15], v108, s8, v[6:7]
	s_waitcnt vmcnt(31)
; #define LAS __attribute__((address_space(3)))
; __device__ __forceinline__ unsigned cvt_pk_bf16(float lo, float hi) { f32x2_t v = {lo, hi}; bf16x2_t b = __builtin_convertvector(v, bf16x2_t); return __builtin_bit_cast(unsigned, b); }
; #define LDS_WAIT() asm volatile("s_waitcnt lgkmcnt(0)" ::: "memory")
; __device__ __forceinline__ void tr_item(const float* W, int ldw, int src_col, int nvalid, int k0, bf16_t* WT, int ldt, int dst_row, int dst_k, LAS float* scr, int lane) {
;     ...
;     for (int i = 0; i < 32; ++i) { const int kk = 2 * i + (lane >> 5), c = lane & 31; scr[kk * 33 + c] = (c < nvalid) ? W[(size_t)(k0 + kk) * ldw + src_col + c] : 0.f; }
;     LDS_WAIT();
;     const int c = lane & 7;
; #pragma unroll
;     for (int j = 0; j < 4; ++j) { const int n = (lane >> 3) + 8 * j; const LAS float* s = scr + (8 * c) * 33 + n;
;         u32x4 o; o.x = cvt_pk_bf16(s[0 * 33], s[1 * 33]); o.y = cvt_pk_bf16(s[2 * 33], s[3 * 33]); o.z = cvt_pk_bf16(s[4 * 33], s[5 * 33]); o.w = cvt_pk_bf16(s[6 * 33], s[7 * 33]);
;         *(u32x4*)(WT + (size_t)(dst_row + n) * ldt + dst_k + k0 + 8 * c) = o; }
;     LDS_WAIT();
	ds_write_b32 v148, v132
	s_waitcnt vmcnt(30)
	ds_write_b32 v149, v133
	s_waitcnt vmcnt(29)
	ds_write_b32 v150, v134
	s_waitcnt vmcnt(28)
	ds_write_b32 v151, v135
	s_waitcnt vmcnt(27)
	ds_write_b32 v152, v136
	s_waitcnt vmcnt(26)
	ds_write_b32 v153, v137
	s_waitcnt vmcnt(25)
	ds_write_b32 v154, v138
	s_waitcnt vmcnt(24)
	ds_write_b32 v155, v139
	s_waitcnt vmcnt(23)
	ds_write_b32 v156, v140
	s_waitcnt vmcnt(22)
	ds_write_b32 v157, v141
	s_waitcnt vmcnt(21)
	ds_write_b32 v158, v142
	s_waitcnt vmcnt(20)
	ds_write_b32 v159, v143
	s_waitcnt vmcnt(19)
	ds_write_b32 v160, v144
	s_waitcnt vmcnt(18)
	ds_write_b32 v161, v145
	s_waitcnt vmcnt(17)
	ds_write_b32 v162, v146
	s_waitcnt vmcnt(16)
	ds_write_b32 v163, v147
	s_waitcnt vmcnt(15)
	ds_write_b32 v52, v110
	s_waitcnt vmcnt(14)
	ds_write_b32 v54, v111
	s_waitcnt vmcnt(13)
	ds_write_b32 v56, v112
	s_waitcnt vmcnt(12)
	ds_write_b32 v58, v113
	s_waitcnt vmcnt(11)
	ds_write_b32 v60, v114
	s_waitcnt vmcnt(10)
	ds_write_b32 v62, v115
	s_waitcnt vmcnt(9)
	ds_write_b32 v64, v116
	s_waitcnt vmcnt(8)
	ds_write_b32 v78, v117
	s_waitcnt vmcnt(7)
	ds_write_b32 v80, v118
	s_waitcnt vmcnt(6)
	ds_write_b32 v82, v119
	s_waitcnt vmcnt(5)
	ds_write_b32 v84, v120
	s_waitcnt vmcnt(4)
	ds_write_b32 v86, v121
	s_waitcnt vmcnt(3)
	ds_write_b32 v88, v122
	s_waitcnt vmcnt(2)
	ds_write_b32 v90, v123
	s_waitcnt vmcnt(1)
	ds_write_b32 v92, v124
	s_waitcnt vmcnt(0)
	ds_write_b32 v94, v125
	s_waitcnt lgkmcnt(0)
	ds_read2_b32 v[54:55], v5 offset0:33 offset1:41
	ds_read2_b32 v[56:57], v5 offset1:8
	ds_read2_b32 v[58:59], v5 offset0:66 offset1:74
	ds_read2_b32 v[60:61], v5 offset0:99 offset1:107
	ds_read2_b32 v[62:63], v5 offset0:132 offset1:140
	ds_read2_b32 v[64:65], v5 offset0:165 offset1:173
	ds_read2_b32 v[78:79], v5 offset0:198 offset1:206
	ds_read2_b32 v[80:81], v5 offset0:231 offset1:239
	s_mov_b32 s5, s25
	v_or_b32_e32 v8, s2, v3
	v_lshl_add_u64 v[82:83], s[4:5], 1, v[18:19]
	v_mul_u32_u24_e32 v8, 0x1600, v8
	s_waitcnt lgkmcnt(6)
	v_cvt_pk_bf16_f32 v50, v56, v54
	s_waitcnt lgkmcnt(4)
	v_cvt_pk_bf16_f32 v51, v58, v60
	s_waitcnt lgkmcnt(2)
	v_cvt_pk_bf16_f32 v52, v62, v64
	s_waitcnt lgkmcnt(0)
	v_cvt_pk_bf16_f32 v53, v78, v80
	v_lshl_add_u64 v[84:85], v[82:83], 0, v[8:9]
	global_store_dwordx4 v[84:85], v[50:53], off
	v_or_b32_e32 v8, s2, v7
	v_mul_u32_u24_e32 v8, 0x1600, v8
	v_cvt_pk_bf16_f32 v50, v57, v55
	v_cvt_pk_bf16_f32 v51, v59, v61
	v_cvt_pk_bf16_f32 v52, v63, v65
	v_cvt_pk_bf16_f32 v53, v79, v81
	ds_read2_b32 v[56:57], v5 offset0:16 offset1:24
	ds_read2_b32 v[58:59], v5 offset0:49 offset1:57
	ds_read2_b32 v[60:61], v5 offset0:82 offset1:90
	ds_read2_b32 v[62:63], v5 offset0:115 offset1:123
	ds_read2_b32 v[64:65], v5 offset0:148 offset1:156
	ds_read2_b32 v[78:79], v5 offset0:181 offset1:189
	ds_read2_b32 v[80:81], v5 offset0:214 offset1:222
	ds_read2_b32 v[84:85], v5 offset0:247 offset1:255
	v_lshl_add_u64 v[54:55], v[82:83], 0, v[8:9]
	v_or_b32_e32 v8, s2, v68
	v_mul_u32_u24_e32 v8, 0x1600, v8
	global_store_dwordx4 v[54:55], v[50:53], off
	v_lshl_add_u64 v[54:55], v[82:83], 0, v[8:9]
	v_or_b32_e32 v8, s2, v69
	s_waitcnt lgkmcnt(6)
	v_cvt_pk_bf16_f32 v50, v56, v58
	s_waitcnt lgkmcnt(4)
	v_cvt_pk_bf16_f32 v51, v60, v62
	s_waitcnt lgkmcnt(2)
	v_cvt_pk_bf16_f32 v52, v64, v78
	s_waitcnt lgkmcnt(0)
	v_cvt_pk_bf16_f32 v53, v80, v84
	v_mul_u32_u24_e32 v8, 0x1600, v8
	global_store_dwordx4 v[54:55], v[50:53], off
	v_lshl_add_u64 v[54:55], v[82:83], 0, v[8:9]
	s_nop 0
	v_cvt_pk_bf16_f32 v50, v57, v59
	v_cvt_pk_bf16_f32 v51, v61, v63
	v_cvt_pk_bf16_f32 v52, v65, v79
	v_cvt_pk_bf16_f32 v53, v81, v85
	global_store_dwordx4 v[54:55], v[50:53], off
	s_waitcnt lgkmcnt(0)

; __device__ __forceinline__ void tr_item(const float* W, int ldw, int src_col, int nvalid, int k0, bf16_t* WT, int ldt, int dst_row, int dst_k, LAS float* scr, int lane) {
; #pragma unroll 8
;     for (int i = 0; i < 32; ++i) { const int kk = 2 * i + (lane >> 5), c = lane & 31; scr[kk * 33 + c] = (c < nvalid) ? W[(size_t)(k0 + kk) * ldw + src_col + c] : 0.f; }
.LBB0_50:
	s_lshl_b32 s14, s5, 1
	s_lshl_b32 s15, s6, 1
	v_or_b32_e32 v8, s14, v1
	v_or_b32_e32 v47, s15, v2
	s_add_i32 s16, s14, 4
	s_add_i32 s17, s15, 4
	s_add_i32 s18, s14, 8
	s_add_i32 s19, s15, 8
	s_add_i32 s23, s14, 12
	s_add_i32 s24, s15, 12
	s_add_i32 s26, s14, 16
	s_add_i32 s27, s15, 16
	s_add_i32 s28, s14, 20
	s_add_i32 s29, s15, 20
	s_add_i32 s30, s14, 24
	s_add_i32 s31, s15, 24
	s_add_i32 s14, s14, 28
	s_add_i32 s15, s15, 28
	v_add_u32_e32 v52, s3, v47
	v_or_b32_e32 v96, s16, v1
	v_or_b32_e32 v97, s17, v2
	v_or_b32_e32 v98, s18, v1
	v_or_b32_e32 v99, s19, v2
	v_or_b32_e32 v100, s23, v1
	v_or_b32_e32 v101, s24, v2
	v_or_b32_e32 v102, s26, v1
	v_or_b32_e32 v103, s27, v2
	v_or_b32_e32 v104, s28, v1
	v_or_b32_e32 v105, s29, v2
	v_or_b32_e32 v106, s30, v1
	v_or_b32_e32 v107, s31, v2
	v_or_b32_e32 v108, s14, v1
	v_or_b32_e32 v109, s15, v2
	v_add_u32_e32 v54, s4, v8
	v_mad_u64_u32 v[52:53], s[14:15], v52, s11, v[50:51]
	v_add_u32_e32 v58, s4, v96
	v_add_u32_e32 v56, s3, v97
	v_add_u32_e32 v62, s4, v98
	v_add_u32_e32 v60, s3, v99
	v_add_u32_e32 v78, s4, v100
	v_add_u32_e32 v64, s3, v101
	v_add_u32_e32 v82, s4, v102
	v_add_u32_e32 v80, s3, v103
	v_add_u32_e32 v86, s4, v104
	v_add_u32_e32 v84, s3, v105
	v_add_u32_e32 v90, s4, v106
	v_add_u32_e32 v88, s3, v107
	v_add_u32_e32 v94, s4, v108
	v_add_u32_e32 v92, s3, v109
	v_mad_u64_u32 v[54:55], s[14:15], v54, s11, v[50:51]
	v_mad_u64_u32 v[56:57], s[14:15], v56, s11, v[50:51]
	v_mad_u64_u32 v[58:59], s[14:15], v58, s11, v[50:51]
	v_mad_u64_u32 v[60:61], s[14:15], v60, s11, v[50:51]
	v_mad_u64_u32 v[62:63], s[14:15], v62, s11, v[50:51]
	v_mad_u64_u32 v[64:65], s[14:15], v64, s11, v[50:51]
	v_mad_u64_u32 v[78:79], s[14:15], v78, s11, v[50:51]
	v_mad_u64_u32 v[80:81], s[14:15], v80, s11, v[50:51]
	v_mad_u64_u32 v[82:83], s[14:15], v82, s11, v[50:51]
	v_mad_u64_u32 v[84:85], s[14:15], v84, s11, v[50:51]
	v_mad_u64_u32 v[86:87], s[14:15], v86, s11, v[50:51]
	v_mad_u64_u32 v[88:89], s[14:15], v88, s11, v[50:51]
	v_mad_u64_u32 v[90:91], s[14:15], v90, s11, v[50:51]
	v_mad_u64_u32 v[92:93], s[14:15], v92, s11, v[50:51]
	v_mad_u64_u32 v[94:95], s[14:15], v94, s11, v[50:51]
	global_load_dword v132, v[52:53], off
	global_load_dword v133, v[54:55], off
	global_load_dword v134, v[56:57], off
	global_load_dword v135, v[58:59], off
	global_load_dword v136, v[60:61], off
	global_load_dword v137, v[62:63], off
	global_load_dword v138, v[64:65], off
	global_load_dword v139, v[78:79], off
	global_load_dword v140, v[80:81], off
	global_load_dword v141, v[82:83], off
	global_load_dword v142, v[84:85], off
	global_load_dword v143, v[86:87], off
	global_load_dword v144, v[88:89], off
	global_load_dword v145, v[90:91], off
	global_load_dword v146, v[92:93], off
	global_load_dword v147, v[94:95], off
	s_add_i32 s6, s6, 16
	s_add_i32 s5, s5, 16
	s_add_i32 s7, s7, -16
	v_mad_u64_u32 v[52:53], s[14:15], v47, s8, v[6:7]
	s_cmp_lg_u32 s7, 0
	v_mad_u64_u32 v[54:55], s[14:15], v8, s8, v[6:7]
	v_mad_u64_u32 v[56:57], s[14:15], v97, s8, v[6:7]
	v_mad_u64_u32 v[58:59], s[14:15], v96, s8, v[6:7]
	v_mad_u64_u32 v[60:61], s[14:15], v99, s8, v[6:7]
	v_mad_u64_u32 v[62:63], s[14:15], v98, s8, v[6:7]
	v_mad_u64_u32 v[64:65], s[14:15], v101, s8, v[6:7]
	v_mad_u64_u32 v[78:79], s[14:15], v100, s8, v[6:7]
	v_mad_u64_u32 v[80:81], s[14:15], v103, s8, v[6:7]
	v_mad_u64_u32 v[82:83], s[14:15], v102, s8, v[6:7]
	v_mad_u64_u32 v[84:85], s[14:15], v105, s8, v[6:7]
	v_mad_u64_u32 v[86:87], s[14:15], v104, s8, v[6:7]
	v_mad_u64_u32 v[88:89], s[14:15], v107, s8, v[6:7]
	v_mad_u64_u32 v[90:91], s[14:15], v106, s8, v[6:7]
	v_mad_u64_u32 v[92:93], s[14:15], v109, s8, v[6:7]
	v_mad_u64_u32 v[94:95], s[14:15], v108, s8, v[6:7]
	v_mov_b32_e32 v148, v52
	v_mov_b32_e32 v149, v54
	v_mov_b32_e32 v150, v56
	v_mov_b32_e32 v151, v58
	v_mov_b32_e32 v152, v60
	v_mov_b32_e32 v153, v62
	v_mov_b32_e32 v154, v64
	v_mov_b32_e32 v155, v78
	v_mov_b32_e32 v156, v80
	v_mov_b32_e32 v157, v82
	v_mov_b32_e32 v158, v84
	v_mov_b32_e32 v159, v86
	v_mov_b32_e32 v160, v88
	v_mov_b32_e32 v161, v90
	v_mov_b32_e32 v162, v92
	v_mov_b32_e32 v163, v94
	s_lshl_b32 s14, s5, 1
	s_lshl_b32 s15, s6, 1
	v_or_b32_e32 v8, s14, v1
	v_or_b32_e32 v47, s15, v2
	s_add_i32 s16, s14, 4
	s_add_i32 s17, s15, 4
	s_add_i32 s18, s14, 8
	s_add_i32 s19, s15, 8
	s_add_i32 s23, s14, 12
	s_add_i32 s24, s15, 12
	s_add_i32 s26, s14, 16
	s_add_i32 s27, s15, 16
	s_add_i32 s28, s14, 20
	s_add_i32 s29, s15, 20
	s_add_i32 s30, s14, 24
	s_add_i32 s31, s15, 24
	s_add_i32 s14, s14, 28
	s_add_i32 s15, s15, 28
	v_add_u32_e32 v52, s3, v47
	v_or_b32_e32 v96, s16, v1
	v_or_b32_e32 v97, s17, v2
	v_or_b32_e32 v98, s18, v1
	v_or_b32_e32 v99, s19, v2
	v_or_b32_e32 v100, s23, v1
	v_or_b32_e32 v101, s24, v2
	v_or_b32_e32 v102, s26, v1
	v_or_b32_e32 v103, s27, v2
	v_or_b32_e32 v104, s28, v1
	v_or_b32_e32 v105, s29, v2
	v_or_b32_e32 v106, s30, v1
	v_or_b32_e32 v107, s31, v2
	v_or_b32_e32 v108, s14, v1
	v_or_b32_e32 v109, s15, v2
	v_add_u32_e32 v54, s4, v8
	v_mad_u64_u32 v[52:53], s[14:15], v52, s11, v[50:51]
	v_add_u32_e32 v58, s4, v96
	v_add_u32_e32 v56, s3, v97
	v_add_u32_e32 v62, s4, v98
	v_add_u32_e32 v60, s3, v99
	v_add_u32_e32 v78, s4, v100
	v_add_u32_e32 v64, s3, v101
	v_add_u32_e32 v82, s4, v102
	v_add_u32_e32 v80, s3, v103
	v_add_u32_e32 v86, s4, v104
	v_add_u32_e32 v84, s3, v105
	v_add_u32_e32 v90, s4, v106
	v_add_u32_e32 v88, s3, v107
	v_add_u32_e32 v94, s4, v108
	v_add_u32_e32 v92, s3, v109
	v_mad_u64_u32 v[54:55], s[14:15], v54, s11, v[50:51]
	v_mad_u64_u32 v[56:57], s[14:15], v56, s11, v[50:51]
	v_mad_u64_u32 v[58:59], s[14:15], v58, s11, v[50:51]
	v_mad_u64_u32 v[60:61], s[14:15], v60, s11, v[50:51]
; #define LAS __attribute__((address_space(3)))
; __device__ __forceinline__ unsigned cvt_pk_bf16(float lo, float hi) { f32x2_t v = {lo, hi}; bf16x2_t b = __builtin_convertvector(v, bf16x2_t); return __builtin_bit_cast(unsigned, b); }
; #define LDS_WAIT() asm volatile("s_waitcnt lgkmcnt(0)" ::: "memory")
; __device__ __forceinline__ void tr_item(const float* W, int ldw, int src_col, int nvalid, int k0, bf16_t* WT, int ldt, int dst_row, int dst_k, LAS float* scr, int lane) {
; #pragma unroll 8
;     for (int i = 0; i < 32; ++i) { const int kk = 2 * i + (lane >> 5), c = lane & 31; scr[kk * 33 + c] = (c < nvalid) ? W[(size_t)(k0 + kk) * ldw + src_col + c] : 0.f; }
;     LDS_WAIT();
;     const int c = lane & 7;
; #pragma unroll
;     for (int j = 0; j < 4; ++j) { const int n = (lane >> 3) + 8 * j; const LAS float* s = scr + (8 * c) * 33 + n;
;         u32x4 o; o.x = cvt_pk_bf16(s[0 * 33], s[1 * 33]); o.y = cvt_pk_bf16(s[2 * 33], s[3 * 33]); o.z = cvt_pk_bf16(s[4 * 33], s[5 * 33]); o.w = cvt_pk_bf16(s[6 * 33], s[7 * 33]);
;         *(u32x4*)(WT + (size_t)(dst_row + n) * ldt + dst_k + k0 + 8 * c) = o; }
;     LDS_WAIT();
	v_mad_u64_u32 v[62:63], s[14:15], v62, s11, v[50:51]
	v_mad_u64_u32 v[64:65], s[14:15], v64, s11, v[50:51]
	v_mad_u64_u32 v[78:79], s[14:15], v78, s11, v[50:51]
	v_mad_u64_u32 v[80:81], s[14:15], v80, s11, v[50:51]
	v_mad_u64_u32 v[82:83], s[14:15], v82, s11, v[50:51]
	v_mad_u64_u32 v[84:85], s[14:15], v84, s11, v[50:51]
	v_mad_u64_u32 v[86:87], s[14:15], v86, s11, v[50:51]
	v_mad_u64_u32 v[88:89], s[14:15], v88, s11, v[50:51]
	v_mad_u64_u32 v[90:91], s[14:15], v90, s11, v[50:51]
	v_mad_u64_u32 v[92:93], s[14:15], v92, s11, v[50:51]
	v_mad_u64_u32 v[94:95], s[14:15], v94, s11, v[50:51]
	global_load_dword v110, v[52:53], off
	global_load_dword v111, v[54:55], off
	global_load_dword v112, v[56:57], off
	global_load_dword v113, v[58:59], off
	global_load_dword v114, v[60:61], off
	global_load_dword v115, v[62:63], off
	global_load_dword v116, v[64:65], off
	global_load_dword v117, v[78:79], off
	global_load_dword v118, v[80:81], off
	global_load_dword v119, v[82:83], off
	global_load_dword v120, v[84:85], off
	global_load_dword v121, v[86:87], off
	global_load_dword v122, v[88:89], off
	global_load_dword v123, v[90:91], off
	global_load_dword v124, v[92:93], off
	global_load_dword v125, v[94:95], off
	s_add_i32 s6, s6, 16
	s_add_i32 s5, s5, 16
	s_add_i32 s7, s7, -16
	v_mad_u64_u32 v[52:53], s[14:15], v47, s8, v[6:7]
	s_cmp_lg_u32 s7, 0
	v_mad_u64_u32 v[54:55], s[14:15], v8, s8, v[6:7]
	v_mad_u64_u32 v[56:57], s[14:15], v97, s8, v[6:7]
	v_mad_u64_u32 v[58:59], s[14:15], v96, s8, v[6:7]
	v_mad_u64_u32 v[60:61], s[14:15], v99, s8, v[6:7]
	v_mad_u64_u32 v[62:63], s[14:15], v98, s8, v[6:7]
	v_mad_u64_u32 v[64:65], s[14:15], v101, s8, v[6:7]
	v_mad_u64_u32 v[78:79], s[14:15], v100, s8, v[6:7]
	v_mad_u64_u32 v[80:81], s[14:15], v103, s8, v[6:7]
	v_mad_u64_u32 v[82:83], s[14:15], v102, s8, v[6:7]
	v_mad_u64_u32 v[84:85], s[14:15], v105, s8, v[6:7]
	v_mad_u64_u32 v[86:87], s[14:15], v104, s8, v[6:7]
	v_mad_u64_u32 v[88:89], s[14:15], v107, s8, v[6:7]
	v_mad_u64_u32 v[90:91], s[14:15], v106, s8, v[6:7]
	v_mad_u64_u32 v[92:93], s[14:15], v109, s8, v[6:7]
	v_mad_u64_u32 v[94:95], s[14:15], v108, s8, v[6:7]
	s_waitcnt vmcnt(31)
	ds_write_b32 v148, v132
	s_waitcnt vmcnt(30)
	ds_write_b32 v149, v133
	s_waitcnt vmcnt(29)
	ds_write_b32 v150, v134
	s_waitcnt vmcnt(28)
	ds_write_b32 v151, v135
	s_waitcnt vmcnt(27)
	ds_write_b32 v152, v136
	s_waitcnt vmcnt(26)
	ds_write_b32 v153, v137
	s_waitcnt vmcnt(25)
	ds_write_b32 v154, v138
	s_waitcnt vmcnt(24)
	ds_write_b32 v155, v139
	s_waitcnt vmcnt(23)
	ds_write_b32 v156, v140
	s_waitcnt vmcnt(22)
	ds_write_b32 v157, v141
	s_waitcnt vmcnt(21)
	ds_write_b32 v158, v142
	s_waitcnt vmcnt(20)
	ds_write_b32 v159, v143
	s_waitcnt vmcnt(19)
	ds_write_b32 v160, v144
	s_waitcnt vmcnt(18)
	ds_write_b32 v161, v145
	s_waitcnt vmcnt(17)
	ds_write_b32 v162, v146
	s_waitcnt vmcnt(16)
	ds_write_b32 v163, v147
	s_waitcnt vmcnt(15)
	ds_write_b32 v52, v110
	s_waitcnt vmcnt(14)
	ds_write_b32 v54, v111
	s_waitcnt vmcnt(13)
	ds_write_b32 v56, v112
	s_waitcnt vmcnt(12)
	ds_write_b32 v58, v113
	s_waitcnt vmcnt(11)
	ds_write_b32 v60, v114
	s_waitcnt vmcnt(10)
	ds_write_b32 v62, v115
	s_waitcnt vmcnt(9)
	ds_write_b32 v64, v116
	s_waitcnt vmcnt(8)
	ds_write_b32 v78, v117
	s_waitcnt vmcnt(7)
	ds_write_b32 v80, v118
	s_waitcnt vmcnt(6)
	ds_write_b32 v82, v119
	s_waitcnt vmcnt(5)
	ds_write_b32 v84, v120
	s_waitcnt vmcnt(4)
	ds_write_b32 v86, v121
	s_waitcnt vmcnt(3)
	ds_write_b32 v88, v122
	s_waitcnt vmcnt(2)
	ds_write_b32 v90, v123
	s_waitcnt vmcnt(1)
	ds_write_b32 v92, v124
	s_waitcnt vmcnt(0)
	ds_write_b32 v94, v125
	s_waitcnt lgkmcnt(0)
	ds_read2_b32 v[54:55], v5 offset0:33 offset1:41
	ds_read2_b32 v[56:57], v5 offset1:8
	ds_read2_b32 v[58:59], v5 offset0:66 offset1:74
	ds_read2_b32 v[60:61], v5 offset0:99 offset1:107
	ds_read2_b32 v[62:63], v5 offset0:132 offset1:140
	ds_read2_b32 v[64:65], v5 offset0:165 offset1:173
	ds_read2_b32 v[78:79], v5 offset0:198 offset1:206
	ds_read2_b32 v[80:81], v5 offset0:231 offset1:239
	s_and_b32 s3, 0xffff, s3
	s_lshl_b32 s24, s3, 1
	v_or_b32_e32 v8, s2, v3
	v_lshl_add_u64 v[82:83], v[20:21], 0, s[24:25]
	v_lshlrev_b32_e32 v8, 11, v8
	s_waitcnt lgkmcnt(6)
	v_cvt_pk_bf16_f32 v50, v56, v54
	s_waitcnt lgkmcnt(4)
	v_cvt_pk_bf16_f32 v51, v58, v60
	s_waitcnt lgkmcnt(2)
	v_cvt_pk_bf16_f32 v52, v62, v64
	s_waitcnt lgkmcnt(0)
	v_cvt_pk_bf16_f32 v53, v78, v80
	v_lshl_add_u64 v[84:85], v[82:83], 0, v[8:9]
	global_store_dwordx4 v[84:85], v[50:53], off
	v_or_b32_e32 v8, s2, v7
	v_lshlrev_b32_e32 v8, 11, v8
	v_cvt_pk_bf16_f32 v50, v57, v55
	v_cvt_pk_bf16_f32 v51, v59, v61
	v_cvt_pk_bf16_f32 v52, v63, v65
	v_cvt_pk_bf16_f32 v53, v79, v81
	ds_read2_b32 v[56:57], v5 offset0:49 offset1:57
	ds_read2_b32 v[58:59], v5 offset0:16 offset1:24
	ds_read2_b32 v[60:61], v5 offset0:82 offset1:90
	ds_read2_b32 v[62:63], v5 offset0:115 offset1:123
	ds_read2_b32 v[64:65], v5 offset0:148 offset1:156
	ds_read2_b32 v[78:79], v5 offset0:181 offset1:189
	ds_read2_b32 v[80:81], v5 offset0:214 offset1:222
	ds_read2_b32 v[84:85], v5 offset0:247 offset1:255
	v_lshl_add_u64 v[54:55], v[82:83], 0, v[8:9]
	v_or_b32_e32 v8, s2, v68
	v_lshlrev_b32_e32 v8, 11, v8
	global_store_dwordx4 v[54:55], v[50:53], off
	v_lshl_add_u64 v[54:55], v[82:83], 0, v[8:9]
	v_or_b32_e32 v8, s2, v69
	s_waitcnt lgkmcnt(6)
	v_cvt_pk_bf16_f32 v50, v58, v56
	s_waitcnt lgkmcnt(4)
	v_cvt_pk_bf16_f32 v51, v60, v62
	s_waitcnt lgkmcnt(2)
	v_cvt_pk_bf16_f32 v52, v64, v78
	s_waitcnt lgkmcnt(0)
	v_cvt_pk_bf16_f32 v53, v80, v84
	v_lshlrev_b32_e32 v8, 11, v8
	global_store_dwordx4 v[54:55], v[50:53], off
	v_lshl_add_u64 v[54:55], v[82:83], 0, v[8:9]
	s_nop 0
	v_cvt_pk_bf16_f32 v50, v59, v57
	v_cvt_pk_bf16_f32 v51, v61, v63
	v_cvt_pk_bf16_f32 v52, v65, v79
	v_cvt_pk_bf16_f32 v53, v81, v85
	global_store_dwordx4 v[54:55], v[50:53], off
	s_waitcnt lgkmcnt(0)

; __device__ __forceinline__ void tr_item(const float* W, int ldw, int src_col, int nvalid, int k0, bf16_t* WT, int ldt, int dst_row, int dst_k, LAS float* scr, int lane) {
; #pragma unroll 8
;     for (int i = 0; i < 32; ++i) { const int kk = 2 * i + (lane >> 5), c = lane & 31; scr[kk * 33 + c] = (c < nvalid) ? W[(size_t)(k0 + kk) * ldw + src_col + c] : 0.f; }
.LBB0_55:
	s_lshl_b32 s14, s3, 1
	s_lshl_b32 s15, s6, 1
	v_or_b32_e32 v8, s14, v1
	v_or_b32_e32 v47, s15, v2
	s_add_i32 s16, s14, 4
	s_add_i32 s17, s15, 4
	s_add_i32 s18, s14, 8
	s_add_i32 s19, s15, 8
	s_add_i32 s23, s14, 12
	s_add_i32 s24, s15, 12
	s_add_i32 s26, s14, 16
	s_add_i32 s27, s15, 16
	s_add_i32 s28, s14, 20
	s_add_i32 s29, s15, 20
	s_add_i32 s30, s14, 24
	s_add_i32 s31, s15, 24
	s_add_i32 s14, s14, 28
	s_add_i32 s15, s15, 28
	v_add_u32_e32 v54, s4, v47
	v_or_b32_e32 v96, s16, v1
	v_or_b32_e32 v97, s17, v2
	v_or_b32_e32 v98, s18, v1
	v_or_b32_e32 v99, s19, v2
	v_or_b32_e32 v100, s23, v1
	v_or_b32_e32 v101, s24, v2
	v_or_b32_e32 v102, s26, v1
	v_or_b32_e32 v103, s27, v2
	v_or_b32_e32 v104, s28, v1
	v_or_b32_e32 v105, s29, v2
	v_or_b32_e32 v106, s30, v1
	v_or_b32_e32 v107, s31, v2
	v_or_b32_e32 v108, s14, v1
	v_or_b32_e32 v109, s15, v2
	v_add_u32_e32 v52, s5, v8
	v_ashrrev_i32_e32 v55, 31, v54
	v_add_u32_e32 v56, s5, v96
	v_add_u32_e32 v58, s4, v97
	v_add_u32_e32 v60, s5, v98
	v_add_u32_e32 v62, s4, v99
	v_add_u32_e32 v64, s5, v100
	v_add_u32_e32 v78, s4, v101
	v_add_u32_e32 v80, s5, v102
	v_add_u32_e32 v82, s4, v103
	v_add_u32_e32 v84, s5, v104
	v_add_u32_e32 v86, s4, v105
	v_add_u32_e32 v88, s5, v106
	v_add_u32_e32 v90, s4, v107
	v_add_u32_e32 v92, s5, v108
	v_add_u32_e32 v94, s4, v109
	v_ashrrev_i32_e32 v53, 31, v52
	v_lshlrev_b64 v[54:55], 12, v[54:55]
	v_ashrrev_i32_e32 v59, 31, v58
	v_ashrrev_i32_e32 v57, 31, v56
	v_ashrrev_i32_e32 v63, 31, v62
	v_ashrrev_i32_e32 v61, 31, v60
	v_ashrrev_i32_e32 v79, 31, v78
	v_ashrrev_i32_e32 v65, 31, v64
	v_ashrrev_i32_e32 v83, 31, v82
	v_ashrrev_i32_e32 v81, 31, v80
	v_ashrrev_i32_e32 v87, 31, v86
	v_ashrrev_i32_e32 v85, 31, v84
	v_ashrrev_i32_e32 v91, 31, v90
	v_ashrrev_i32_e32 v89, 31, v88
	v_ashrrev_i32_e32 v95, 31, v94
	v_ashrrev_i32_e32 v93, 31, v92
	v_lshlrev_b64 v[52:53], 12, v[52:53]
	v_lshl_add_u64 v[54:55], v[50:51], 0, v[54:55]
	v_lshlrev_b64 v[56:57], 12, v[56:57]
	v_lshlrev_b64 v[58:59], 12, v[58:59]
	v_lshlrev_b64 v[60:61], 12, v[60:61]
	v_lshlrev_b64 v[62:63], 12, v[62:63]
	v_lshlrev_b64 v[64:65], 12, v[64:65]
	v_lshlrev_b64 v[78:79], 12, v[78:79]
	v_lshlrev_b64 v[80:81], 12, v[80:81]
	v_lshlrev_b64 v[82:83], 12, v[82:83]
	v_lshlrev_b64 v[84:85], 12, v[84:85]
	v_lshlrev_b64 v[86:87], 12, v[86:87]
	v_lshlrev_b64 v[88:89], 12, v[88:89]
	v_lshlrev_b64 v[90:91], 12, v[90:91]
	v_lshlrev_b64 v[92:93], 12, v[92:93]
	v_lshlrev_b64 v[94:95], 12, v[94:95]
	v_lshl_add_u64 v[52:53], v[50:51], 0, v[52:53]
	v_lshl_add_u64 v[58:59], v[50:51], 0, v[58:59]
	v_lshl_add_u64 v[56:57], v[50:51], 0, v[56:57]
	v_lshl_add_u64 v[62:63], v[50:51], 0, v[62:63]
	v_lshl_add_u64 v[60:61], v[50:51], 0, v[60:61]
	v_lshl_add_u64 v[78:79], v[50:51], 0, v[78:79]
	v_lshl_add_u64 v[64:65], v[50:51], 0, v[64:65]
	v_lshl_add_u64 v[82:83], v[50:51], 0, v[82:83]
	v_lshl_add_u64 v[80:81], v[50:51], 0, v[80:81]
	v_lshl_add_u64 v[86:87], v[50:51], 0, v[86:87]
	v_lshl_add_u64 v[84:85], v[50:51], 0, v[84:85]
	v_lshl_add_u64 v[90:91], v[50:51], 0, v[90:91]
	v_lshl_add_u64 v[88:89], v[50:51], 0, v[88:89]
	v_lshl_add_u64 v[94:95], v[50:51], 0, v[94:95]
	v_lshl_add_u64 v[92:93], v[50:51], 0, v[92:93]
	global_load_dword v132, v[54:55], off
	global_load_dword v133, v[52:53], off
	global_load_dword v134, v[58:59], off
	global_load_dword v135, v[56:57], off
	global_load_dword v136, v[62:63], off
	global_load_dword v137, v[60:61], off
	global_load_dword v138, v[78:79], off
	global_load_dword v139, v[64:65], off
	global_load_dword v140, v[82:83], off
	global_load_dword v141, v[80:81], off
	global_load_dword v142, v[86:87], off
	global_load_dword v143, v[84:85], off
	global_load_dword v144, v[90:91], off
	global_load_dword v145, v[88:89], off
	global_load_dword v146, v[94:95], off
	global_load_dword v147, v[92:93], off
	s_add_i32 s6, s6, 16
	s_add_i32 s3, s3, 16
	s_add_i32 s7, s7, -16
	v_mad_u64_u32 v[52:53], s[14:15], v47, s8, v[6:7]
	s_cmp_lg_u32 s7, 0
	v_mad_u64_u32 v[54:55], s[14:15], v8, s8, v[6:7]
	v_mad_u64_u32 v[56:57], s[14:15], v97, s8, v[6:7]
	v_mad_u64_u32 v[58:59], s[14:15], v96, s8, v[6:7]
	v_mad_u64_u32 v[60:61], s[14:15], v99, s8, v[6:7]
	v_mad_u64_u32 v[62:63], s[14:15], v98, s8, v[6:7]
	v_mad_u64_u32 v[64:65], s[14:15], v101, s8, v[6:7]
	v_mad_u64_u32 v[78:79], s[14:15], v100, s8, v[6:7]
	v_mad_u64_u32 v[80:81], s[14:15], v103, s8, v[6:7]
	v_mad_u64_u32 v[82:83], s[14:15], v102, s8, v[6:7]
	v_mad_u64_u32 v[84:85], s[14:15], v105, s8, v[6:7]
	v_mad_u64_u32 v[86:87], s[14:15], v104, s8, v[6:7]
	v_mad_u64_u32 v[88:89], s[14:15], v107, s8, v[6:7]
	v_mad_u64_u32 v[90:91], s[14:15], v106, s8, v[6:7]
	v_mad_u64_u32 v[92:93], s[14:15], v109, s8, v[6:7]
	v_mad_u64_u32 v[94:95], s[14:15], v108, s8, v[6:7]
	v_mov_b32_e32 v148, v52
	v_mov_b32_e32 v149, v54
	v_mov_b32_e32 v150, v56
	v_mov_b32_e32 v151, v58
	v_mov_b32_e32 v152, v60
	v_mov_b32_e32 v153, v62
	v_mov_b32_e32 v154, v64
	v_mov_b32_e32 v155, v78
	v_mov_b32_e32 v156, v80
	v_mov_b32_e32 v157, v82
	v_mov_b32_e32 v158, v84
	v_mov_b32_e32 v159, v86
	v_mov_b32_e32 v160, v88
	v_mov_b32_e32 v161, v90
	v_mov_b32_e32 v162, v92
	v_mov_b32_e32 v163, v94
	s_lshl_b32 s14, s3, 1
	s_lshl_b32 s15, s6, 1
	v_or_b32_e32 v8, s14, v1
	v_or_b32_e32 v47, s15, v2
	s_add_i32 s16, s14, 4
	s_add_i32 s17, s15, 4
	s_add_i32 s18, s14, 8
	s_add_i32 s19, s15, 8
	s_add_i32 s23, s14, 12
	s_add_i32 s24, s15, 12
	s_add_i32 s26, s14, 16
	s_add_i32 s27, s15, 16
	s_add_i32 s28, s14, 20
	s_add_i32 s29, s15, 20
	s_add_i32 s30, s14, 24
	s_add_i32 s31, s15, 24
	s_add_i32 s14, s14, 28
	s_add_i32 s15, s15, 28
	v_add_u32_e32 v54, s4, v47
	v_or_b32_e32 v96, s16, v1
	v_or_b32_e32 v97, s17, v2
	v_or_b32_e32 v98, s18, v1
; __device__ __forceinline__ void tr_item(const float* W, int ldw, int src_col, int nvalid, int k0, bf16_t* WT, int ldt, int dst_row, int dst_k, LAS float* scr, int lane) {
; #pragma unroll 8
;     for (int i = 0; i < 32; ++i) { const int kk = 2 * i + (lane >> 5), c = lane & 31; scr[kk * 33 + c] = (c < nvalid) ? W[(size_t)(k0 + kk) * ldw + src_col + c] : 0.f; }
	v_or_b32_e32 v99, s19, v2
	v_or_b32_e32 v100, s23, v1
	v_or_b32_e32 v101, s24, v2
	v_or_b32_e32 v102, s26, v1
	v_or_b32_e32 v103, s27, v2
	v_or_b32_e32 v104, s28, v1
	v_or_b32_e32 v105, s29, v2
	v_or_b32_e32 v106, s30, v1
	v_or_b32_e32 v107, s31, v2
	v_or_b32_e32 v108, s14, v1
	v_or_b32_e32 v109, s15, v2
	v_add_u32_e32 v52, s5, v8
	v_ashrrev_i32_e32 v55, 31, v54
	v_add_u32_e32 v56, s5, v96
	v_add_u32_e32 v58, s4, v97
	v_add_u32_e32 v60, s5, v98
	v_add_u32_e32 v62, s4, v99
	v_add_u32_e32 v64, s5, v100
	v_add_u32_e32 v78, s4, v101
	v_add_u32_e32 v80, s5, v102
	v_add_u32_e32 v82, s4, v103
	v_add_u32_e32 v84, s5, v104
	v_add_u32_e32 v86, s4, v105
	v_add_u32_e32 v88, s5, v106
	v_add_u32_e32 v90, s4, v107
	v_add_u32_e32 v92, s5, v108
	v_add_u32_e32 v94, s4, v109
	v_ashrrev_i32_e32 v53, 31, v52
	v_lshlrev_b64 v[54:55], 12, v[54:55]
	v_ashrrev_i32_e32 v59, 31, v58
	v_ashrrev_i32_e32 v57, 31, v56
	v_ashrrev_i32_e32 v63, 31, v62
	v_ashrrev_i32_e32 v61, 31, v60
	v_ashrrev_i32_e32 v79, 31, v78
	v_ashrrev_i32_e32 v65, 31, v64
	v_ashrrev_i32_e32 v83, 31, v82
	v_ashrrev_i32_e32 v81, 31, v80
	v_ashrrev_i32_e32 v87, 31, v86
	v_ashrrev_i32_e32 v85, 31, v84
	v_ashrrev_i32_e32 v91, 31, v90
	v_ashrrev_i32_e32 v89, 31, v88
	v_ashrrev_i32_e32 v95, 31, v94
	v_ashrrev_i32_e32 v93, 31, v92
	v_lshlrev_b64 v[52:53], 12, v[52:53]
	v_lshl_add_u64 v[54:55], v[50:51], 0, v[54:55]
	v_lshlrev_b64 v[56:57], 12, v[56:57]
	v_lshlrev_b64 v[58:59], 12, v[58:59]
	v_lshlrev_b64 v[60:61], 12, v[60:61]
	v_lshlrev_b64 v[62:63], 12, v[62:63]
	v_lshlrev_b64 v[64:65], 12, v[64:65]
	v_lshlrev_b64 v[78:79], 12, v[78:79]
	v_lshlrev_b64 v[80:81], 12, v[80:81]
	v_lshlrev_b64 v[82:83], 12, v[82:83]
	v_lshlrev_b64 v[84:85], 12, v[84:85]
	v_lshlrev_b64 v[86:87], 12, v[86:87]
	v_lshlrev_b64 v[88:89], 12, v[88:89]
	v_lshlrev_b64 v[90:91], 12, v[90:91]
	v_lshlrev_b64 v[92:93], 12, v[92:93]
	v_lshlrev_b64 v[94:95], 12, v[94:95]
	v_lshl_add_u64 v[52:53], v[50:51], 0, v[52:53]
	v_lshl_add_u64 v[58:59], v[50:51], 0, v[58:59]
	v_lshl_add_u64 v[56:57], v[50:51], 0, v[56:57]
	v_lshl_add_u64 v[62:63], v[50:51], 0, v[62:63]
	v_lshl_add_u64 v[60:61], v[50:51], 0, v[60:61]
	v_lshl_add_u64 v[78:79], v[50:51], 0, v[78:79]
	v_lshl_add_u64 v[64:65], v[50:51], 0, v[64:65]
	v_lshl_add_u64 v[82:83], v[50:51], 0, v[82:83]
	v_lshl_add_u64 v[80:81], v[50:51], 0, v[80:81]
	v_lshl_add_u64 v[86:87], v[50:51], 0, v[86:87]
	v_lshl_add_u64 v[84:85], v[50:51], 0, v[84:85]
	v_lshl_add_u64 v[90:91], v[50:51], 0, v[90:91]
	v_lshl_add_u64 v[88:89], v[50:51], 0, v[88:89]
	v_lshl_add_u64 v[94:95], v[50:51], 0, v[94:95]
	v_lshl_add_u64 v[92:93], v[50:51], 0, v[92:93]
	global_load_dword v110, v[54:55], off
	global_load_dword v111, v[52:53], off
	global_load_dword v112, v[58:59], off
	global_load_dword v113, v[56:57], off
	global_load_dword v114, v[62:63], off
	global_load_dword v115, v[60:61], off
	global_load_dword v116, v[78:79], off
	global_load_dword v117, v[64:65], off
	global_load_dword v118, v[82:83], off
	global_load_dword v119, v[80:81], off
	global_load_dword v120, v[86:87], off
	global_load_dword v121, v[84:85], off
	global_load_dword v122, v[90:91], off
	global_load_dword v123, v[88:89], off
	global_load_dword v124, v[94:95], off
	global_load_dword v125, v[92:93], off
	s_add_i32 s6, s6, 16
	s_add_i32 s3, s3, 16
	s_add_i32 s7, s7, -16
	v_mad_u64_u32 v[52:53], s[14:15], v47, s8, v[6:7]
	s_cmp_lg_u32 s7, 0
	v_mad_u64_u32 v[54:55], s[14:15], v8, s8, v[6:7]
	v_mad_u64_u32 v[56:57], s[14:15], v97, s8, v[6:7]
	v_mad_u64_u32 v[58:59], s[14:15], v96, s8, v[6:7]
	v_mad_u64_u32 v[60:61], s[14:15], v99, s8, v[6:7]
	v_mad_u64_u32 v[62:63], s[14:15], v98, s8, v[6:7]
	v_mad_u64_u32 v[64:65], s[14:15], v101, s8, v[6:7]
	v_mad_u64_u32 v[78:79], s[14:15], v100, s8, v[6:7]
	v_mad_u64_u32 v[80:81], s[14:15], v103, s8, v[6:7]
	v_mad_u64_u32 v[82:83], s[14:15], v102, s8, v[6:7]
	v_mad_u64_u32 v[84:85], s[14:15], v105, s8, v[6:7]
	v_mad_u64_u32 v[86:87], s[14:15], v104, s8, v[6:7]
	v_mad_u64_u32 v[88:89], s[14:15], v107, s8, v[6:7]
	v_mad_u64_u32 v[90:91], s[14:15], v106, s8, v[6:7]
	v_mad_u64_u32 v[92:93], s[14:15], v109, s8, v[6:7]
	v_mad_u64_u32 v[94:95], s[14:15], v108, s8, v[6:7]
	s_waitcnt vmcnt(31)
; #define LAS __attribute__((address_space(3)))
; __device__ __forceinline__ unsigned cvt_pk_bf16(float lo, float hi) { f32x2_t v = {lo, hi}; bf16x2_t b = __builtin_convertvector(v, bf16x2_t); return __builtin_bit_cast(unsigned, b); }
; #define LDS_WAIT() asm volatile("s_waitcnt lgkmcnt(0)" ::: "memory")
; __device__ __forceinline__ void tr_item(const float* W, int ldw, int src_col, int nvalid, int k0, bf16_t* WT, int ldt, int dst_row, int dst_k, LAS float* scr, int lane) {
;     ...
;     for (int i = 0; i < 32; ++i) { const int kk = 2 * i + (lane >> 5), c = lane & 31; scr[kk * 33 + c] = (c < nvalid) ? W[(size_t)(k0 + kk) * ldw + src_col + c] : 0.f; }
;     LDS_WAIT();
;     const int c = lane & 7;
; #pragma unroll
;     for (int j = 0; j < 4; ++j) { const int n = (lane >> 3) + 8 * j; const LAS float* s = scr + (8 * c) * 33 + n;
;         u32x4 o; o.x = cvt_pk_bf16(s[0 * 33], s[1 * 33]); o.y = cvt_pk_bf16(s[2 * 33], s[3 * 33]); o.z = cvt_pk_bf16(s[4 * 33], s[5 * 33]); o.w = cvt_pk_bf16(s[6 * 33], s[7 * 33]);
;         *(u32x4*)(WT + (size_t)(dst_row + n) * ldt + dst_k + k0 + 8 * c) = o; }
;     LDS_WAIT();
	ds_write_b32 v148, v132
	s_waitcnt vmcnt(30)
	ds_write_b32 v149, v133
	s_waitcnt vmcnt(29)
	ds_write_b32 v150, v134
	s_waitcnt vmcnt(28)
	ds_write_b32 v151, v135
	s_waitcnt vmcnt(27)
	ds_write_b32 v152, v136
	s_waitcnt vmcnt(26)
	ds_write_b32 v153, v137
	s_waitcnt vmcnt(25)
	ds_write_b32 v154, v138
	s_waitcnt vmcnt(24)
	ds_write_b32 v155, v139
	s_waitcnt vmcnt(23)
	ds_write_b32 v156, v140
	s_waitcnt vmcnt(22)
	ds_write_b32 v157, v141
	s_waitcnt vmcnt(21)
	ds_write_b32 v158, v142
	s_waitcnt vmcnt(20)
	ds_write_b32 v159, v143
	s_waitcnt vmcnt(19)
	ds_write_b32 v160, v144
	s_waitcnt vmcnt(18)
	ds_write_b32 v161, v145
	s_waitcnt vmcnt(17)
	ds_write_b32 v162, v146
	s_waitcnt vmcnt(16)
	ds_write_b32 v163, v147
	s_waitcnt vmcnt(15)
	ds_write_b32 v52, v110
	s_waitcnt vmcnt(14)
	ds_write_b32 v54, v111
	s_waitcnt vmcnt(13)
	ds_write_b32 v56, v112
	s_waitcnt vmcnt(12)
	ds_write_b32 v58, v113
	s_waitcnt vmcnt(11)
	ds_write_b32 v60, v114
	s_waitcnt vmcnt(10)
	ds_write_b32 v62, v115
	s_waitcnt vmcnt(9)
	ds_write_b32 v64, v116
	s_waitcnt vmcnt(8)
	ds_write_b32 v78, v117
	s_waitcnt vmcnt(7)
	ds_write_b32 v80, v118
	s_waitcnt vmcnt(6)
	ds_write_b32 v82, v119
	s_waitcnt vmcnt(5)
	ds_write_b32 v84, v120
	s_waitcnt vmcnt(4)
	ds_write_b32 v86, v121
	s_waitcnt vmcnt(3)
	ds_write_b32 v88, v122
	s_waitcnt vmcnt(2)
	ds_write_b32 v90, v123
	s_waitcnt vmcnt(1)
	ds_write_b32 v92, v124
	s_waitcnt vmcnt(0)
	ds_write_b32 v94, v125
	s_waitcnt lgkmcnt(0)
	ds_read2_b32 v[54:55], v5 offset0:33 offset1:41
	ds_read2_b32 v[56:57], v5 offset1:8
	ds_read2_b32 v[58:59], v5 offset0:66 offset1:74
	ds_read2_b32 v[60:61], v5 offset0:99 offset1:107
	ds_read2_b32 v[62:63], v5 offset0:132 offset1:140
	ds_read2_b32 v[64:65], v5 offset0:165 offset1:173
	ds_read2_b32 v[78:79], v5 offset0:198 offset1:206
	ds_read2_b32 v[80:81], v5 offset0:231 offset1:239
	s_mov_b32 s5, s25
	v_or_b32_e32 v8, s2, v3
	v_lshl_add_u64 v[82:83], s[4:5], 1, v[22:23]
	v_lshlrev_b32_e32 v8, 11, v8
	s_waitcnt lgkmcnt(6)
	v_cvt_pk_bf16_f32 v50, v56, v54
	s_waitcnt lgkmcnt(4)
	v_cvt_pk_bf16_f32 v51, v58, v60
	s_waitcnt lgkmcnt(2)
	v_cvt_pk_bf16_f32 v52, v62, v64
	s_waitcnt lgkmcnt(0)
	v_cvt_pk_bf16_f32 v53, v78, v80
	v_lshl_add_u64 v[84:85], v[82:83], 0, v[8:9]
	global_store_dwordx4 v[84:85], v[50:53], off
	v_or_b32_e32 v8, s2, v7
	v_lshlrev_b32_e32 v8, 11, v8
	v_cvt_pk_bf16_f32 v50, v57, v55
	v_cvt_pk_bf16_f32 v51, v59, v61
	v_cvt_pk_bf16_f32 v52, v63, v65
	v_cvt_pk_bf16_f32 v53, v79, v81
	ds_read2_b32 v[56:57], v5 offset0:49 offset1:57
	ds_read2_b32 v[58:59], v5 offset0:16 offset1:24
	ds_read2_b32 v[60:61], v5 offset0:82 offset1:90
	ds_read2_b32 v[62:63], v5 offset0:115 offset1:123
	ds_read2_b32 v[64:65], v5 offset0:148 offset1:156
	ds_read2_b32 v[78:79], v5 offset0:181 offset1:189
	ds_read2_b32 v[80:81], v5 offset0:214 offset1:222
	ds_read2_b32 v[84:85], v5 offset0:247 offset1:255
	v_lshl_add_u64 v[54:55], v[82:83], 0, v[8:9]
	v_or_b32_e32 v8, s2, v68
	v_lshlrev_b32_e32 v8, 11, v8
	global_store_dwordx4 v[54:55], v[50:53], off
	v_lshl_add_u64 v[54:55], v[82:83], 0, v[8:9]
	v_or_b32_e32 v8, s2, v69
	s_waitcnt lgkmcnt(6)
	v_cvt_pk_bf16_f32 v50, v58, v56
	s_waitcnt lgkmcnt(4)
	v_cvt_pk_bf16_f32 v51, v60, v62
	s_waitcnt lgkmcnt(2)
	v_cvt_pk_bf16_f32 v52, v64, v78
	s_waitcnt lgkmcnt(0)
	v_cvt_pk_bf16_f32 v53, v80, v84
	v_lshlrev_b32_e32 v8, 11, v8
	global_store_dwordx4 v[54:55], v[50:53], off
	v_lshl_add_u64 v[54:55], v[82:83], 0, v[8:9]
	s_nop 0
	v_cvt_pk_bf16_f32 v50, v59, v57
	v_cvt_pk_bf16_f32 v51, v61, v63
	v_cvt_pk_bf16_f32 v52, v65, v79
	v_cvt_pk_bf16_f32 v53, v81, v85
	global_store_dwordx4 v[54:55], v[50:53], off
	s_waitcnt lgkmcnt(0)

; __device__ __forceinline__ void tr_item(const float* W, int ldw, int src_col, int nvalid, int k0, bf16_t* WT, int ldt, int dst_row, int dst_k, LAS float* scr, int lane) {
; #pragma unroll 8
;     for (int i = 0; i < 32; ++i) { const int kk = 2 * i + (lane >> 5), c = lane & 31; scr[kk * 33 + c] = (c < nvalid) ? W[(size_t)(k0 + kk) * ldw + src_col + c] : 0.f; }
.LBB0_60:
	s_lshl_b32 s15, s4, 1
	s_lshl_b32 s16, s7, 1
	v_or_b32_e32 v86, s16, v2
	s_add_i32 s17, s15, 4
	s_add_i32 s18, s16, 4
	s_add_i32 s23, s16, 8
	v_add_u32_e32 v8, s5, v86
	v_or_b32_e32 v87, s17, v1
	v_or_b32_e32 v88, s18, v2
	v_mov_b32_e32 v55, v9
	v_or_b32_e32 v47, s15, v1
	s_add_i32 s26, s16, 12
	v_or_b32_e32 v90, s23, v2
	v_lshlrev_b64 v[80:81], 12, v[8:9]
	v_add_u32_e32 v54, s6, v87
	v_add_u32_e32 v8, s5, v88
	v_mov_b32_e32 v53, v9
	s_add_i32 s19, s15, 8
	s_add_i32 s24, s15, 12
	s_add_i32 s28, s16, 16
	v_add_u32_e32 v52, s6, v47
	v_or_b32_e32 v92, s26, v2
	v_lshlrev_b64 v[54:55], 12, v[54:55]
	v_lshlrev_b64 v[82:83], 12, v[8:9]
	v_add_u32_e32 v8, s5, v90
	s_add_i32 s30, s16, 20
	v_or_b32_e32 v89, s19, v1
	v_or_b32_e32 v91, s24, v1
	v_or_b32_e32 v94, s28, v2
	v_lshlrev_b64 v[52:53], 12, v[52:53]
	v_lshl_add_u64 v[80:81], v[50:51], 0, v[80:81]
	v_lshl_add_u64 v[54:55], v[50:51], 0, v[54:55]
	v_lshlrev_b64 v[84:85], 12, v[8:9]
	v_add_u32_e32 v8, s5, v92
	v_mov_b32_e32 v57, v9
	v_mov_b32_e32 v59, v9
	s_add_i32 s27, s15, 16
	s_add_i32 s29, s15, 20
	s_add_i32 s34, s16, 24
	v_or_b32_e32 v96, s30, v2
	v_add_u32_e32 v56, s6, v89
	v_add_u32_e32 v58, s6, v91
	v_lshl_add_u64 v[52:53], v[50:51], 0, v[52:53]
	v_lshl_add_u64 v[82:83], v[50:51], 0, v[82:83]
	global_load_dword v132, v[80:81], off
	global_load_dword v133, v[52:53], off
	global_load_dword v134, v[82:83], off
	global_load_dword v135, v[54:55], off
	v_lshlrev_b64 v[54:55], 12, v[8:9]
	v_add_u32_e32 v8, s5, v94
	s_add_i32 s31, s15, 24
	s_add_i32 s15, s15, 28
	s_add_i32 s16, s16, 28
	v_or_b32_e32 v93, s27, v1
	v_or_b32_e32 v95, s29, v1
	v_or_b32_e32 v98, s34, v2
	v_lshlrev_b64 v[56:57], 12, v[56:57]
	v_lshlrev_b64 v[58:59], 12, v[58:59]
	v_lshl_add_u64 v[52:53], v[50:51], 0, v[84:85]
	v_lshl_add_u64 v[54:55], v[50:51], 0, v[54:55]
	v_lshlrev_b64 v[80:81], 12, v[8:9]
	v_add_u32_e32 v8, s5, v96
	v_mov_b32_e32 v61, v9
	v_mov_b32_e32 v63, v9
	v_or_b32_e32 v97, s31, v1
	v_or_b32_e32 v99, s15, v1
	v_or_b32_e32 v100, s16, v2
	v_add_u32_e32 v60, s6, v93
	v_add_u32_e32 v62, s6, v95
	v_lshl_add_u64 v[56:57], v[50:51], 0, v[56:57]
	v_lshl_add_u64 v[58:59], v[50:51], 0, v[58:59]
	global_load_dword v136, v[52:53], off
	global_load_dword v137, v[56:57], off
	global_load_dword v138, v[54:55], off
	global_load_dword v139, v[58:59], off
	v_lshlrev_b64 v[54:55], 12, v[8:9]
	v_add_u32_e32 v8, s5, v98
	v_mov_b32_e32 v65, v9
	v_mov_b32_e32 v79, v9
	v_add_u32_e32 v64, s6, v97
	v_add_u32_e32 v78, s6, v99
	v_lshlrev_b64 v[60:61], 12, v[60:61]
	v_lshlrev_b64 v[62:63], 12, v[62:63]
	v_lshl_add_u64 v[52:53], v[50:51], 0, v[80:81]
	v_lshl_add_u64 v[54:55], v[50:51], 0, v[54:55]
	v_lshlrev_b64 v[56:57], 12, v[8:9]
	v_add_u32_e32 v8, s5, v100
	v_lshlrev_b64 v[64:65], 12, v[64:65]
	v_lshlrev_b64 v[78:79], 12, v[78:79]
	v_lshl_add_u64 v[60:61], v[50:51], 0, v[60:61]
	v_lshl_add_u64 v[62:63], v[50:51], 0, v[62:63]
	global_load_dword v140, v[52:53], off
	global_load_dword v141, v[60:61], off
	global_load_dword v142, v[54:55], off
	global_load_dword v143, v[62:63], off
	v_lshl_add_u64 v[52:53], v[50:51], 0, v[56:57]
	v_lshlrev_b64 v[54:55], 12, v[8:9]
	v_lshl_add_u64 v[64:65], v[50:51], 0, v[64:65]
	v_lshl_add_u64 v[78:79], v[50:51], 0, v[78:79]
	v_lshl_add_u64 v[54:55], v[50:51], 0, v[54:55]
	global_load_dword v144, v[52:53], off
	global_load_dword v145, v[64:65], off
	global_load_dword v146, v[54:55], off
	global_load_dword v147, v[78:79], off
	s_add_i32 s7, s7, 16
	s_add_i32 s4, s4, 16
	s_add_i32 s14, s14, -16
	v_mad_u64_u32 v[52:53], s[16:17], v86, s8, v[6:7]
	s_cmp_lg_u32 s14, 0
	v_mad_u64_u32 v[54:55], s[16:17], v47, s8, v[6:7]
	v_mad_u64_u32 v[56:57], s[16:17], v88, s8, v[6:7]
	v_mad_u64_u32 v[58:59], s[16:17], v87, s8, v[6:7]
	v_mad_u64_u32 v[60:61], s[16:17], v90, s8, v[6:7]
	v_mad_u64_u32 v[62:63], s[16:17], v89, s8, v[6:7]
	v_mad_u64_u32 v[64:65], s[16:17], v92, s8, v[6:7]
	v_mad_u64_u32 v[78:79], s[16:17], v91, s8, v[6:7]
	v_mad_u64_u32 v[80:81], s[16:17], v94, s8, v[6:7]
	v_mad_u64_u32 v[82:83], s[16:17], v93, s8, v[6:7]
	v_mad_u64_u32 v[84:85], s[16:17], v96, s8, v[6:7]
	v_mad_u64_u32 v[86:87], s[16:17], v95, s8, v[6:7]
	v_mad_u64_u32 v[88:89], s[16:17], v98, s8, v[6:7]
	v_mad_u64_u32 v[90:91], s[16:17], v97, s8, v[6:7]
	v_mad_u64_u32 v[92:93], s[16:17], v100, s8, v[6:7]
	v_mad_u64_u32 v[94:95], s[16:17], v99, s8, v[6:7]
	v_mov_b32_e32 v148, v52
	v_mov_b32_e32 v149, v54
	v_mov_b32_e32 v150, v56
	v_mov_b32_e32 v151, v58
	v_mov_b32_e32 v152, v60
	v_mov_b32_e32 v153, v62
	v_mov_b32_e32 v154, v64
	v_mov_b32_e32 v155, v78
	v_mov_b32_e32 v156, v80
	v_mov_b32_e32 v157, v82
	v_mov_b32_e32 v158, v84
	v_mov_b32_e32 v159, v86
	v_mov_b32_e32 v160, v88
	v_mov_b32_e32 v161, v90
	v_mov_b32_e32 v162, v92
	v_mov_b32_e32 v163, v94
	s_lshl_b32 s15, s4, 1
	s_lshl_b32 s16, s7, 1
	v_or_b32_e32 v86, s16, v2
	s_add_i32 s17, s15, 4
	s_add_i32 s18, s16, 4
	s_add_i32 s23, s16, 8
	v_add_u32_e32 v8, s5, v86
	v_or_b32_e32 v87, s17, v1
	v_or_b32_e32 v88, s18, v2
	v_mov_b32_e32 v55, v9
	v_or_b32_e32 v47, s15, v1
	s_add_i32 s26, s16, 12
	v_or_b32_e32 v90, s23, v2
	v_lshlrev_b64 v[80:81], 12, v[8:9]
	v_add_u32_e32 v54, s6, v87
	v_add_u32_e32 v8, s5, v88
	v_mov_b32_e32 v53, v9
	s_add_i32 s19, s15, 8
	s_add_i32 s24, s15, 12
	s_add_i32 s28, s16, 16
	v_add_u32_e32 v52, s6, v47
	v_or_b32_e32 v92, s26, v2
	v_lshlrev_b64 v[54:55], 12, v[54:55]
	v_lshlrev_b64 v[82:83], 12, v[8:9]
	v_add_u32_e32 v8, s5, v90
	s_add_i32 s30, s16, 20
	v_or_b32_e32 v89, s19, v1
	v_or_b32_e32 v91, s24, v1
	v_or_b32_e32 v94, s28, v2
	v_lshlrev_b64 v[52:53], 12, v[52:53]
	v_lshl_add_u64 v[80:81], v[50:51], 0, v[80:81]
	v_lshl_add_u64 v[54:55], v[50:51], 0, v[54:55]
; __device__ __forceinline__ void tr_item(const float* W, int ldw, int src_col, int nvalid, int k0, bf16_t* WT, int ldt, int dst_row, int dst_k, LAS float* scr, int lane) {
; #pragma unroll 8
;     for (int i = 0; i < 32; ++i) { const int kk = 2 * i + (lane >> 5), c = lane & 31; scr[kk * 33 + c] = (c < nvalid) ? W[(size_t)(k0 + kk) * ldw + src_col + c] : 0.f; }
	v_lshlrev_b64 v[84:85], 12, v[8:9]
	v_add_u32_e32 v8, s5, v92
	v_mov_b32_e32 v57, v9
	v_mov_b32_e32 v59, v9
	s_add_i32 s27, s15, 16
	s_add_i32 s29, s15, 20
	s_add_i32 s34, s16, 24
	v_or_b32_e32 v96, s30, v2
	v_add_u32_e32 v56, s6, v89
	v_add_u32_e32 v58, s6, v91
	v_lshl_add_u64 v[52:53], v[50:51], 0, v[52:53]
	v_lshl_add_u64 v[82:83], v[50:51], 0, v[82:83]
	global_load_dword v101, v[80:81], off
	global_load_dword v102, v[52:53], off
	global_load_dword v103, v[82:83], off
	global_load_dword v104, v[54:55], off
	v_lshlrev_b64 v[54:55], 12, v[8:9]
	v_add_u32_e32 v8, s5, v94
	s_add_i32 s31, s15, 24
	s_add_i32 s15, s15, 28
	s_add_i32 s16, s16, 28
	v_or_b32_e32 v93, s27, v1
	v_or_b32_e32 v95, s29, v1
	v_or_b32_e32 v98, s34, v2
	v_lshlrev_b64 v[56:57], 12, v[56:57]
	v_lshlrev_b64 v[58:59], 12, v[58:59]
	v_lshl_add_u64 v[52:53], v[50:51], 0, v[84:85]
	v_lshl_add_u64 v[54:55], v[50:51], 0, v[54:55]
	v_lshlrev_b64 v[80:81], 12, v[8:9]
	v_add_u32_e32 v8, s5, v96
	v_mov_b32_e32 v61, v9
	v_mov_b32_e32 v63, v9
	v_or_b32_e32 v97, s31, v1
	v_or_b32_e32 v99, s15, v1
	v_or_b32_e32 v100, s16, v2
	v_add_u32_e32 v60, s6, v93
	v_add_u32_e32 v62, s6, v95
	v_lshl_add_u64 v[56:57], v[50:51], 0, v[56:57]
	v_lshl_add_u64 v[58:59], v[50:51], 0, v[58:59]
	global_load_dword v105, v[52:53], off
	global_load_dword v106, v[56:57], off
	global_load_dword v107, v[54:55], off
	global_load_dword v108, v[58:59], off
	v_lshlrev_b64 v[54:55], 12, v[8:9]
	v_add_u32_e32 v8, s5, v98
	v_mov_b32_e32 v65, v9
	v_mov_b32_e32 v79, v9
	v_add_u32_e32 v64, s6, v97
	v_add_u32_e32 v78, s6, v99
	v_lshlrev_b64 v[60:61], 12, v[60:61]
	v_lshlrev_b64 v[62:63], 12, v[62:63]
	v_lshl_add_u64 v[52:53], v[50:51], 0, v[80:81]
	v_lshl_add_u64 v[54:55], v[50:51], 0, v[54:55]
	v_lshlrev_b64 v[56:57], 12, v[8:9]
	v_add_u32_e32 v8, s5, v100
	v_lshlrev_b64 v[64:65], 12, v[64:65]
	v_lshlrev_b64 v[78:79], 12, v[78:79]
	v_lshl_add_u64 v[60:61], v[50:51], 0, v[60:61]
	v_lshl_add_u64 v[62:63], v[50:51], 0, v[62:63]
	global_load_dword v109, v[52:53], off
	global_load_dword v110, v[60:61], off
	global_load_dword v111, v[54:55], off
	global_load_dword v112, v[62:63], off
	v_lshl_add_u64 v[52:53], v[50:51], 0, v[56:57]
	v_lshlrev_b64 v[54:55], 12, v[8:9]
	v_lshl_add_u64 v[64:65], v[50:51], 0, v[64:65]
	v_lshl_add_u64 v[78:79], v[50:51], 0, v[78:79]
	v_lshl_add_u64 v[54:55], v[50:51], 0, v[54:55]
	global_load_dword v8, v[52:53], off
	global_load_dword v113, v[64:65], off
	global_load_dword v114, v[54:55], off
	global_load_dword v115, v[78:79], off
	s_add_i32 s7, s7, 16
	s_add_i32 s4, s4, 16
	s_add_i32 s14, s14, -16
	v_mad_u64_u32 v[52:53], s[16:17], v86, s8, v[6:7]
	s_cmp_lg_u32 s14, 0
	v_mad_u64_u32 v[54:55], s[16:17], v47, s8, v[6:7]
	v_mad_u64_u32 v[56:57], s[16:17], v88, s8, v[6:7]
	v_mad_u64_u32 v[58:59], s[16:17], v87, s8, v[6:7]
	v_mad_u64_u32 v[60:61], s[16:17], v90, s8, v[6:7]
	v_mad_u64_u32 v[62:63], s[16:17], v89, s8, v[6:7]
	v_mad_u64_u32 v[64:65], s[16:17], v92, s8, v[6:7]
	v_mad_u64_u32 v[78:79], s[16:17], v91, s8, v[6:7]
	v_mad_u64_u32 v[80:81], s[16:17], v94, s8, v[6:7]
	v_mad_u64_u32 v[82:83], s[16:17], v93, s8, v[6:7]
	v_mad_u64_u32 v[84:85], s[16:17], v96, s8, v[6:7]
	v_mad_u64_u32 v[86:87], s[16:17], v95, s8, v[6:7]
	v_mad_u64_u32 v[88:89], s[16:17], v98, s8, v[6:7]
	v_mad_u64_u32 v[90:91], s[16:17], v97, s8, v[6:7]
	v_mad_u64_u32 v[92:93], s[16:17], v100, s8, v[6:7]
	v_mad_u64_u32 v[94:95], s[16:17], v99, s8, v[6:7]
	s_waitcnt vmcnt(31)
	ds_write_b32 v148, v132
	s_waitcnt vmcnt(30)
	ds_write_b32 v149, v133
	s_waitcnt vmcnt(29)
	ds_write_b32 v150, v134
	s_waitcnt vmcnt(28)
	ds_write_b32 v151, v135
	s_waitcnt vmcnt(27)
; #define LAS __attribute__((address_space(3)))
; __device__ __forceinline__ unsigned cvt_pk_bf16(float lo, float hi) { f32x2_t v = {lo, hi}; bf16x2_t b = __builtin_convertvector(v, bf16x2_t); return __builtin_bit_cast(unsigned, b); }
; #define LDS_WAIT() asm volatile("s_waitcnt lgkmcnt(0)" ::: "memory")
; __device__ __forceinline__ void tr_item(const float* W, int ldw, int src_col, int nvalid, int k0, bf16_t* WT, int ldt, int dst_row, int dst_k, LAS float* scr, int lane) {
;     ...
;     for (int i = 0; i < 32; ++i) { const int kk = 2 * i + (lane >> 5), c = lane & 31; scr[kk * 33 + c] = (c < nvalid) ? W[(size_t)(k0 + kk) * ldw + src_col + c] : 0.f; }
;     LDS_WAIT();
;     const int c = lane & 7;
; #pragma unroll
;     for (int j = 0; j < 4; ++j) { const int n = (lane >> 3) + 8 * j; const LAS float* s = scr + (8 * c) * 33 + n;
;         u32x4 o; o.x = cvt_pk_bf16(s[0 * 33], s[1 * 33]); o.y = cvt_pk_bf16(s[2 * 33], s[3 * 33]); o.z = cvt_pk_bf16(s[4 * 33], s[5 * 33]); o.w = cvt_pk_bf16(s[6 * 33], s[7 * 33]);
;         *(u32x4*)(WT + (size_t)(dst_row + n) * ldt + dst_k + k0 + 8 * c) = o; }
;     LDS_WAIT();
	ds_write_b32 v152, v136
	s_waitcnt vmcnt(26)
	ds_write_b32 v153, v137
	s_waitcnt vmcnt(25)
	ds_write_b32 v154, v138
	s_waitcnt vmcnt(24)
	ds_write_b32 v155, v139
	s_waitcnt vmcnt(23)
	ds_write_b32 v156, v140
	s_waitcnt vmcnt(22)
	ds_write_b32 v157, v141
	s_waitcnt vmcnt(21)
	ds_write_b32 v158, v142
	s_waitcnt vmcnt(20)
	ds_write_b32 v159, v143
	s_waitcnt vmcnt(19)
	ds_write_b32 v160, v144
	s_waitcnt vmcnt(18)
	ds_write_b32 v161, v145
	s_waitcnt vmcnt(17)
	ds_write_b32 v162, v146
	s_waitcnt vmcnt(16)
	ds_write_b32 v163, v147
	s_waitcnt vmcnt(15)
	ds_write_b32 v52, v101
	s_waitcnt vmcnt(14)
	ds_write_b32 v54, v102
	s_waitcnt vmcnt(13)
	ds_write_b32 v56, v103
	s_waitcnt vmcnt(12)
	ds_write_b32 v58, v104
	s_waitcnt vmcnt(11)
	ds_write_b32 v60, v105
	s_waitcnt vmcnt(10)
	ds_write_b32 v62, v106
	s_waitcnt vmcnt(9)
	ds_write_b32 v64, v107
	s_waitcnt vmcnt(8)
	ds_write_b32 v78, v108
	s_waitcnt vmcnt(7)
	ds_write_b32 v80, v109
	s_waitcnt vmcnt(6)
	ds_write_b32 v82, v110
	s_waitcnt vmcnt(5)
	ds_write_b32 v84, v111
	s_waitcnt vmcnt(4)
	ds_write_b32 v86, v112
	s_waitcnt vmcnt(3)
	ds_write_b32 v88, v8
	s_waitcnt vmcnt(2)
	ds_write_b32 v90, v113
	s_waitcnt vmcnt(1)
	ds_write_b32 v92, v114
	s_waitcnt vmcnt(0)
	ds_write_b32 v94, v115
	s_waitcnt lgkmcnt(0)
	s_lshl_b32 s3, s3, 10
	s_add_u32 s3, s9, s3
	ds_read2_b32 v[54:55], v5 offset0:33 offset1:41
	ds_read2_b32 v[56:57], v5 offset1:8
	ds_read2_b32 v[58:59], v5 offset0:66 offset1:74
	ds_read2_b32 v[60:61], v5 offset0:99 offset1:107
	ds_read2_b32 v[62:63], v5 offset0:132 offset1:140
	ds_read2_b32 v[64:65], v5 offset0:165 offset1:173
	ds_read2_b32 v[78:79], v5 offset0:198 offset1:206
	ds_read2_b32 v[80:81], v5 offset0:231 offset1:239
	s_addc_u32 s6, s10, 0
	s_lshl_b32 s4, s5, 1
	s_add_u32 s4, s3, s4
	s_addc_u32 s5, s6, 0
	v_mov_b32_e32 v47, v9
	v_or_b32_e32 v8, s2, v3
	v_lshl_add_u64 v[82:83], s[4:5], 0, v[46:47]
	v_mul_u32_u24_e32 v8, 0xc00, v8
	s_waitcnt lgkmcnt(6)
	v_cvt_pk_bf16_f32 v50, v56, v54
	s_waitcnt lgkmcnt(4)
	v_cvt_pk_bf16_f32 v51, v58, v60
	s_waitcnt lgkmcnt(2)
	v_cvt_pk_bf16_f32 v52, v62, v64
	s_waitcnt lgkmcnt(0)
	v_cvt_pk_bf16_f32 v53, v78, v80
	v_lshl_add_u64 v[84:85], v[82:83], 0, v[8:9]
	global_store_dwordx4 v[84:85], v[50:53], off
	v_or_b32_e32 v8, s2, v7
	v_mul_u32_u24_e32 v8, 0xc00, v8
	v_cvt_pk_bf16_f32 v50, v57, v55
	v_cvt_pk_bf16_f32 v51, v59, v61
	v_cvt_pk_bf16_f32 v52, v63, v65
	v_cvt_pk_bf16_f32 v53, v79, v81
	ds_read2_b32 v[56:57], v5 offset0:16 offset1:24
	ds_read2_b32 v[58:59], v5 offset0:49 offset1:57
	ds_read2_b32 v[60:61], v5 offset0:82 offset1:90
	ds_read2_b32 v[62:63], v5 offset0:115 offset1:123
	ds_read2_b32 v[64:65], v5 offset0:148 offset1:156
	ds_read2_b32 v[78:79], v5 offset0:181 offset1:189
	ds_read2_b32 v[80:81], v5 offset0:214 offset1:222
	ds_read2_b32 v[84:85], v5 offset0:247 offset1:255
	v_lshl_add_u64 v[54:55], v[82:83], 0, v[8:9]
	v_or_b32_e32 v8, s2, v68
	v_mul_u32_u24_e32 v8, 0xc00, v8
	global_store_dwordx4 v[54:55], v[50:53], off
	v_lshl_add_u64 v[54:55], v[82:83], 0, v[8:9]
	v_or_b32_e32 v8, s2, v69
	s_waitcnt lgkmcnt(6)
	v_cvt_pk_bf16_f32 v50, v56, v58
	s_waitcnt lgkmcnt(4)
	v_cvt_pk_bf16_f32 v51, v60, v62
	s_waitcnt lgkmcnt(2)
	v_cvt_pk_bf16_f32 v52, v64, v78
	s_waitcnt lgkmcnt(0)
	v_cvt_pk_bf16_f32 v53, v80, v84
	v_mul_u32_u24_e32 v8, 0xc00, v8
	global_store_dwordx4 v[54:55], v[50:53], off
	v_lshl_add_u64 v[54:55], v[82:83], 0, v[8:9]
	s_nop 0
	v_cvt_pk_bf16_f32 v50, v57, v59
	v_cvt_pk_bf16_f32 v51, v61, v63
	v_cvt_pk_bf16_f32 v52, v65, v79
	v_cvt_pk_bf16_f32 v53, v81, v85
	global_store_dwordx4 v[54:55], v[50:53], off
	s_waitcnt lgkmcnt(0)

; __device__ __forceinline__ void tr_item(const float* W, int ldw, int src_col, int nvalid, int k0, bf16_t* WT, int ldt, int dst_row, int dst_k, LAS float* scr, int lane) {
; #pragma unroll 8
;     for (int i = 0; i < 32; ++i) { const int kk = 2 * i + (lane >> 5), c = lane & 31; scr[kk * 33 + c] = (c < nvalid) ? W[(size_t)(k0 + kk) * ldw + src_col + c] : 0.f; }
.LBB0_65:
	s_lshl_b32 s14, s5, 1
	s_lshl_b32 s15, s6, 1
	v_or_b32_e32 v8, s14, v1
	v_or_b32_e32 v47, s15, v2
	s_add_i32 s16, s14, 4
	s_add_i32 s17, s15, 4
	s_add_i32 s18, s14, 8
	s_add_i32 s19, s15, 8
	s_add_i32 s23, s14, 12
	s_add_i32 s24, s15, 12
	s_add_i32 s26, s14, 16
	s_add_i32 s27, s15, 16
	s_add_i32 s28, s14, 20
	s_add_i32 s29, s15, 20
	s_add_i32 s30, s14, 24
	s_add_i32 s31, s15, 24
	s_add_i32 s14, s14, 28
	s_add_i32 s15, s15, 28
	v_add_u32_e32 v52, s2, v47
	v_or_b32_e32 v96, s16, v1
	v_or_b32_e32 v97, s17, v2
	v_or_b32_e32 v98, s18, v1
	v_or_b32_e32 v99, s19, v2
	v_or_b32_e32 v100, s23, v1
	v_or_b32_e32 v101, s24, v2
	v_or_b32_e32 v102, s26, v1
	v_or_b32_e32 v103, s27, v2
	v_or_b32_e32 v104, s28, v1
	v_or_b32_e32 v105, s29, v2
	v_or_b32_e32 v106, s30, v1
	v_or_b32_e32 v107, s31, v2
	v_or_b32_e32 v108, s14, v1
	v_or_b32_e32 v109, s15, v2
	v_add_u32_e32 v54, s4, v8
	v_mad_u64_u32 v[52:53], s[14:15], v52, s12, v[50:51]
	v_add_u32_e32 v58, s4, v96
	v_add_u32_e32 v56, s2, v97
	v_add_u32_e32 v62, s4, v98
	v_add_u32_e32 v60, s2, v99
	v_add_u32_e32 v78, s4, v100
	v_add_u32_e32 v64, s2, v101
	v_add_u32_e32 v82, s4, v102
	v_add_u32_e32 v80, s2, v103
	v_add_u32_e32 v86, s4, v104
	v_add_u32_e32 v84, s2, v105
	v_add_u32_e32 v90, s4, v106
	v_add_u32_e32 v88, s2, v107
	v_add_u32_e32 v94, s4, v108
	v_add_u32_e32 v92, s2, v109
	v_mad_u64_u32 v[54:55], s[14:15], v54, s12, v[50:51]
	v_mad_u64_u32 v[56:57], s[14:15], v56, s12, v[50:51]
	v_mad_u64_u32 v[58:59], s[14:15], v58, s12, v[50:51]
	v_mad_u64_u32 v[60:61], s[14:15], v60, s12, v[50:51]
	v_mad_u64_u32 v[62:63], s[14:15], v62, s12, v[50:51]
	v_mad_u64_u32 v[64:65], s[14:15], v64, s12, v[50:51]
	v_mad_u64_u32 v[78:79], s[14:15], v78, s12, v[50:51]
	v_mad_u64_u32 v[80:81], s[14:15], v80, s12, v[50:51]
	v_mad_u64_u32 v[82:83], s[14:15], v82, s12, v[50:51]
	v_mad_u64_u32 v[84:85], s[14:15], v84, s12, v[50:51]
	v_mad_u64_u32 v[86:87], s[14:15], v86, s12, v[50:51]
	v_mad_u64_u32 v[88:89], s[14:15], v88, s12, v[50:51]
	v_mad_u64_u32 v[90:91], s[14:15], v90, s12, v[50:51]
	v_mad_u64_u32 v[92:93], s[14:15], v92, s12, v[50:51]
	v_mad_u64_u32 v[94:95], s[14:15], v94, s12, v[50:51]
	global_load_dword v132, v[52:53], off
	global_load_dword v133, v[54:55], off
	global_load_dword v134, v[56:57], off
	global_load_dword v135, v[58:59], off
	global_load_dword v136, v[60:61], off
	global_load_dword v137, v[62:63], off
	global_load_dword v138, v[64:65], off
	global_load_dword v139, v[78:79], off
	global_load_dword v140, v[80:81], off
	global_load_dword v141, v[82:83], off
	global_load_dword v142, v[84:85], off
	global_load_dword v143, v[86:87], off
	global_load_dword v144, v[88:89], off
	global_load_dword v145, v[90:91], off
	global_load_dword v146, v[92:93], off
	global_load_dword v147, v[94:95], off
	s_add_i32 s6, s6, 16
	s_add_i32 s5, s5, 16
	s_add_i32 s7, s7, -16
	v_mad_u64_u32 v[52:53], s[14:15], v47, s8, v[6:7]
	s_cmp_lg_u32 s7, 0
	v_mad_u64_u32 v[54:55], s[14:15], v8, s8, v[6:7]
	v_mad_u64_u32 v[56:57], s[14:15], v97, s8, v[6:7]
	v_mad_u64_u32 v[58:59], s[14:15], v96, s8, v[6:7]
	v_mad_u64_u32 v[60:61], s[14:15], v99, s8, v[6:7]
	v_mad_u64_u32 v[62:63], s[14:15], v98, s8, v[6:7]
	v_mad_u64_u32 v[64:65], s[14:15], v101, s8, v[6:7]
	v_mad_u64_u32 v[78:79], s[14:15], v100, s8, v[6:7]
	v_mad_u64_u32 v[80:81], s[14:15], v103, s8, v[6:7]
	v_mad_u64_u32 v[82:83], s[14:15], v102, s8, v[6:7]
	v_mad_u64_u32 v[84:85], s[14:15], v105, s8, v[6:7]
	v_mad_u64_u32 v[86:87], s[14:15], v104, s8, v[6:7]
	v_mad_u64_u32 v[88:89], s[14:15], v107, s8, v[6:7]
	v_mad_u64_u32 v[90:91], s[14:15], v106, s8, v[6:7]
	v_mad_u64_u32 v[92:93], s[14:15], v109, s8, v[6:7]
	v_mad_u64_u32 v[94:95], s[14:15], v108, s8, v[6:7]
	v_mov_b32_e32 v148, v52
	v_mov_b32_e32 v149, v54
	v_mov_b32_e32 v150, v56
	v_mov_b32_e32 v151, v58
	v_mov_b32_e32 v152, v60
	v_mov_b32_e32 v153, v62
	v_mov_b32_e32 v154, v64
	v_mov_b32_e32 v155, v78
	v_mov_b32_e32 v156, v80
	v_mov_b32_e32 v157, v82
	v_mov_b32_e32 v158, v84
	v_mov_b32_e32 v159, v86
	v_mov_b32_e32 v160, v88
	v_mov_b32_e32 v161, v90
	v_mov_b32_e32 v162, v92
	v_mov_b32_e32 v163, v94
	s_lshl_b32 s14, s5, 1
	s_lshl_b32 s15, s6, 1
	v_or_b32_e32 v8, s14, v1
	v_or_b32_e32 v47, s15, v2
	s_add_i32 s16, s14, 4
	s_add_i32 s17, s15, 4
	s_add_i32 s18, s14, 8
	s_add_i32 s19, s15, 8
	s_add_i32 s23, s14, 12
	s_add_i32 s24, s15, 12
	s_add_i32 s26, s14, 16
	s_add_i32 s27, s15, 16
	s_add_i32 s28, s14, 20
	s_add_i32 s29, s15, 20
	s_add_i32 s30, s14, 24
	s_add_i32 s31, s15, 24
	s_add_i32 s14, s14, 28
	s_add_i32 s15, s15, 28
	v_add_u32_e32 v52, s2, v47
	v_or_b32_e32 v96, s16, v1
	v_or_b32_e32 v97, s17, v2
	v_or_b32_e32 v98, s18, v1
	v_or_b32_e32 v99, s19, v2
	v_or_b32_e32 v100, s23, v1
	v_or_b32_e32 v101, s24, v2
	v_or_b32_e32 v102, s26, v1
	v_or_b32_e32 v103, s27, v2
	v_or_b32_e32 v104, s28, v1
	v_or_b32_e32 v105, s29, v2
	v_or_b32_e32 v106, s30, v1
	v_or_b32_e32 v107, s31, v2
	v_or_b32_e32 v108, s14, v1
	v_or_b32_e32 v109, s15, v2
	v_add_u32_e32 v54, s4, v8
	v_mad_u64_u32 v[52:53], s[14:15], v52, s12, v[50:51]
	v_add_u32_e32 v58, s4, v96
	v_add_u32_e32 v56, s2, v97
	v_add_u32_e32 v62, s4, v98
	v_add_u32_e32 v60, s2, v99
	v_add_u32_e32 v78, s4, v100
	v_add_u32_e32 v64, s2, v101
	v_add_u32_e32 v82, s4, v102
	v_add_u32_e32 v80, s2, v103
	v_add_u32_e32 v86, s4, v104
	v_add_u32_e32 v84, s2, v105
	v_add_u32_e32 v90, s4, v106
	v_add_u32_e32 v88, s2, v107
	v_add_u32_e32 v94, s4, v108
	v_add_u32_e32 v92, s2, v109
	v_mad_u64_u32 v[54:55], s[14:15], v54, s12, v[50:51]
	v_mad_u64_u32 v[56:57], s[14:15], v56, s12, v[50:51]
	v_mad_u64_u32 v[58:59], s[14:15], v58, s12, v[50:51]
	v_mad_u64_u32 v[60:61], s[14:15], v60, s12, v[50:51]
; #define LAS __attribute__((address_space(3)))
; __device__ __forceinline__ unsigned cvt_pk_bf16(float lo, float hi) { f32x2_t v = {lo, hi}; bf16x2_t b = __builtin_convertvector(v, bf16x2_t); return __builtin_bit_cast(unsigned, b); }
; #define LDS_WAIT() asm volatile("s_waitcnt lgkmcnt(0)" ::: "memory")
; __device__ __forceinline__ void tr_item(const float* W, int ldw, int src_col, int nvalid, int k0, bf16_t* WT, int ldt, int dst_row, int dst_k, LAS float* scr, int lane) {
; #pragma unroll 8
;     for (int i = 0; i < 32; ++i) { const int kk = 2 * i + (lane >> 5), c = lane & 31; scr[kk * 33 + c] = (c < nvalid) ? W[(size_t)(k0 + kk) * ldw + src_col + c] : 0.f; }
;     LDS_WAIT();
;     const int c = lane & 7;
; #pragma unroll
;     for (int j = 0; j < 4; ++j) { const int n = (lane >> 3) + 8 * j; const LAS float* s = scr + (8 * c) * 33 + n;
;         u32x4 o; o.x = cvt_pk_bf16(s[0 * 33], s[1 * 33]); o.y = cvt_pk_bf16(s[2 * 33], s[3 * 33]); o.z = cvt_pk_bf16(s[4 * 33], s[5 * 33]); o.w = cvt_pk_bf16(s[6 * 33], s[7 * 33]);
;         *(u32x4*)(WT + (size_t)(dst_row + n) * ldt + dst_k + k0 + 8 * c) = o; }
;     LDS_WAIT();
	v_mad_u64_u32 v[62:63], s[14:15], v62, s12, v[50:51]
	v_mad_u64_u32 v[64:65], s[14:15], v64, s12, v[50:51]
	v_mad_u64_u32 v[78:79], s[14:15], v78, s12, v[50:51]
	v_mad_u64_u32 v[80:81], s[14:15], v80, s12, v[50:51]
	v_mad_u64_u32 v[82:83], s[14:15], v82, s12, v[50:51]
	v_mad_u64_u32 v[84:85], s[14:15], v84, s12, v[50:51]
	v_mad_u64_u32 v[86:87], s[14:15], v86, s12, v[50:51]
	v_mad_u64_u32 v[88:89], s[14:15], v88, s12, v[50:51]
	v_mad_u64_u32 v[90:91], s[14:15], v90, s12, v[50:51]
	v_mad_u64_u32 v[92:93], s[14:15], v92, s12, v[50:51]
	v_mad_u64_u32 v[94:95], s[14:15], v94, s12, v[50:51]
	global_load_dword v110, v[52:53], off
	global_load_dword v111, v[54:55], off
	global_load_dword v112, v[56:57], off
	global_load_dword v113, v[58:59], off
	global_load_dword v114, v[60:61], off
	global_load_dword v115, v[62:63], off
	global_load_dword v116, v[64:65], off
	global_load_dword v117, v[78:79], off
	global_load_dword v118, v[80:81], off
	global_load_dword v119, v[82:83], off
	global_load_dword v120, v[84:85], off
	global_load_dword v121, v[86:87], off
	global_load_dword v122, v[88:89], off
	global_load_dword v123, v[90:91], off
	global_load_dword v124, v[92:93], off
	global_load_dword v125, v[94:95], off
	s_add_i32 s6, s6, 16
	s_add_i32 s5, s5, 16
	s_add_i32 s7, s7, -16
	v_mad_u64_u32 v[52:53], s[14:15], v47, s8, v[6:7]
	s_cmp_lg_u32 s7, 0
	v_mad_u64_u32 v[54:55], s[14:15], v8, s8, v[6:7]
	v_mad_u64_u32 v[56:57], s[14:15], v97, s8, v[6:7]
	v_mad_u64_u32 v[58:59], s[14:15], v96, s8, v[6:7]
	v_mad_u64_u32 v[60:61], s[14:15], v99, s8, v[6:7]
	v_mad_u64_u32 v[62:63], s[14:15], v98, s8, v[6:7]
	v_mad_u64_u32 v[64:65], s[14:15], v101, s8, v[6:7]
	v_mad_u64_u32 v[78:79], s[14:15], v100, s8, v[6:7]
	v_mad_u64_u32 v[80:81], s[14:15], v103, s8, v[6:7]
	v_mad_u64_u32 v[82:83], s[14:15], v102, s8, v[6:7]
	v_mad_u64_u32 v[84:85], s[14:15], v105, s8, v[6:7]
	v_mad_u64_u32 v[86:87], s[14:15], v104, s8, v[6:7]
	v_mad_u64_u32 v[88:89], s[14:15], v107, s8, v[6:7]
	v_mad_u64_u32 v[90:91], s[14:15], v106, s8, v[6:7]
	v_mad_u64_u32 v[92:93], s[14:15], v109, s8, v[6:7]
	v_mad_u64_u32 v[94:95], s[14:15], v108, s8, v[6:7]
	s_waitcnt vmcnt(31)
	ds_write_b32 v148, v132
	s_waitcnt vmcnt(30)
	ds_write_b32 v149, v133
	s_waitcnt vmcnt(29)
	ds_write_b32 v150, v134
	s_waitcnt vmcnt(28)
	ds_write_b32 v151, v135
	s_waitcnt vmcnt(27)
	ds_write_b32 v152, v136
	s_waitcnt vmcnt(26)
	ds_write_b32 v153, v137
	s_waitcnt vmcnt(25)
	ds_write_b32 v154, v138
	s_waitcnt vmcnt(24)
	ds_write_b32 v155, v139
	s_waitcnt vmcnt(23)
	ds_write_b32 v156, v140
	s_waitcnt vmcnt(22)
	ds_write_b32 v157, v141
	s_waitcnt vmcnt(21)
	ds_write_b32 v158, v142
	s_waitcnt vmcnt(20)
	ds_write_b32 v159, v143
	s_waitcnt vmcnt(19)
	ds_write_b32 v160, v144
	s_waitcnt vmcnt(18)
	ds_write_b32 v161, v145
	s_waitcnt vmcnt(17)
	ds_write_b32 v162, v146
	s_waitcnt vmcnt(16)
	ds_write_b32 v163, v147
	s_waitcnt vmcnt(15)
	ds_write_b32 v52, v110
	s_waitcnt vmcnt(14)
	ds_write_b32 v54, v111
	s_waitcnt vmcnt(13)
	ds_write_b32 v56, v112
	s_waitcnt vmcnt(12)
	ds_write_b32 v58, v113
	s_waitcnt vmcnt(11)
	ds_write_b32 v60, v114
	s_waitcnt vmcnt(10)
	ds_write_b32 v62, v115
	s_waitcnt vmcnt(9)
	ds_write_b32 v64, v116
	s_waitcnt vmcnt(8)
	ds_write_b32 v78, v117
	s_waitcnt vmcnt(7)
	ds_write_b32 v80, v118
	s_waitcnt vmcnt(6)
	ds_write_b32 v82, v119
	s_waitcnt vmcnt(5)
	ds_write_b32 v84, v120
	s_waitcnt vmcnt(4)
	ds_write_b32 v86, v121
	s_waitcnt vmcnt(3)
	ds_write_b32 v88, v122
	s_waitcnt vmcnt(2)
	ds_write_b32 v90, v123
	s_waitcnt vmcnt(1)
	ds_write_b32 v92, v124
	s_waitcnt vmcnt(0)
	ds_write_b32 v94, v125
	s_waitcnt lgkmcnt(0)
	ds_read2_b32 v[54:55], v5 offset0:33 offset1:41
	ds_read2_b32 v[56:57], v5 offset1:8
	ds_read2_b32 v[58:59], v5 offset0:66 offset1:74
	ds_read2_b32 v[60:61], v5 offset0:99 offset1:107
	ds_read2_b32 v[62:63], v5 offset0:132 offset1:140
	ds_read2_b32 v[64:65], v5 offset0:165 offset1:173
	ds_read2_b32 v[78:79], v5 offset0:198 offset1:206
	ds_read2_b32 v[80:81], v5 offset0:231 offset1:239
	s_and_b32 s3, 0xffff, s3
	s_and_b32 s2, 0xffff, s2
	s_lshl_b32 s24, s2, 1
	v_or_b32_e32 v8, s3, v3
	v_lshl_add_u64 v[82:83], v[24:25], 0, s[24:25]
	v_lshlrev_b32_e32 v8, 11, v8
	s_waitcnt lgkmcnt(6)
	v_cvt_pk_bf16_f32 v50, v56, v54
	s_waitcnt lgkmcnt(4)
	v_cvt_pk_bf16_f32 v51, v58, v60
	s_waitcnt lgkmcnt(2)
	v_cvt_pk_bf16_f32 v52, v62, v64
	s_waitcnt lgkmcnt(0)
	v_cvt_pk_bf16_f32 v53, v78, v80
	v_lshl_add_u64 v[84:85], v[82:83], 0, v[8:9]
	global_store_dwordx4 v[84:85], v[50:53], off
	v_or_b32_e32 v8, s3, v7
	v_lshlrev_b32_e32 v8, 11, v8
	v_cvt_pk_bf16_f32 v50, v57, v55
	v_cvt_pk_bf16_f32 v51, v59, v61
	v_cvt_pk_bf16_f32 v52, v63, v65
	v_cvt_pk_bf16_f32 v53, v79, v81
	ds_read2_b32 v[56:57], v5 offset0:49 offset1:57
	ds_read2_b32 v[58:59], v5 offset0:16 offset1:24
	ds_read2_b32 v[60:61], v5 offset0:82 offset1:90
	ds_read2_b32 v[62:63], v5 offset0:115 offset1:123
	ds_read2_b32 v[64:65], v5 offset0:148 offset1:156
	ds_read2_b32 v[78:79], v5 offset0:181 offset1:189
	ds_read2_b32 v[80:81], v5 offset0:214 offset1:222
	ds_read2_b32 v[84:85], v5 offset0:247 offset1:255
	v_lshl_add_u64 v[54:55], v[82:83], 0, v[8:9]
	v_or_b32_e32 v8, s3, v68
	v_lshlrev_b32_e32 v8, 11, v8
	global_store_dwordx4 v[54:55], v[50:53], off
	v_lshl_add_u64 v[54:55], v[82:83], 0, v[8:9]
	v_or_b32_e32 v8, s3, v69
	s_waitcnt lgkmcnt(6)
	v_cvt_pk_bf16_f32 v50, v58, v56
	s_waitcnt lgkmcnt(4)
	v_cvt_pk_bf16_f32 v51, v60, v62
	s_waitcnt lgkmcnt(2)
	v_cvt_pk_bf16_f32 v52, v64, v78
	s_waitcnt lgkmcnt(0)
	v_cvt_pk_bf16_f32 v53, v80, v84
	v_lshlrev_b32_e32 v8, 11, v8
	global_store_dwordx4 v[54:55], v[50:53], off
	v_lshl_add_u64 v[54:55], v[82:83], 0, v[8:9]
	s_nop 0
	v_cvt_pk_bf16_f32 v50, v59, v57
	v_cvt_pk_bf16_f32 v51, v61, v63
	v_cvt_pk_bf16_f32 v52, v65, v79
	v_cvt_pk_bf16_f32 v53, v81, v85
	global_store_dwordx4 v[54:55], v[50:53], off
	s_waitcnt lgkmcnt(0)

; __device__ __forceinline__ void tr_item(const float* W, int ldw, int src_col, int nvalid, int k0, bf16_t* WT, int ldt, int dst_row, int dst_k, LAS float* scr, int lane) {
; #pragma unroll 8
;     for (int i = 0; i < 32; ++i) { const int kk = 2 * i + (lane >> 5), c = lane & 31; scr[kk * 33 + c] = (c < nvalid) ? W[(size_t)(k0 + kk) * ldw + src_col + c] : 0.f; }
.LBB0_100:
	s_lshl_b32 s14, s3, 1
	s_lshl_b32 s15, s6, 1
	v_or_b32_e32 v8, s14, v1
	v_or_b32_e32 v47, s15, v2
	s_add_i32 s16, s14, 4
	s_add_i32 s17, s15, 4
	s_add_i32 s18, s14, 8
	s_add_i32 s19, s15, 8
	s_add_i32 s23, s14, 12
	s_add_i32 s24, s15, 12
	s_add_i32 s26, s14, 16
	s_add_i32 s27, s15, 16
	s_add_i32 s28, s14, 20
	s_add_i32 s29, s15, 20
	s_add_i32 s30, s14, 24
	s_add_i32 s31, s15, 24
	s_add_i32 s14, s14, 28
	s_add_i32 s15, s15, 28
	v_add_u32_e32 v54, s4, v47
	v_or_b32_e32 v96, s16, v1
	v_or_b32_e32 v97, s17, v2
	v_or_b32_e32 v98, s18, v1
	v_or_b32_e32 v99, s19, v2
	v_or_b32_e32 v100, s23, v1
	v_or_b32_e32 v101, s24, v2
	v_or_b32_e32 v102, s26, v1
	v_or_b32_e32 v103, s27, v2
	v_or_b32_e32 v104, s28, v1
	v_or_b32_e32 v105, s29, v2
	v_or_b32_e32 v106, s30, v1
	v_or_b32_e32 v107, s31, v2
	v_or_b32_e32 v108, s14, v1
	v_or_b32_e32 v109, s15, v2
	v_add_u32_e32 v52, s5, v8
	v_ashrrev_i32_e32 v55, 31, v54
	v_add_u32_e32 v56, s5, v96
	v_add_u32_e32 v58, s4, v97
	v_add_u32_e32 v60, s5, v98
	v_add_u32_e32 v62, s4, v99
	v_add_u32_e32 v64, s5, v100
	v_add_u32_e32 v78, s4, v101
	v_add_u32_e32 v80, s5, v102
	v_add_u32_e32 v82, s4, v103
	v_add_u32_e32 v84, s5, v104
	v_add_u32_e32 v86, s4, v105
	v_add_u32_e32 v88, s5, v106
	v_add_u32_e32 v90, s4, v107
	v_add_u32_e32 v92, s5, v108
	v_add_u32_e32 v94, s4, v109
	v_ashrrev_i32_e32 v53, 31, v52
	v_lshlrev_b64 v[54:55], 12, v[54:55]
	v_ashrrev_i32_e32 v59, 31, v58
	v_ashrrev_i32_e32 v57, 31, v56
	v_ashrrev_i32_e32 v63, 31, v62
	v_ashrrev_i32_e32 v61, 31, v60
	v_ashrrev_i32_e32 v79, 31, v78
	v_ashrrev_i32_e32 v65, 31, v64
	v_ashrrev_i32_e32 v83, 31, v82
	v_ashrrev_i32_e32 v81, 31, v80
	v_ashrrev_i32_e32 v87, 31, v86
	v_ashrrev_i32_e32 v85, 31, v84
	v_ashrrev_i32_e32 v91, 31, v90
	v_ashrrev_i32_e32 v89, 31, v88
	v_ashrrev_i32_e32 v95, 31, v94
	v_ashrrev_i32_e32 v93, 31, v92
	v_lshlrev_b64 v[52:53], 12, v[52:53]
	v_lshl_add_u64 v[54:55], v[50:51], 0, v[54:55]
	v_lshlrev_b64 v[56:57], 12, v[56:57]
	v_lshlrev_b64 v[58:59], 12, v[58:59]
	v_lshlrev_b64 v[60:61], 12, v[60:61]
	v_lshlrev_b64 v[62:63], 12, v[62:63]
	v_lshlrev_b64 v[64:65], 12, v[64:65]
	v_lshlrev_b64 v[78:79], 12, v[78:79]
	v_lshlrev_b64 v[80:81], 12, v[80:81]
	v_lshlrev_b64 v[82:83], 12, v[82:83]
	v_lshlrev_b64 v[84:85], 12, v[84:85]
	v_lshlrev_b64 v[86:87], 12, v[86:87]
	v_lshlrev_b64 v[88:89], 12, v[88:89]
	v_lshlrev_b64 v[90:91], 12, v[90:91]
	v_lshlrev_b64 v[92:93], 12, v[92:93]
	v_lshlrev_b64 v[94:95], 12, v[94:95]
	v_lshl_add_u64 v[52:53], v[50:51], 0, v[52:53]
	v_lshl_add_u64 v[58:59], v[50:51], 0, v[58:59]
	v_lshl_add_u64 v[56:57], v[50:51], 0, v[56:57]
	v_lshl_add_u64 v[62:63], v[50:51], 0, v[62:63]
	v_lshl_add_u64 v[60:61], v[50:51], 0, v[60:61]
	v_lshl_add_u64 v[78:79], v[50:51], 0, v[78:79]
	v_lshl_add_u64 v[64:65], v[50:51], 0, v[64:65]
	v_lshl_add_u64 v[82:83], v[50:51], 0, v[82:83]
	v_lshl_add_u64 v[80:81], v[50:51], 0, v[80:81]
	v_lshl_add_u64 v[86:87], v[50:51], 0, v[86:87]
	v_lshl_add_u64 v[84:85], v[50:51], 0, v[84:85]
	v_lshl_add_u64 v[90:91], v[50:51], 0, v[90:91]
	v_lshl_add_u64 v[88:89], v[50:51], 0, v[88:89]
	v_lshl_add_u64 v[94:95], v[50:51], 0, v[94:95]
	v_lshl_add_u64 v[92:93], v[50:51], 0, v[92:93]
	global_load_dword v132, v[54:55], off
	global_load_dword v133, v[52:53], off
	global_load_dword v134, v[58:59], off
	global_load_dword v135, v[56:57], off
	global_load_dword v136, v[62:63], off
	global_load_dword v137, v[60:61], off
	global_load_dword v138, v[78:79], off
	global_load_dword v139, v[64:65], off
	global_load_dword v140, v[82:83], off
	global_load_dword v141, v[80:81], off
	global_load_dword v142, v[86:87], off
	global_load_dword v143, v[84:85], off
	global_load_dword v144, v[90:91], off
	global_load_dword v145, v[88:89], off
	global_load_dword v146, v[94:95], off
	global_load_dword v147, v[92:93], off
	s_add_i32 s6, s6, 16
	s_add_i32 s3, s3, 16
	s_add_i32 s7, s7, -16
	v_mad_u64_u32 v[52:53], s[14:15], v47, s8, v[6:7]
	s_cmp_lg_u32 s7, 0
	v_mad_u64_u32 v[54:55], s[14:15], v8, s8, v[6:7]
	v_mad_u64_u32 v[56:57], s[14:15], v97, s8, v[6:7]
	v_mad_u64_u32 v[58:59], s[14:15], v96, s8, v[6:7]
	v_mad_u64_u32 v[60:61], s[14:15], v99, s8, v[6:7]
	v_mad_u64_u32 v[62:63], s[14:15], v98, s8, v[6:7]
	v_mad_u64_u32 v[64:65], s[14:15], v101, s8, v[6:7]
	v_mad_u64_u32 v[78:79], s[14:15], v100, s8, v[6:7]
	v_mad_u64_u32 v[80:81], s[14:15], v103, s8, v[6:7]
	v_mad_u64_u32 v[82:83], s[14:15], v102, s8, v[6:7]
	v_mad_u64_u32 v[84:85], s[14:15], v105, s8, v[6:7]
	v_mad_u64_u32 v[86:87], s[14:15], v104, s8, v[6:7]
	v_mad_u64_u32 v[88:89], s[14:15], v107, s8, v[6:7]
	v_mad_u64_u32 v[90:91], s[14:15], v106, s8, v[6:7]
	v_mad_u64_u32 v[92:93], s[14:15], v109, s8, v[6:7]
	v_mad_u64_u32 v[94:95], s[14:15], v108, s8, v[6:7]
	v_mov_b32_e32 v148, v52
	v_mov_b32_e32 v149, v54
	v_mov_b32_e32 v150, v56
	v_mov_b32_e32 v151, v58
	v_mov_b32_e32 v152, v60
	v_mov_b32_e32 v153, v62
	v_mov_b32_e32 v154, v64
	v_mov_b32_e32 v155, v78
	v_mov_b32_e32 v156, v80
	v_mov_b32_e32 v157, v82
	v_mov_b32_e32 v158, v84
	v_mov_b32_e32 v159, v86
	v_mov_b32_e32 v160, v88
	v_mov_b32_e32 v161, v90
	v_mov_b32_e32 v162, v92
	v_mov_b32_e32 v163, v94
	s_lshl_b32 s14, s3, 1
	s_lshl_b32 s15, s6, 1
	v_or_b32_e32 v8, s14, v1
	v_or_b32_e32 v47, s15, v2
	s_add_i32 s16, s14, 4
	s_add_i32 s17, s15, 4
	s_add_i32 s18, s14, 8
	s_add_i32 s19, s15, 8
	s_add_i32 s23, s14, 12
	s_add_i32 s24, s15, 12
	s_add_i32 s26, s14, 16
	s_add_i32 s27, s15, 16
	s_add_i32 s28, s14, 20
	s_add_i32 s29, s15, 20
	s_add_i32 s30, s14, 24
	s_add_i32 s31, s15, 24
	s_add_i32 s14, s14, 28
	s_add_i32 s15, s15, 28
	v_add_u32_e32 v54, s4, v47
	v_or_b32_e32 v96, s16, v1
	v_or_b32_e32 v97, s17, v2
	v_or_b32_e32 v98, s18, v1
; #define LAS __attribute__((address_space(3)))
; #define LDS_WAIT() asm volatile("s_waitcnt lgkmcnt(0)" ::: "memory")
; __device__ __forceinline__ void tr_item(const float* W, int ldw, int src_col, int nvalid, int k0, bf16_t* WT, int ldt, int dst_row, int dst_k, LAS float* scr, int lane) {
; #pragma unroll 8
;     for (int i = 0; i < 32; ++i) { const int kk = 2 * i + (lane >> 5), c = lane & 31; scr[kk * 33 + c] = (c < nvalid) ? W[(size_t)(k0 + kk) * ldw + src_col + c] : 0.f; }
;     LDS_WAIT();
	v_or_b32_e32 v99, s19, v2
	v_or_b32_e32 v100, s23, v1
	v_or_b32_e32 v101, s24, v2
	v_or_b32_e32 v102, s26, v1
	v_or_b32_e32 v103, s27, v2
	v_or_b32_e32 v104, s28, v1
	v_or_b32_e32 v105, s29, v2
	v_or_b32_e32 v106, s30, v1
	v_or_b32_e32 v107, s31, v2
	v_or_b32_e32 v108, s14, v1
	v_or_b32_e32 v109, s15, v2
	v_add_u32_e32 v52, s5, v8
	v_ashrrev_i32_e32 v55, 31, v54
	v_add_u32_e32 v56, s5, v96
	v_add_u32_e32 v58, s4, v97
	v_add_u32_e32 v60, s5, v98
	v_add_u32_e32 v62, s4, v99
	v_add_u32_e32 v64, s5, v100
	v_add_u32_e32 v78, s4, v101
	v_add_u32_e32 v80, s5, v102
	v_add_u32_e32 v82, s4, v103
	v_add_u32_e32 v84, s5, v104
	v_add_u32_e32 v86, s4, v105
	v_add_u32_e32 v88, s5, v106
	v_add_u32_e32 v90, s4, v107
	v_add_u32_e32 v92, s5, v108
	v_add_u32_e32 v94, s4, v109
	v_ashrrev_i32_e32 v53, 31, v52
	v_lshlrev_b64 v[54:55], 12, v[54:55]
	v_ashrrev_i32_e32 v59, 31, v58
	v_ashrrev_i32_e32 v57, 31, v56
	v_ashrrev_i32_e32 v63, 31, v62
	v_ashrrev_i32_e32 v61, 31, v60
	v_ashrrev_i32_e32 v79, 31, v78
	v_ashrrev_i32_e32 v65, 31, v64
	v_ashrrev_i32_e32 v83, 31, v82
	v_ashrrev_i32_e32 v81, 31, v80
	v_ashrrev_i32_e32 v87, 31, v86
	v_ashrrev_i32_e32 v85, 31, v84
	v_ashrrev_i32_e32 v91, 31, v90
	v_ashrrev_i32_e32 v89, 31, v88
	v_ashrrev_i32_e32 v95, 31, v94
	v_ashrrev_i32_e32 v93, 31, v92
	v_lshlrev_b64 v[52:53], 12, v[52:53]
	v_lshl_add_u64 v[54:55], v[50:51], 0, v[54:55]
	v_lshlrev_b64 v[56:57], 12, v[56:57]
	v_lshlrev_b64 v[58:59], 12, v[58:59]
	v_lshlrev_b64 v[60:61], 12, v[60:61]
	v_lshlrev_b64 v[62:63], 12, v[62:63]
	v_lshlrev_b64 v[64:65], 12, v[64:65]
	v_lshlrev_b64 v[78:79], 12, v[78:79]
	v_lshlrev_b64 v[80:81], 12, v[80:81]
	v_lshlrev_b64 v[82:83], 12, v[82:83]
	v_lshlrev_b64 v[84:85], 12, v[84:85]
	v_lshlrev_b64 v[86:87], 12, v[86:87]
	v_lshlrev_b64 v[88:89], 12, v[88:89]
	v_lshlrev_b64 v[90:91], 12, v[90:91]
	v_lshlrev_b64 v[92:93], 12, v[92:93]
	v_lshlrev_b64 v[94:95], 12, v[94:95]
	v_lshl_add_u64 v[52:53], v[50:51], 0, v[52:53]
	v_lshl_add_u64 v[58:59], v[50:51], 0, v[58:59]
	v_lshl_add_u64 v[56:57], v[50:51], 0, v[56:57]
	v_lshl_add_u64 v[62:63], v[50:51], 0, v[62:63]
	v_lshl_add_u64 v[60:61], v[50:51], 0, v[60:61]
	v_lshl_add_u64 v[78:79], v[50:51], 0, v[78:79]
	v_lshl_add_u64 v[64:65], v[50:51], 0, v[64:65]
	v_lshl_add_u64 v[82:83], v[50:51], 0, v[82:83]
	v_lshl_add_u64 v[80:81], v[50:51], 0, v[80:81]
	v_lshl_add_u64 v[86:87], v[50:51], 0, v[86:87]
	v_lshl_add_u64 v[84:85], v[50:51], 0, v[84:85]
	v_lshl_add_u64 v[90:91], v[50:51], 0, v[90:91]
	v_lshl_add_u64 v[88:89], v[50:51], 0, v[88:89]
	v_lshl_add_u64 v[94:95], v[50:51], 0, v[94:95]
	v_lshl_add_u64 v[92:93], v[50:51], 0, v[92:93]
	global_load_dword v110, v[54:55], off
	global_load_dword v111, v[52:53], off
	global_load_dword v112, v[58:59], off
	global_load_dword v113, v[56:57], off
	global_load_dword v114, v[62:63], off
	global_load_dword v115, v[60:61], off
	global_load_dword v116, v[78:79], off
	global_load_dword v117, v[64:65], off
	global_load_dword v118, v[82:83], off
	global_load_dword v119, v[80:81], off
	global_load_dword v120, v[86:87], off
	global_load_dword v121, v[84:85], off
	global_load_dword v122, v[90:91], off
	global_load_dword v123, v[88:89], off
	global_load_dword v124, v[94:95], off
	global_load_dword v125, v[92:93], off
	s_add_i32 s6, s6, 16
	s_add_i32 s3, s3, 16
	s_add_i32 s7, s7, -16
	v_mad_u64_u32 v[52:53], s[14:15], v47, s8, v[6:7]
	s_cmp_lg_u32 s7, 0
	v_mad_u64_u32 v[54:55], s[14:15], v8, s8, v[6:7]
	v_mad_u64_u32 v[56:57], s[14:15], v97, s8, v[6:7]
	v_mad_u64_u32 v[58:59], s[14:15], v96, s8, v[6:7]
	v_mad_u64_u32 v[60:61], s[14:15], v99, s8, v[6:7]
	v_mad_u64_u32 v[62:63], s[14:15], v98, s8, v[6:7]
	v_mad_u64_u32 v[64:65], s[14:15], v101, s8, v[6:7]
	v_mad_u64_u32 v[78:79], s[14:15], v100, s8, v[6:7]
	v_mad_u64_u32 v[80:81], s[14:15], v103, s8, v[6:7]
	v_mad_u64_u32 v[82:83], s[14:15], v102, s8, v[6:7]
	v_mad_u64_u32 v[84:85], s[14:15], v105, s8, v[6:7]
	v_mad_u64_u32 v[86:87], s[14:15], v104, s8, v[6:7]
	v_mad_u64_u32 v[88:89], s[14:15], v107, s8, v[6:7]
	v_mad_u64_u32 v[90:91], s[14:15], v106, s8, v[6:7]
	v_mad_u64_u32 v[92:93], s[14:15], v109, s8, v[6:7]
	v_mad_u64_u32 v[94:95], s[14:15], v108, s8, v[6:7]
	s_waitcnt vmcnt(31)
; #define LAS __attribute__((address_space(3)))
; __device__ __forceinline__ unsigned cvt_pk_bf16(float lo, float hi) { f32x2_t v = {lo, hi}; bf16x2_t b = __builtin_convertvector(v, bf16x2_t); return __builtin_bit_cast(unsigned, b); }
; #define LDS_WAIT() asm volatile("s_waitcnt lgkmcnt(0)" ::: "memory")
; __device__ __forceinline__ void tr_item(const float* W, int ldw, int src_col, int nvalid, int k0, bf16_t* WT, int ldt, int dst_row, int dst_k, LAS float* scr, int lane) {
; #pragma unroll 8
;     for (int i = 0; i < 32; ++i) { const int kk = 2 * i + (lane >> 5), c = lane & 31; scr[kk * 33 + c] = (c < nvalid) ? W[(size_t)(k0 + kk) * ldw + src_col + c] : 0.f; }
;     LDS_WAIT();
;     const int c = lane & 7;
; #pragma unroll
;     for (int j = 0; j < 4; ++j) { const int n = (lane >> 3) + 8 * j; const LAS float* s = scr + (8 * c) * 33 + n;
;         u32x4 o; o.x = cvt_pk_bf16(s[0 * 33], s[1 * 33]); o.y = cvt_pk_bf16(s[2 * 33], s[3 * 33]); o.z = cvt_pk_bf16(s[4 * 33], s[5 * 33]); o.w = cvt_pk_bf16(s[6 * 33], s[7 * 33]);
;         *(u32x4*)(WT + (size_t)(dst_row + n) * ldt + dst_k + k0 + 8 * c) = o; }
;     LDS_WAIT();
; }
	ds_write_b32 v148, v132
	s_waitcnt vmcnt(30)
	ds_write_b32 v149, v133
	s_waitcnt vmcnt(29)
	ds_write_b32 v150, v134
	s_waitcnt vmcnt(28)
	ds_write_b32 v151, v135
	s_waitcnt vmcnt(27)
	ds_write_b32 v152, v136
	s_waitcnt vmcnt(26)
	ds_write_b32 v153, v137
	s_waitcnt vmcnt(25)
	ds_write_b32 v154, v138
	s_waitcnt vmcnt(24)
	ds_write_b32 v155, v139
	s_waitcnt vmcnt(23)
	ds_write_b32 v156, v140
	s_waitcnt vmcnt(22)
	ds_write_b32 v157, v141
	s_waitcnt vmcnt(21)
	ds_write_b32 v158, v142
	s_waitcnt vmcnt(20)
	ds_write_b32 v159, v143
	s_waitcnt vmcnt(19)
	ds_write_b32 v160, v144
	s_waitcnt vmcnt(18)
	ds_write_b32 v161, v145
	s_waitcnt vmcnt(17)
	ds_write_b32 v162, v146
	s_waitcnt vmcnt(16)
	ds_write_b32 v163, v147
	s_waitcnt vmcnt(15)
	ds_write_b32 v52, v110
	s_waitcnt vmcnt(14)
	ds_write_b32 v54, v111
	s_waitcnt vmcnt(13)
	ds_write_b32 v56, v112
	s_waitcnt vmcnt(12)
	ds_write_b32 v58, v113
	s_waitcnt vmcnt(11)
	ds_write_b32 v60, v114
	s_waitcnt vmcnt(10)
	ds_write_b32 v62, v115
	s_waitcnt vmcnt(9)
	ds_write_b32 v64, v116
	s_waitcnt vmcnt(8)
	ds_write_b32 v78, v117
	s_waitcnt vmcnt(7)
	ds_write_b32 v80, v118
	s_waitcnt vmcnt(6)
	ds_write_b32 v82, v119
	s_waitcnt vmcnt(5)
	ds_write_b32 v84, v120
	s_waitcnt vmcnt(4)
	ds_write_b32 v86, v121
	s_waitcnt vmcnt(3)
	ds_write_b32 v88, v122
	s_waitcnt vmcnt(2)
	ds_write_b32 v90, v123
	s_waitcnt vmcnt(1)
	ds_write_b32 v92, v124
	s_waitcnt vmcnt(0)
	ds_write_b32 v94, v125
	s_waitcnt lgkmcnt(0)
	ds_read2_b32 v[54:55], v5 offset0:33 offset1:41
	ds_read2_b32 v[56:57], v5 offset1:8
	ds_read2_b32 v[58:59], v5 offset0:66 offset1:74
	ds_read2_b32 v[60:61], v5 offset0:99 offset1:107
	ds_read2_b32 v[62:63], v5 offset0:132 offset1:140
	ds_read2_b32 v[64:65], v5 offset0:165 offset1:173
	ds_read2_b32 v[78:79], v5 offset0:198 offset1:206
	ds_read2_b32 v[80:81], v5 offset0:231 offset1:239
	s_mov_b32 s5, s25
	v_or_b32_e32 v8, s2, v3
	v_lshl_add_u64 v[82:83], s[4:5], 1, v[48:49]
	v_mul_u32_u24_e32 v8, 0x1600, v8
	s_waitcnt lgkmcnt(6)
	v_cvt_pk_bf16_f32 v50, v56, v54
	s_waitcnt lgkmcnt(4)
	v_cvt_pk_bf16_f32 v51, v58, v60
	s_waitcnt lgkmcnt(2)
	v_cvt_pk_bf16_f32 v52, v62, v64
	s_waitcnt lgkmcnt(0)
	v_cvt_pk_bf16_f32 v53, v78, v80
	v_lshl_add_u64 v[84:85], v[82:83], 0, v[8:9]
	global_store_dwordx4 v[84:85], v[50:53], off
	v_or_b32_e32 v8, s2, v7
	v_mul_u32_u24_e32 v8, 0x1600, v8
	v_cvt_pk_bf16_f32 v50, v57, v55
	v_cvt_pk_bf16_f32 v51, v59, v61
	v_cvt_pk_bf16_f32 v52, v63, v65
	v_cvt_pk_bf16_f32 v53, v79, v81
	ds_read2_b32 v[56:57], v5 offset0:16 offset1:24
	ds_read2_b32 v[58:59], v5 offset0:49 offset1:57
	ds_read2_b32 v[60:61], v5 offset0:82 offset1:90
	ds_read2_b32 v[62:63], v5 offset0:115 offset1:123
	ds_read2_b32 v[64:65], v5 offset0:148 offset1:156
	ds_read2_b32 v[78:79], v5 offset0:181 offset1:189
	ds_read2_b32 v[80:81], v5 offset0:214 offset1:222
	ds_read2_b32 v[84:85], v5 offset0:247 offset1:255
	v_lshl_add_u64 v[54:55], v[82:83], 0, v[8:9]
	v_or_b32_e32 v8, s2, v68
	v_mul_u32_u24_e32 v8, 0x1600, v8
	global_store_dwordx4 v[54:55], v[50:53], off
	v_lshl_add_u64 v[54:55], v[82:83], 0, v[8:9]
	v_or_b32_e32 v8, s2, v69
	s_waitcnt lgkmcnt(6)
	v_cvt_pk_bf16_f32 v50, v56, v58
	s_waitcnt lgkmcnt(4)
	v_cvt_pk_bf16_f32 v51, v60, v62
	s_waitcnt lgkmcnt(2)
	v_cvt_pk_bf16_f32 v52, v64, v78
	s_waitcnt lgkmcnt(0)
	v_cvt_pk_bf16_f32 v53, v80, v84
	v_mul_u32_u24_e32 v8, 0x1600, v8
	global_store_dwordx4 v[54:55], v[50:53], off
	v_lshl_add_u64 v[54:55], v[82:83], 0, v[8:9]
	s_nop 0
	v_cvt_pk_bf16_f32 v50, v57, v59
	v_cvt_pk_bf16_f32 v51, v61, v63
	v_cvt_pk_bf16_f32 v52, v65, v79
	v_cvt_pk_bf16_f32 v53, v81, v85
	global_store_dwordx4 v[54:55], v[50:53], off
	s_waitcnt lgkmcnt(0)

; #define LAS __attribute__((address_space(3)))
; #define LDS_WAIT() asm volatile("s_waitcnt lgkmcnt(0)" ::: "memory")
; __device__ __forceinline__ void tr_item(const float* W, int ldw, int src_col, int nvalid, int k0, bf16_t* WT, int ldt, int dst_row, int dst_k, LAS float* scr, int lane) {
; #pragma unroll 8
;     for (int i = 0; i < 32; ++i) { const int kk = 2 * i + (lane >> 5), c = lane & 31; scr[kk * 33 + c] = (c < nvalid) ? W[(size_t)(k0 + kk) * ldw + src_col + c] : 0.f; }
;     LDS_WAIT();
.LBB0_104:
	s_lshl_b32 s14, s5, 1
	s_lshl_b32 s15, s6, 1
	v_or_b32_e32 v8, s14, v1
	v_or_b32_e32 v47, s15, v2
	s_add_i32 s16, s14, 4
	s_add_i32 s17, s15, 4
	s_add_i32 s18, s14, 8
	s_add_i32 s19, s15, 8
	s_add_i32 s23, s14, 12
	s_add_i32 s24, s15, 12
	s_add_i32 s26, s14, 16
	s_add_i32 s27, s15, 16
	s_add_i32 s28, s14, 20
	s_add_i32 s29, s15, 20
	s_add_i32 s30, s14, 24
	s_add_i32 s31, s15, 24
	s_add_i32 s14, s14, 28
	s_add_i32 s15, s15, 28
	v_add_u32_e32 v52, s4, v47
	v_or_b32_e32 v96, s16, v1
	v_or_b32_e32 v97, s17, v2
	v_or_b32_e32 v98, s18, v1
	v_or_b32_e32 v99, s19, v2
	v_or_b32_e32 v100, s23, v1
	v_or_b32_e32 v101, s24, v2
	v_or_b32_e32 v102, s26, v1
	v_or_b32_e32 v103, s27, v2
	v_or_b32_e32 v104, s28, v1
	v_or_b32_e32 v105, s29, v2
	v_or_b32_e32 v106, s30, v1
	v_or_b32_e32 v107, s31, v2
	v_or_b32_e32 v108, s14, v1
	v_or_b32_e32 v109, s15, v2
	v_add_u32_e32 v54, s3, v8
	v_mad_i64_i32 v[52:53], s[14:15], v52, s11, v[50:51]
	v_add_u32_e32 v58, s3, v96
	v_add_u32_e32 v56, s4, v97
	v_add_u32_e32 v62, s3, v98
	v_add_u32_e32 v60, s4, v99
	v_add_u32_e32 v78, s3, v100
	v_add_u32_e32 v64, s4, v101
	v_add_u32_e32 v82, s3, v102
	v_add_u32_e32 v80, s4, v103
	v_add_u32_e32 v86, s3, v104
	v_add_u32_e32 v84, s4, v105
	v_add_u32_e32 v90, s3, v106
	v_add_u32_e32 v88, s4, v107
	v_add_u32_e32 v94, s3, v108
	v_add_u32_e32 v92, s4, v109
	v_mad_i64_i32 v[54:55], s[14:15], v54, s11, v[50:51]
	v_mad_i64_i32 v[56:57], s[14:15], v56, s11, v[50:51]
	v_mad_i64_i32 v[58:59], s[14:15], v58, s11, v[50:51]
	v_mad_i64_i32 v[60:61], s[14:15], v60, s11, v[50:51]
	v_mad_i64_i32 v[62:63], s[14:15], v62, s11, v[50:51]
	v_mad_i64_i32 v[64:65], s[14:15], v64, s11, v[50:51]
	v_mad_i64_i32 v[78:79], s[14:15], v78, s11, v[50:51]
	v_mad_i64_i32 v[80:81], s[14:15], v80, s11, v[50:51]
	v_mad_i64_i32 v[82:83], s[14:15], v82, s11, v[50:51]
	v_mad_i64_i32 v[84:85], s[14:15], v84, s11, v[50:51]
	v_mad_i64_i32 v[86:87], s[14:15], v86, s11, v[50:51]
	v_mad_i64_i32 v[88:89], s[14:15], v88, s11, v[50:51]
	v_mad_i64_i32 v[90:91], s[14:15], v90, s11, v[50:51]
	v_mad_i64_i32 v[92:93], s[14:15], v92, s11, v[50:51]
	v_mad_i64_i32 v[94:95], s[14:15], v94, s11, v[50:51]
	global_load_dword v132, v[52:53], off
	global_load_dword v133, v[54:55], off
	global_load_dword v134, v[56:57], off
	global_load_dword v135, v[58:59], off
	global_load_dword v136, v[60:61], off
	global_load_dword v137, v[62:63], off
	global_load_dword v138, v[64:65], off
	global_load_dword v139, v[78:79], off
	global_load_dword v140, v[80:81], off
	global_load_dword v141, v[82:83], off
	global_load_dword v142, v[84:85], off
	global_load_dword v143, v[86:87], off
	global_load_dword v144, v[88:89], off
	global_load_dword v145, v[90:91], off
	global_load_dword v146, v[92:93], off
	global_load_dword v147, v[94:95], off
	s_add_i32 s6, s6, 16
	s_add_i32 s5, s5, 16
	s_add_i32 s7, s7, -16
	v_mad_u64_u32 v[52:53], s[14:15], v47, s8, v[6:7]
	s_cmp_lg_u32 s7, 0
	v_mad_u64_u32 v[54:55], s[14:15], v8, s8, v[6:7]
	v_mad_u64_u32 v[56:57], s[14:15], v97, s8, v[6:7]
	v_mad_u64_u32 v[58:59], s[14:15], v96, s8, v[6:7]
	v_mad_u64_u32 v[60:61], s[14:15], v99, s8, v[6:7]
	v_mad_u64_u32 v[62:63], s[14:15], v98, s8, v[6:7]
	v_mad_u64_u32 v[64:65], s[14:15], v101, s8, v[6:7]
	v_mad_u64_u32 v[78:79], s[14:15], v100, s8, v[6:7]
	v_mad_u64_u32 v[80:81], s[14:15], v103, s8, v[6:7]
	v_mad_u64_u32 v[82:83], s[14:15], v102, s8, v[6:7]
	v_mad_u64_u32 v[84:85], s[14:15], v105, s8, v[6:7]
	v_mad_u64_u32 v[86:87], s[14:15], v104, s8, v[6:7]
	v_mad_u64_u32 v[88:89], s[14:15], v107, s8, v[6:7]
	v_mad_u64_u32 v[90:91], s[14:15], v106, s8, v[6:7]
	v_mad_u64_u32 v[92:93], s[14:15], v109, s8, v[6:7]
	v_mad_u64_u32 v[94:95], s[14:15], v108, s8, v[6:7]
	v_mov_b32_e32 v148, v52
	v_mov_b32_e32 v149, v54
	v_mov_b32_e32 v150, v56
	v_mov_b32_e32 v151, v58
	v_mov_b32_e32 v152, v60
	v_mov_b32_e32 v153, v62
	v_mov_b32_e32 v154, v64
	v_mov_b32_e32 v155, v78
	v_mov_b32_e32 v156, v80
	v_mov_b32_e32 v157, v82
	v_mov_b32_e32 v158, v84
	v_mov_b32_e32 v159, v86
	v_mov_b32_e32 v160, v88
	v_mov_b32_e32 v161, v90
	v_mov_b32_e32 v162, v92
	v_mov_b32_e32 v163, v94
	s_lshl_b32 s14, s5, 1
	s_lshl_b32 s15, s6, 1
	v_or_b32_e32 v8, s14, v1
	v_or_b32_e32 v47, s15, v2
	s_add_i32 s16, s14, 4
	s_add_i32 s17, s15, 4
	s_add_i32 s18, s14, 8
	s_add_i32 s19, s15, 8
	s_add_i32 s23, s14, 12
	s_add_i32 s24, s15, 12
	s_add_i32 s26, s14, 16
	s_add_i32 s27, s15, 16
	s_add_i32 s28, s14, 20
	s_add_i32 s29, s15, 20
	s_add_i32 s30, s14, 24
	s_add_i32 s31, s15, 24
	s_add_i32 s14, s14, 28
	s_add_i32 s15, s15, 28
	v_add_u32_e32 v52, s4, v47
	v_or_b32_e32 v96, s16, v1
	v_or_b32_e32 v97, s17, v2
	v_or_b32_e32 v98, s18, v1
	v_or_b32_e32 v99, s19, v2
	v_or_b32_e32 v100, s23, v1
	v_or_b32_e32 v101, s24, v2
	v_or_b32_e32 v102, s26, v1
	v_or_b32_e32 v103, s27, v2
	v_or_b32_e32 v104, s28, v1
	v_or_b32_e32 v105, s29, v2
	v_or_b32_e32 v106, s30, v1
	v_or_b32_e32 v107, s31, v2
	v_or_b32_e32 v108, s14, v1
	v_or_b32_e32 v109, s15, v2
	v_add_u32_e32 v54, s3, v8
	v_mad_i64_i32 v[52:53], s[14:15], v52, s11, v[50:51]
	v_add_u32_e32 v58, s3, v96
	v_add_u32_e32 v56, s4, v97
	v_add_u32_e32 v62, s3, v98
	v_add_u32_e32 v60, s4, v99
	v_add_u32_e32 v78, s3, v100
	v_add_u32_e32 v64, s4, v101
	v_add_u32_e32 v82, s3, v102
	v_add_u32_e32 v80, s4, v103
	v_add_u32_e32 v86, s3, v104
	v_add_u32_e32 v84, s4, v105
	v_add_u32_e32 v90, s3, v106
	v_add_u32_e32 v88, s4, v107
	v_add_u32_e32 v94, s3, v108
	v_add_u32_e32 v92, s4, v109
	v_mad_i64_i32 v[54:55], s[14:15], v54, s11, v[50:51]
	v_mad_i64_i32 v[56:57], s[14:15], v56, s11, v[50:51]
	v_mad_i64_i32 v[58:59], s[14:15], v58, s11, v[50:51]
	v_mad_i64_i32 v[60:61], s[14:15], v60, s11, v[50:51]
; #define LAS __attribute__((address_space(3)))
; __device__ __forceinline__ unsigned cvt_pk_bf16(float lo, float hi) { f32x2_t v = {lo, hi}; bf16x2_t b = __builtin_convertvector(v, bf16x2_t); return __builtin_bit_cast(unsigned, b); }
; #define LDS_WAIT() asm volatile("s_waitcnt lgkmcnt(0)" ::: "memory")
; __device__ __forceinline__ void tr_item(const float* W, int ldw, int src_col, int nvalid, int k0, bf16_t* WT, int ldt, int dst_row, int dst_k, LAS float* scr, int lane) {
; #pragma unroll 8
;     for (int i = 0; i < 32; ++i) { const int kk = 2 * i + (lane >> 5), c = lane & 31; scr[kk * 33 + c] = (c < nvalid) ? W[(size_t)(k0 + kk) * ldw + src_col + c] : 0.f; }
;     LDS_WAIT();
;     const int c = lane & 7;
; #pragma unroll
;     for (int j = 0; j < 4; ++j) { const int n = (lane >> 3) + 8 * j; const LAS float* s = scr + (8 * c) * 33 + n;
;         u32x4 o; o.x = cvt_pk_bf16(s[0 * 33], s[1 * 33]); o.y = cvt_pk_bf16(s[2 * 33], s[3 * 33]); o.z = cvt_pk_bf16(s[4 * 33], s[5 * 33]); o.w = cvt_pk_bf16(s[6 * 33], s[7 * 33]);
;         *(u32x4*)(WT + (size_t)(dst_row + n) * ldt + dst_k + k0 + 8 * c) = o; }
;     LDS_WAIT();
; }
	v_mad_i64_i32 v[62:63], s[14:15], v62, s11, v[50:51]
	v_mad_i64_i32 v[64:65], s[14:15], v64, s11, v[50:51]
	v_mad_i64_i32 v[78:79], s[14:15], v78, s11, v[50:51]
	v_mad_i64_i32 v[80:81], s[14:15], v80, s11, v[50:51]
	v_mad_i64_i32 v[82:83], s[14:15], v82, s11, v[50:51]
	v_mad_i64_i32 v[84:85], s[14:15], v84, s11, v[50:51]
	v_mad_i64_i32 v[86:87], s[14:15], v86, s11, v[50:51]
	v_mad_i64_i32 v[88:89], s[14:15], v88, s11, v[50:51]
	v_mad_i64_i32 v[90:91], s[14:15], v90, s11, v[50:51]
	v_mad_i64_i32 v[92:93], s[14:15], v92, s11, v[50:51]
	v_mad_i64_i32 v[94:95], s[14:15], v94, s11, v[50:51]
	global_load_dword v110, v[52:53], off
	global_load_dword v111, v[54:55], off
	global_load_dword v112, v[56:57], off
	global_load_dword v113, v[58:59], off
	global_load_dword v114, v[60:61], off
	global_load_dword v115, v[62:63], off
	global_load_dword v116, v[64:65], off
	global_load_dword v117, v[78:79], off
	global_load_dword v118, v[80:81], off
	global_load_dword v119, v[82:83], off
	global_load_dword v120, v[84:85], off
	global_load_dword v121, v[86:87], off
	global_load_dword v122, v[88:89], off
	global_load_dword v123, v[90:91], off
	global_load_dword v124, v[92:93], off
	global_load_dword v125, v[94:95], off
	s_add_i32 s6, s6, 16
	s_add_i32 s5, s5, 16
	s_add_i32 s7, s7, -16
	v_mad_u64_u32 v[52:53], s[14:15], v47, s8, v[6:7]
	s_cmp_lg_u32 s7, 0
	v_mad_u64_u32 v[54:55], s[14:15], v8, s8, v[6:7]
	v_mad_u64_u32 v[56:57], s[14:15], v97, s8, v[6:7]
	v_mad_u64_u32 v[58:59], s[14:15], v96, s8, v[6:7]
	v_mad_u64_u32 v[60:61], s[14:15], v99, s8, v[6:7]
	v_mad_u64_u32 v[62:63], s[14:15], v98, s8, v[6:7]
	v_mad_u64_u32 v[64:65], s[14:15], v101, s8, v[6:7]
	v_mad_u64_u32 v[78:79], s[14:15], v100, s8, v[6:7]
	v_mad_u64_u32 v[80:81], s[14:15], v103, s8, v[6:7]
	v_mad_u64_u32 v[82:83], s[14:15], v102, s8, v[6:7]
	v_mad_u64_u32 v[84:85], s[14:15], v105, s8, v[6:7]
	v_mad_u64_u32 v[86:87], s[14:15], v104, s8, v[6:7]
	v_mad_u64_u32 v[88:89], s[14:15], v107, s8, v[6:7]
	v_mad_u64_u32 v[90:91], s[14:15], v106, s8, v[6:7]
	v_mad_u64_u32 v[92:93], s[14:15], v109, s8, v[6:7]
	v_mad_u64_u32 v[94:95], s[14:15], v108, s8, v[6:7]
	s_waitcnt vmcnt(31)
	ds_write_b32 v148, v132
	s_waitcnt vmcnt(30)
	ds_write_b32 v149, v133
	s_waitcnt vmcnt(29)
	ds_write_b32 v150, v134
	s_waitcnt vmcnt(28)
	ds_write_b32 v151, v135
	s_waitcnt vmcnt(27)
	ds_write_b32 v152, v136
	s_waitcnt vmcnt(26)
	ds_write_b32 v153, v137
	s_waitcnt vmcnt(25)
	ds_write_b32 v154, v138
	s_waitcnt vmcnt(24)
	ds_write_b32 v155, v139
	s_waitcnt vmcnt(23)
	ds_write_b32 v156, v140
	s_waitcnt vmcnt(22)
	ds_write_b32 v157, v141
	s_waitcnt vmcnt(21)
	ds_write_b32 v158, v142
	s_waitcnt vmcnt(20)
	ds_write_b32 v159, v143
	s_waitcnt vmcnt(19)
	ds_write_b32 v160, v144
	s_waitcnt vmcnt(18)
	ds_write_b32 v161, v145
	s_waitcnt vmcnt(17)
	ds_write_b32 v162, v146
	s_waitcnt vmcnt(16)
	ds_write_b32 v163, v147
	s_waitcnt vmcnt(15)
	ds_write_b32 v52, v110
	s_waitcnt vmcnt(14)
	ds_write_b32 v54, v111
	s_waitcnt vmcnt(13)
	ds_write_b32 v56, v112
	s_waitcnt vmcnt(12)
	ds_write_b32 v58, v113
	s_waitcnt vmcnt(11)
	ds_write_b32 v60, v114
	s_waitcnt vmcnt(10)
	ds_write_b32 v62, v115
	s_waitcnt vmcnt(9)
	ds_write_b32 v64, v116
	s_waitcnt vmcnt(8)
	ds_write_b32 v78, v117
	s_waitcnt vmcnt(7)
	ds_write_b32 v80, v118
	s_waitcnt vmcnt(6)
	ds_write_b32 v82, v119
	s_waitcnt vmcnt(5)
	ds_write_b32 v84, v120
	s_waitcnt vmcnt(4)
	ds_write_b32 v86, v121
	s_waitcnt vmcnt(3)
	ds_write_b32 v88, v122
	s_waitcnt vmcnt(2)
	ds_write_b32 v90, v123
	s_waitcnt vmcnt(1)
	ds_write_b32 v92, v124
	s_waitcnt vmcnt(0)
	ds_write_b32 v94, v125
	s_waitcnt lgkmcnt(0)
	ds_read2_b32 v[54:55], v5 offset0:33 offset1:41
	ds_read2_b32 v[56:57], v5 offset1:8
	ds_read2_b32 v[58:59], v5 offset0:66 offset1:74
	ds_read2_b32 v[60:61], v5 offset0:99 offset1:107
	ds_read2_b32 v[62:63], v5 offset0:132 offset1:140
	ds_read2_b32 v[64:65], v5 offset0:165 offset1:173
	ds_read2_b32 v[78:79], v5 offset0:198 offset1:206
	ds_read2_b32 v[80:81], v5 offset0:231 offset1:239
	v_or_b32_e32 v84, s2, v3
	s_ashr_i32 s5, s4, 31
	v_ashrrev_i32_e32 v85, 31, v84
	v_lshl_add_u64 v[82:83], s[4:5], 1, v[10:11]
	v_lshlrev_b64 v[84:85], 11, v[84:85]
	s_waitcnt lgkmcnt(6)
	v_cvt_pk_bf16_f32 v50, v56, v54
	s_waitcnt lgkmcnt(4)
	v_cvt_pk_bf16_f32 v51, v58, v60
	s_waitcnt lgkmcnt(2)
	v_cvt_pk_bf16_f32 v52, v62, v64
	s_waitcnt lgkmcnt(0)
	v_cvt_pk_bf16_f32 v53, v78, v80
	v_lshl_add_u64 v[84:85], v[82:83], 0, v[84:85]
	v_or_b32_e32 v54, s2, v7
	global_store_dwordx4 v[84:85], v[50:53], off
	s_nop 1
	v_cvt_pk_bf16_f32 v50, v57, v55
	v_ashrrev_i32_e32 v55, 31, v54
	v_cvt_pk_bf16_f32 v51, v59, v61
	v_cvt_pk_bf16_f32 v52, v63, v65
	v_cvt_pk_bf16_f32 v53, v79, v81
	v_lshlrev_b64 v[54:55], 11, v[54:55]
	ds_read2_b32 v[56:57], v5 offset0:49 offset1:57
	ds_read2_b32 v[58:59], v5 offset0:16 offset1:24
	ds_read2_b32 v[60:61], v5 offset0:82 offset1:90
	ds_read2_b32 v[62:63], v5 offset0:115 offset1:123
	ds_read2_b32 v[64:65], v5 offset0:148 offset1:156
	ds_read2_b32 v[78:79], v5 offset0:181 offset1:189
	ds_read2_b32 v[80:81], v5 offset0:214 offset1:222
	ds_read2_b32 v[84:85], v5 offset0:247 offset1:255
	v_lshl_add_u64 v[54:55], v[82:83], 0, v[54:55]
	global_store_dwordx4 v[54:55], v[50:53], off
	v_or_b32_e32 v54, s2, v68
	v_ashrrev_i32_e32 v55, 31, v54
	v_lshlrev_b64 v[54:55], 11, v[54:55]
	s_waitcnt lgkmcnt(6)
	v_cvt_pk_bf16_f32 v50, v58, v56
	s_waitcnt lgkmcnt(4)
	v_cvt_pk_bf16_f32 v51, v60, v62
	s_waitcnt lgkmcnt(2)
	v_cvt_pk_bf16_f32 v52, v64, v78
	s_waitcnt lgkmcnt(0)
	v_cvt_pk_bf16_f32 v53, v80, v84
	v_lshl_add_u64 v[54:55], v[82:83], 0, v[54:55]
	global_store_dwordx4 v[54:55], v[50:53], off
	v_or_b32_e32 v54, s2, v69
	v_ashrrev_i32_e32 v55, 31, v54
	v_lshlrev_b64 v[54:55], 11, v[54:55]
	v_cvt_pk_bf16_f32 v50, v59, v57
	v_cvt_pk_bf16_f32 v51, v61, v63
	v_cvt_pk_bf16_f32 v52, v65, v79
	v_cvt_pk_bf16_f32 v53, v81, v85
	v_lshl_add_u64 v[54:55], v[82:83], 0, v[54:55]
	global_store_dwordx4 v[54:55], v[50:53], off
	s_waitcnt lgkmcnt(0)
	s_branch .LBB0_19

; __device__ __forceinline__ void convert_layer(const Ctx& C, int l) {
;     ...
;             for (int k = ch * 64; k < ch * 64 + 64; ++k) { const float pv = pos[k];
; #pragma unroll
;                 for (int q = 0; q < 4; ++q) p[q] += pv * w1[(size_t)k * 256 + lane + 64 * q]; }
.LBB0_114:
	global_load_dwordx4 v[14:17], v5, s[6:7] offset:-12
	global_load_dwordx4 v[18:21], v5, s[6:7] offset:-28
	global_load_dwordx4 v[164:167], v5, s[6:7] offset:20
	global_load_dwordx4 v[168:171], v5, s[6:7] offset:4
	s_mov_b64 vcc, 0x1000
	v_lshl_add_u64 v[22:23], v[8:9], 0, s[8:9]
	global_load_dword v24, v[22:23], off
	global_load_dword v25, v[22:23], off offset:256
	global_load_dword v26, v[22:23], off offset:512
	global_load_dword v27, v[22:23], off offset:768
	global_load_dword v28, v[22:23], off offset:1024
	global_load_dword v29, v[22:23], off offset:1280
	global_load_dword v30, v[22:23], off offset:1536
	global_load_dword v31, v[22:23], off offset:1792
	global_load_dword v32, v[22:23], off offset:2048
	global_load_dword v33, v[22:23], off offset:2304
	global_load_dword v34, v[22:23], off offset:2560
	global_load_dword v35, v[22:23], off offset:2816
	global_load_dword v36, v[22:23], off offset:3072
	global_load_dword v37, v[22:23], off offset:3328
	global_load_dword v38, v[22:23], off offset:3584
	global_load_dword v39, v[22:23], off offset:3840
	v_lshl_add_u64 v[22:23], v[22:23], 0, vcc
	global_load_dword v40, v[22:23], off
	global_load_dword v41, v[22:23], off offset:256
	global_load_dword v42, v[22:23], off offset:512
	global_load_dword v43, v[22:23], off offset:768
	global_load_dword v44, v[22:23], off offset:1024
	global_load_dword v45, v[22:23], off offset:1280
	global_load_dword v46, v[22:23], off offset:1536
	global_load_dword v47, v[22:23], off offset:1792
	global_load_dword v48, v[22:23], off offset:2048
	global_load_dword v49, v[22:23], off offset:2304
	global_load_dword v50, v[22:23], off offset:2560
	global_load_dword v51, v[22:23], off offset:2816
	global_load_dword v52, v[22:23], off offset:3072
	global_load_dword v53, v[22:23], off offset:3328
	global_load_dword v54, v[22:23], off offset:3584
	global_load_dword v55, v[22:23], off offset:3840
	v_lshl_add_u64 v[22:23], v[22:23], 0, vcc
	global_load_dword v132, v[22:23], off
	global_load_dword v133, v[22:23], off offset:256
	global_load_dword v134, v[22:23], off offset:512
	global_load_dword v135, v[22:23], off offset:768
	global_load_dword v136, v[22:23], off offset:1024
	global_load_dword v137, v[22:23], off offset:1280
	global_load_dword v138, v[22:23], off offset:1536
	global_load_dword v139, v[22:23], off offset:1792
	global_load_dword v140, v[22:23], off offset:2048
	global_load_dword v141, v[22:23], off offset:2304
	global_load_dword v142, v[22:23], off offset:2560
	global_load_dword v143, v[22:23], off offset:2816
	global_load_dword v144, v[22:23], off offset:3072
	global_load_dword v145, v[22:23], off offset:3328
	global_load_dword v146, v[22:23], off offset:3584
	global_load_dword v147, v[22:23], off offset:3840
	v_lshl_add_u64 v[22:23], v[22:23], 0, vcc
	global_load_dword v148, v[22:23], off
	global_load_dword v149, v[22:23], off offset:256
	global_load_dword v150, v[22:23], off offset:512
	global_load_dword v151, v[22:23], off offset:768
	global_load_dword v152, v[22:23], off offset:1024
	global_load_dword v153, v[22:23], off offset:1280
	global_load_dword v154, v[22:23], off offset:1536
	global_load_dword v155, v[22:23], off offset:1792
	global_load_dword v156, v[22:23], off offset:2048
	global_load_dword v157, v[22:23], off offset:2304
	global_load_dword v158, v[22:23], off offset:2560
	global_load_dword v159, v[22:23], off offset:2816
	global_load_dword v160, v[22:23], off offset:3072
	global_load_dword v161, v[22:23], off offset:3328
	global_load_dword v162, v[22:23], off offset:3584
	global_load_dword v163, v[22:23], off offset:3840
	s_add_u32 s8, s8, 0x4000
	s_addc_u32 s9, s9, 0
	s_add_u32 s6, s6, 64
	s_addc_u32 s7, s7, 0
	s_cmp_eq_u32 s8, 0x10000
	s_waitcnt vmcnt(62)
	v_pk_fma_f32 v[12:13], v[18:19], v[24:25], v[12:13] op_sel_hi:[0,1,1]
	s_waitcnt vmcnt(60)
	v_pk_fma_f32 v[10:11], v[18:19], v[26:27], v[10:11] op_sel_hi:[0,1,1]
	s_waitcnt vmcnt(58)
	v_pk_fma_f32 v[12:13], v[18:19], v[28:29], v[12:13] op_sel:[1,0,0]
	s_waitcnt vmcnt(56)
	v_pk_fma_f32 v[10:11], v[18:19], v[30:31], v[10:11] op_sel:[1,0,0]
	s_waitcnt vmcnt(54)
	v_pk_fma_f32 v[12:13], v[20:21], v[32:33], v[12:13] op_sel_hi:[0,1,1]
	s_waitcnt vmcnt(52)
	v_pk_fma_f32 v[10:11], v[20:21], v[34:35], v[10:11] op_sel_hi:[0,1,1]
	s_waitcnt vmcnt(50)
	v_pk_fma_f32 v[12:13], v[20:21], v[36:37], v[12:13] op_sel:[1,0,0]
	s_waitcnt vmcnt(48)
	v_pk_fma_f32 v[10:11], v[20:21], v[38:39], v[10:11] op_sel:[1,0,0]
	s_waitcnt vmcnt(46)
	v_pk_fma_f32 v[12:13], v[14:15], v[40:41], v[12:13] op_sel_hi:[0,1,1]
	s_waitcnt vmcnt(44)
	v_pk_fma_f32 v[10:11], v[14:15], v[42:43], v[10:11] op_sel_hi:[0,1,1]
	s_waitcnt vmcnt(42)
	v_pk_fma_f32 v[12:13], v[14:15], v[44:45], v[12:13] op_sel:[1,0,0]
	s_waitcnt vmcnt(40)
	v_pk_fma_f32 v[10:11], v[14:15], v[46:47], v[10:11] op_sel:[1,0,0]
	s_waitcnt vmcnt(38)
	v_pk_fma_f32 v[12:13], v[16:17], v[48:49], v[12:13] op_sel_hi:[0,1,1]
	s_waitcnt vmcnt(36)
	v_pk_fma_f32 v[10:11], v[16:17], v[50:51], v[10:11] op_sel_hi:[0,1,1]
	s_waitcnt vmcnt(34)
	v_pk_fma_f32 v[12:13], v[16:17], v[52:53], v[12:13] op_sel:[1,0,0]
	s_waitcnt vmcnt(32)
	v_pk_fma_f32 v[10:11], v[16:17], v[54:55], v[10:11] op_sel:[1,0,0]
	s_waitcnt vmcnt(30)
	v_pk_fma_f32 v[12:13], v[168:169], v[132:133], v[12:13] op_sel_hi:[0,1,1]
	s_waitcnt vmcnt(28)
	v_pk_fma_f32 v[10:11], v[168:169], v[134:135], v[10:11] op_sel_hi:[0,1,1]
	s_waitcnt vmcnt(26)
	v_pk_fma_f32 v[12:13], v[168:169], v[136:137], v[12:13] op_sel:[1,0,0]
	s_waitcnt vmcnt(24)
	v_pk_fma_f32 v[10:11], v[168:169], v[138:139], v[10:11] op_sel:[1,0,0]
	s_waitcnt vmcnt(22)
	v_pk_fma_f32 v[12:13], v[170:171], v[140:141], v[12:13] op_sel_hi:[0,1,1]
	s_waitcnt vmcnt(20)
	v_pk_fma_f32 v[10:11], v[170:171], v[142:143], v[10:11] op_sel_hi:[0,1,1]
	s_waitcnt vmcnt(18)
	v_pk_fma_f32 v[12:13], v[170:171], v[144:145], v[12:13] op_sel:[1,0,0]
	s_waitcnt vmcnt(16)
	v_pk_fma_f32 v[10:11], v[170:171], v[146:147], v[10:11] op_sel:[1,0,0]
	s_waitcnt vmcnt(14)
	v_pk_fma_f32 v[12:13], v[164:165], v[148:149], v[12:13] op_sel_hi:[0,1,1]
	s_waitcnt vmcnt(12)
	v_pk_fma_f32 v[10:11], v[164:165], v[150:151], v[10:11] op_sel_hi:[0,1,1]
	s_waitcnt vmcnt(10)
	v_pk_fma_f32 v[12:13], v[164:165], v[152:153], v[12:13] op_sel:[1,0,0]
	s_waitcnt vmcnt(8)
	v_pk_fma_f32 v[10:11], v[164:165], v[154:155], v[10:11] op_sel:[1,0,0]
	s_waitcnt vmcnt(6)
	v_pk_fma_f32 v[12:13], v[166:167], v[156:157], v[12:13] op_sel_hi:[0,1,1]
	s_waitcnt vmcnt(4)
	v_pk_fma_f32 v[10:11], v[166:167], v[158:159], v[10:11] op_sel_hi:[0,1,1]
	s_waitcnt vmcnt(2)
	v_pk_fma_f32 v[12:13], v[166:167], v[160:161], v[12:13] op_sel:[1,0,0]
	s_waitcnt vmcnt(0)
	v_pk_fma_f32 v[10:11], v[166:167], v[162:163], v[10:11] op_sel:[1,0,0]
	s_cbranch_scc0 .LBB0_114
; __device__ __forceinline__ void convert_layer(const Ctx& C, int l) {
;     ...
;         for (int it = C.gw; it < 64; it += C.NGW) {
;             const int kv = it >> 5, ch = it & 31;
;             const float* pos = kv ? INF(13, l, 2048) : INF(12, l, 2048);
;             const float* w1 = kv ? INF(17, l, 2048 * 256) : INF(14, l, 2048 * 256);
;             float p[4] = {0.f, 0.f, 0.f, 0.f};
;             for (int k = ch * 64; k < ch * 64 + 64; ++k) { const float pv = pos[k];
; #pragma unroll
;                 for (int q = 0; q < 4; ++q) p[q] += pv * w1[(size_t)k * 256 + lane + 64 * q]; }
; #pragma unroll
;             for (int q = 0; q < 4; ++q) cb[(size_t)it * 256 + lane + 64 * q] = p[q];
;         }
	s_ashr_i32 s5, s4, 31
	s_lshl_b64 s[6:7], s[4:5], 10
	s_add_i32 s4, s4, s70
	s_add_i32 s11, s11, s3
	v_lshl_add_u64 v[8:9], v[6:7], 0, s[6:7]
	s_cmp_gt_i32 s4, 63
	global_store_dword v[8:9], v12, off
	global_store_dword v[8:9], v13, off offset:256
	global_store_dword v[8:9], v10, off offset:512
	global_store_dword v[8:9], v11, off offset:768
	s_cbranch_scc0 .LBB0_113

; __device__ __forceinline__ void convert_layer(const Ctx& C, int l) {
;     ...
;             for (int k = ch * 64; k < ch * 64 + 64; ++k) { const float pv = pos[k];
; #pragma unroll
;                 for (int q = 0; q < 4; ++q) p[q] += pv * w1[(size_t)k * 256 + lane + 64 * q]; }
.LBB0_1503:
	global_load_dwordx4 v[2:5], v1, s[0:1] offset:-12
	global_load_dwordx4 v[14:17], v1, s[0:1] offset:-28
	global_load_dwordx4 v[24:27], v1, s[0:1] offset:20
	global_load_dwordx4 v[28:31], v1, s[0:1] offset:4
	v_lshl_add_u64 v[18:19], v[8:9], 0, s[12:13]
	s_mov_b64 vcc, 0x200000
	v_lshl_add_u64 v[22:23], v[18:19], 0, vcc
	s_mov_b64 vcc, 0x1000
	s_mov_b32 s3, 0x201000
	global_load_dword v132, v[22:23], off
	global_load_dword v133, v[22:23], off offset:256
	global_load_dword v134, v[22:23], off offset:512
	global_load_dword v135, v[22:23], off offset:768
	global_load_dword v136, v[22:23], off offset:1024
	global_load_dword v137, v[22:23], off offset:1280
	global_load_dword v138, v[22:23], off offset:1536
	global_load_dword v139, v[22:23], off offset:1792
	global_load_dword v140, v[22:23], off offset:2048
	global_load_dword v141, v[22:23], off offset:2304
	global_load_dword v142, v[22:23], off offset:2560
	global_load_dword v143, v[22:23], off offset:2816
	global_load_dword v144, v[22:23], off offset:3072
	global_load_dword v145, v[22:23], off offset:3328
	global_load_dword v146, v[22:23], off offset:3584
	global_load_dword v147, v[22:23], off offset:3840
	v_lshl_add_u64 v[22:23], v[22:23], 0, vcc
	global_load_dword v148, v[22:23], off
	global_load_dword v149, v[22:23], off offset:256
	global_load_dword v150, v[22:23], off offset:512
	global_load_dword v151, v[22:23], off offset:768
	global_load_dword v152, v[22:23], off offset:1024
	global_load_dword v153, v[22:23], off offset:1280
	global_load_dword v154, v[22:23], off offset:1536
	global_load_dword v155, v[22:23], off offset:1792
	global_load_dword v156, v[22:23], off offset:2048
	global_load_dword v157, v[22:23], off offset:2304
	global_load_dword v158, v[22:23], off offset:2560
	global_load_dword v159, v[22:23], off offset:2816
	global_load_dword v160, v[22:23], off offset:3072
	global_load_dword v161, v[22:23], off offset:3328
	global_load_dword v162, v[22:23], off offset:3584
	global_load_dword v163, v[22:23], off offset:3840
	v_lshl_add_u64 v[22:23], v[22:23], 0, vcc
	global_load_dword v164, v[22:23], off
	global_load_dword v165, v[22:23], off offset:256
	global_load_dword v166, v[22:23], off offset:512
	global_load_dword v167, v[22:23], off offset:768
	global_load_dword v168, v[22:23], off offset:1024
	global_load_dword v169, v[22:23], off offset:1280
	global_load_dword v170, v[22:23], off offset:1536
	global_load_dword v171, v[22:23], off offset:1792
	global_load_dword v172, v[22:23], off offset:2048
	global_load_dword v173, v[22:23], off offset:2304
	global_load_dword v174, v[22:23], off offset:2560
	global_load_dword v175, v[22:23], off offset:2816
	global_load_dword v176, v[22:23], off offset:3072
	global_load_dword v177, v[22:23], off offset:3328
	global_load_dword v178, v[22:23], off offset:3584
	global_load_dword v179, v[22:23], off offset:3840
	v_lshl_add_u64 v[22:23], v[22:23], 0, vcc
	global_load_dword v180, v[22:23], off
	global_load_dword v181, v[22:23], off offset:256
	global_load_dword v182, v[22:23], off offset:512
	global_load_dword v183, v[22:23], off offset:768
	global_load_dword v184, v[22:23], off offset:1024
	global_load_dword v185, v[22:23], off offset:1280
	global_load_dword v186, v[22:23], off offset:1536
	global_load_dword v187, v[22:23], off offset:1792
	global_load_dword v188, v[22:23], off offset:2048
	global_load_dword v189, v[22:23], off offset:2304
	global_load_dword v190, v[22:23], off offset:2560
	global_load_dword v191, v[22:23], off offset:2816
	global_load_dword v192, v[22:23], off offset:3072
	global_load_dword v193, v[22:23], off offset:3328
	global_load_dword v194, v[22:23], off offset:3584
	global_load_dword v195, v[22:23], off offset:3840
	s_add_u32 s12, s12, 0x4000
	s_addc_u32 s13, s13, 0
	s_add_u32 s0, s0, 64
	s_addc_u32 s1, s1, 0
	s_cmp_eq_u32 s12, 0x10000
	s_waitcnt vmcnt(62)
	v_pk_fma_f32 v[10:11], v[14:15], v[132:133], v[10:11] op_sel_hi:[0,1,1]
	s_waitcnt vmcnt(60)
	v_pk_fma_f32 v[12:13], v[14:15], v[134:135], v[12:13] op_sel_hi:[0,1,1]
	s_waitcnt vmcnt(58)
	v_pk_fma_f32 v[10:11], v[14:15], v[136:137], v[10:11] op_sel:[1,0,0]
	s_waitcnt vmcnt(56)
	v_pk_fma_f32 v[12:13], v[14:15], v[138:139], v[12:13] op_sel:[1,0,0]
	s_waitcnt vmcnt(54)
	v_pk_fma_f32 v[10:11], v[16:17], v[140:141], v[10:11] op_sel_hi:[0,1,1]
	s_waitcnt vmcnt(52)
	v_pk_fma_f32 v[12:13], v[16:17], v[142:143], v[12:13] op_sel_hi:[0,1,1]
	s_waitcnt vmcnt(50)
	v_pk_fma_f32 v[10:11], v[16:17], v[144:145], v[10:11] op_sel:[1,0,0]
	s_waitcnt vmcnt(48)
	v_pk_fma_f32 v[12:13], v[16:17], v[146:147], v[12:13] op_sel:[1,0,0]
	s_waitcnt vmcnt(46)
	v_pk_fma_f32 v[10:11], v[2:3], v[148:149], v[10:11] op_sel_hi:[0,1,1]
	s_waitcnt vmcnt(44)
	v_pk_fma_f32 v[12:13], v[2:3], v[150:151], v[12:13] op_sel_hi:[0,1,1]
	s_waitcnt vmcnt(42)
	v_pk_fma_f32 v[10:11], v[2:3], v[152:153], v[10:11] op_sel:[1,0,0]
	s_waitcnt vmcnt(40)
	v_pk_fma_f32 v[12:13], v[2:3], v[154:155], v[12:13] op_sel:[1,0,0]
	s_waitcnt vmcnt(38)
	v_pk_fma_f32 v[10:11], v[4:5], v[156:157], v[10:11] op_sel_hi:[0,1,1]
	s_waitcnt vmcnt(36)
	v_pk_fma_f32 v[12:13], v[4:5], v[158:159], v[12:13] op_sel_hi:[0,1,1]
	s_waitcnt vmcnt(34)
	v_pk_fma_f32 v[10:11], v[4:5], v[160:161], v[10:11] op_sel:[1,0,0]
	s_waitcnt vmcnt(32)
	v_pk_fma_f32 v[12:13], v[4:5], v[162:163], v[12:13] op_sel:[1,0,0]
	s_waitcnt vmcnt(30)
	v_pk_fma_f32 v[10:11], v[28:29], v[164:165], v[10:11] op_sel_hi:[0,1,1]
	s_waitcnt vmcnt(28)
	v_pk_fma_f32 v[12:13], v[28:29], v[166:167], v[12:13] op_sel_hi:[0,1,1]
	s_waitcnt vmcnt(26)
	v_pk_fma_f32 v[10:11], v[28:29], v[168:169], v[10:11] op_sel:[1,0,0]
	s_waitcnt vmcnt(24)
	v_pk_fma_f32 v[12:13], v[28:29], v[170:171], v[12:13] op_sel:[1,0,0]
	s_waitcnt vmcnt(22)
	v_pk_fma_f32 v[10:11], v[30:31], v[172:173], v[10:11] op_sel_hi:[0,1,1]
	s_waitcnt vmcnt(20)
	v_pk_fma_f32 v[12:13], v[30:31], v[174:175], v[12:13] op_sel_hi:[0,1,1]
	s_waitcnt vmcnt(18)
	v_pk_fma_f32 v[10:11], v[30:31], v[176:177], v[10:11] op_sel:[1,0,0]
	s_waitcnt vmcnt(16)
	v_pk_fma_f32 v[12:13], v[30:31], v[178:179], v[12:13] op_sel:[1,0,0]
	s_waitcnt vmcnt(14)
	v_pk_fma_f32 v[10:11], v[24:25], v[180:181], v[10:11] op_sel_hi:[0,1,1]
	s_waitcnt vmcnt(12)
	v_pk_fma_f32 v[12:13], v[24:25], v[182:183], v[12:13] op_sel_hi:[0,1,1]
	s_waitcnt vmcnt(10)
	v_pk_fma_f32 v[10:11], v[24:25], v[184:185], v[10:11] op_sel:[1,0,0]
	s_waitcnt vmcnt(8)
	v_pk_fma_f32 v[12:13], v[24:25], v[186:187], v[12:13] op_sel:[1,0,0]
	s_waitcnt vmcnt(6)
	v_pk_fma_f32 v[10:11], v[26:27], v[188:189], v[10:11] op_sel_hi:[0,1,1]
	s_waitcnt vmcnt(4)
	v_pk_fma_f32 v[12:13], v[26:27], v[190:191], v[12:13] op_sel_hi:[0,1,1]
	s_waitcnt vmcnt(2)
	v_pk_fma_f32 v[10:11], v[26:27], v[192:193], v[10:11] op_sel:[1,0,0]
	s_waitcnt vmcnt(0)
	v_pk_fma_f32 v[12:13], v[26:27], v[194:195], v[12:13] op_sel:[1,0,0]
	s_cbranch_scc0 .LBB0_1503
; __device__ __forceinline__ void convert_layer(const Ctx& C, int l) {
;     ...
;         for (int it = C.gw; it < 64; it += C.NGW) {
;             const int kv = it >> 5, ch = it & 31;
;             const float* pos = kv ? INF(13, l, 2048) : INF(12, l, 2048);
;             const float* w1 = kv ? INF(17, l, 2048 * 256) : INF(14, l, 2048 * 256);
;             float p[4] = {0.f, 0.f, 0.f, 0.f};
;             for (int k = ch * 64; k < ch * 64 + 64; ++k) { const float pv = pos[k];
; #pragma unroll
;                 for (int q = 0; q < 4; ++q) p[q] += pv * w1[(size_t)k * 256 + lane + 64 * q]; }
; #pragma unroll
;             for (int q = 0; q < 4; ++q) cb[(size_t)it * 256 + lane + 64 * q] = p[q];
;         }
	s_ashr_i32 s35, s34, 31
	s_lshl_b64 s[0:1], s[34:35], 10
	s_add_i32 s34, s34, s70
	s_add_i32 s2, s2, s10
	v_lshl_add_u64 v[2:3], v[6:7], 0, s[0:1]
	s_cmp_gt_i32 s34, 63
	global_store_dword v[2:3], v10, off
	global_store_dword v[2:3], v11, off offset:256
	global_store_dword v[2:3], v12, off offset:512
	global_store_dword v[2:3], v13, off offset:768
	s_cbranch_scc0 .LBB0_1502
	v_readlane_b32 s40, v254, 0
	v_readlane_b32 s44, v254, 48
	v_readlane_b32 s50, v254, 53
	v_readlane_b32 s42, v253, 46
	v_readlane_b32 s41, v254, 1
	v_readlane_b32 s43, v254, 47
	v_readlane_b32 s45, v254, 49
	v_readlane_b32 s46, v254, 50
	v_readlane_b32 s48, v254, 51
	v_readlane_b32 s51, v254, 54
	v_readlane_b32 s47, v254, 55
	v_readlane_b32 s26, v254, 56
	v_readlane_b32 s20, v254, 57
	v_readlane_b32 s21, v254, 58
	v_readlane_b32 s27, v254, 59
	v_readlane_b32 s36, v254, 62
	v_readlane_b32 s49, v254, 52
